# adds RWKV state-update reassociation (shorter dependent chain, in-place in k regs) and steady-state counted vmcnt ladders in both merge GEMM loops
# speedup vs baseline: 1.0003x; 1.0003x over previous
; DI float row16_sum(float v) { v += dppf(v, 0); v += dppf(v, 1); v += dppf(v, 2); v += dppf(v, 3); return v; }
; DI void rwkv_scan(CP p, const Ptrs& w, int l, int item, float* sm) {
;     ...
;   auto load = [&](int c, RPre& P) {
;     int ii = pos2i(c * 16 + sj, dir);
;     size_t tok = (size_t)b * TPB + ii;
;     const bf16_t* prow = w.pB + tok * SPB + sc_;
;     bool hp = (ii != 0) && (ii != CTXL), hn = (ii != CTXL - 1) && (ii != TPB - 1);
;     const int op = hp ? -SPB : 0, on = hn ? SPB : 0;
;     P.pmk[0] = hp ? 0.5f : 0.f; P.pmk[1] = hn ? 0.5f : 0.f;
; #pragma unroll
;     for (int q = 0; q < 3; ++q) {
;       P.pq[q][0] = *(const uint2*)(prow + q * 512);
;       P.pq[q][1] = *(const uint2*)(prow + q * 512 + op);
;       P.pq[q][2] = *(const uint2*)(prow + q * 512 + on);
;     }
;     P.pwd = *(const uint2*)(Wd + tok * 512 + sc_);
;     P.pad_ = *(const uint2*)(Ad + tok * 512 + sc_);
;     const float* sc = w.bonus + (tok * 8 + hd) * 8;
;     P.psc[0] = sc[0]; P.psc[1] = sc[1 + 3 * dir]; P.psc[2] = sc[2 + 3 * dir];
;   };
;     ...
;   auto flush = [&](int c) {
;     {
;       int j = tid >> 4, rr = tid & 15;
;       int ii = pos2i(c * 16 + j, dir);
;       yout[((size_t)b * TPB + ii) * 512 + hd * 64 + rq * 16 + rr] = f2bf(sY[(c & 1) * 256 + j * 16 + rr]);
;     }
;   };
;   __syncthreads();
;   load(0, PA);
;   stage(PA, sm);
;   load(1, PB);
;   __syncthreads();
;   const int NCH = TPB / 16;
;   auto run_chunk = [&](int c, const float* bf, float* sy) {
;     flush(max(c - 1, 0));
;     RStep cur = lds_step(bf, 0);
; #pragma unroll
;     for (int j = 0; j < 16; ++j) {
;       RStep nxt = cur;
;       if (j + 1 < 16) nxt = lds_step(bf, j + 1);
;       f2v sa2 = SA * cur.a4.xy + SB * cur.a4.zw;
;       f2v yp2 = SA * cur.wr4.xy + SB * cur.wr4.zw;
;       float sa = sa2.x + sa2.y, yp = yp2.x + yp2.y;
;       sa = row16_sum(sa); yp = row16_sum(yp);
;       float y = yp + sa * cur.sc.x + cur.vv * cur.sc.y;
;       SA = SA * cur.w4.xy + (sa * cur.b4.xy + cur.vv * cur.k4.xy);
;       SB = SB * cur.w4.zw + (sa * cur.b4.zw + cur.vv * cur.k4.zw);
;       sy[(kg == 0 ? j * 16 : 0) + ysel - (c & 1) * 0] = y;
;       cur = nxt;
;     }
.LBB0_554:
	s_min_u32 s4, s38, 1
	s_lshl_b32 s5, s4, 8
	s_lshl_b32 s46, s4, 4
	s_add_i32 s4, s17, 4
	s_min_u32 s4, s4, 0x20f
	v_lshl_add_u32 v24, s4, 4, v97
	s_sub_i32 s39, s16, s5
	v_cmp_lt_i32_e64 s[4:5], s37, v24
	s_nop 1
	v_cndmask_b32_e64 v25, v231, v232, s[4:5]
	v_sub_u32_e32 v25, v25, v24
	v_cndmask_b32_e32 v24, v25, v24, vcc
	v_ashrrev_i32_e32 v25, 31, v24
	v_lshl_add_u64 v[26:27], s[12:13], 0, v[24:25]
	v_mad_u64_u32 v[28:29], s[4:5], v26, s20, v[42:43]
	v_mov_b32_e32 v30, v29
	v_mad_u64_u32 v[30:31], s[4:5], v27, s20, v[30:31]
	v_and_b32_e32 v25, 0xfffffeff, v24
	v_mov_b32_e32 v29, v30
	v_and_b32_e32 v30, 0xffffdfff, v24
	v_cmp_eq_u32_e64 s[42:43], 0, v25
	v_cmp_eq_u32_e64 s[44:45], s37, v30
	s_and_b32 s4, s39, 0x100
	v_cndmask_b32_e64 v25, -1, 0, s[42:43]
	v_cndmask_b32_e64 v24, v236, 0, s[42:43]
	v_cndmask_b32_e64 v156, v237, 0, s[44:45]
	v_lshl_add_u64 v[24:25], v[28:29], 0, v[24:25]
	v_lshl_add_u64 v[30:31], v[28:29], 0, v[156:157]
	global_load_dwordx2 v[88:89], v[28:29], off
	global_load_dwordx2 v[86:87], v[28:29], off offset:1024
	global_load_dwordx2 v[84:85], v[28:29], off offset:2048
	global_load_dwordx2 v[74:75], v[24:25], off
	global_load_dwordx2 v[76:77], v[30:31], off
	global_load_dwordx2 v[78:79], v[24:25], off offset:1024
	global_load_dwordx2 v[70:71], v[24:25], off offset:2048
	v_lshlrev_b64 v[24:25], 10, v[26:27]
	v_lshl_add_u64 v[28:29], v[34:35], 0, v[24:25]
	v_lshl_add_u64 v[24:25], v[36:37], 0, v[24:25]
	global_load_dwordx2 v[80:81], v[30:31], off offset:1024
	global_load_dwordx2 v[72:73], v[30:31], off offset:2048
	global_load_dwordx2 v[92:93], v[28:29], off
	global_load_dwordx2 v[90:91], v[24:25], off
	v_lshlrev_b64 v[24:25], 8, v[26:27]
	v_lshl_add_u64 v[24:25], s[6:7], 0, v[24:25]
	v_lshl_add_u64 v[26:27], v[24:25], 0, s[90:91]
	global_load_dword v82, v[24:25], off
	global_load_dwordx2 v[68:69], v[26:27], off offset:4
	v_lshl_add_u32 v25, s4, 2, v83
	v_subrev_u32_e32 v24, s46, v125
	ds_read_b32 v25, v25 offset:49408
	v_cmp_lt_i32_e64 s[4:5], s37, v24
	ds_read2st64_b32 v[154:155], v106 offset0:80 offset1:81
	s_nop 0
	v_cndmask_b32_e64 v26, v231, v232, s[4:5]
	v_add3_u32 v26, v26, v124, s46
	v_cndmask_b32_e32 v24, v26, v24, vcc
	s_waitcnt lgkmcnt(1)
	v_cvt_pk_bf16_f32 v26, v25, s0
	v_ashrrev_i32_e32 v25, 31, v24
	v_lshl_add_u64 v[24:25], s[12:13], 0, v[24:25]
	v_lshlrev_b64 v[24:25], 10, v[24:25]
	v_lshl_add_u64 v[24:25], v[38:39], 0, v[24:25]
	global_store_short v[24:25], v26, off
	s_waitcnt lgkmcnt(0)
	v_add_u32_e64 v24, s21, 0
	ds_read2_b64 v[24:27], v24 offset1:1
	ds_read_b128 v[28:31], v105
	ds_read_b128 v[98:101], v105 offset:256
	ds_read_b128 v[126:129], v105 offset:4096
	ds_read_b128 v[130:133], v105 offset:4352
	ds_read_b128 v[134:137], v105 offset:8192
	ds_read_b128 v[138:141], v105 offset:8448
	ds_read_b128 v[142:145], v105 offset:12288
	ds_read_b128 v[146:149], v105 offset:12544
	ds_read_b128 v[150:153], v105 offset:16384
	ds_read_b128 v[168:171], v105 offset:16640
	s_waitcnt lgkmcnt(9)
	v_mul_f32 v30, v22, v30
	v_mul_f32 v31, v23, v31
	v_fma_f32 v28, v20, v28, v30
	v_fma_f32 v29, v21, v29, v31
	s_waitcnt lgkmcnt(7)
	v_mul_f32 v30, v22, v128
	v_mul_f32 v31, v23, v129
	v_add_f32_e32 v28, v28, v29
	v_fma_f32 v30, v20, v126, v30
	v_fma_f32 v31, v21, v127, v31
	v_add_f32_dpp v28, v28, v28 quad_perm:[1,0,3,2] row_mask:0xf bank_mask:0xf bound_ctrl:1
	v_add_f32_e32 v29, v30, v31
	s_nop 0
	v_add_f32_dpp v28, v28, v28 quad_perm:[2,3,0,1] row_mask:0xf bank_mask:0xf bound_ctrl:1
	v_add_f32_dpp v29, v29, v29 quad_perm:[1,0,3,2] row_mask:0xf bank_mask:0xf bound_ctrl:1
	s_nop 0
	v_add_f32_dpp v28, v28, v28 row_half_mirror row_mask:0xf bank_mask:0xf bound_ctrl:1
	v_add_f32_dpp v29, v29, v29 quad_perm:[2,3,0,1] row_mask:0xf bank_mask:0xf bound_ctrl:1
	s_nop 0
	v_add_f32_dpp v28, v28, v28 row_mirror row_mask:0xf bank_mask:0xf bound_ctrl:1
	v_add_f32_dpp v29, v29, v29 row_half_mirror row_mask:0xf bank_mask:0xf bound_ctrl:1
	s_nop 1
	v_add_f32_dpp v29, v29, v29 row_mirror row_mask:0xf bank_mask:0xf bound_ctrl:1
	v_fmac_f32_e32 v29, v24, v28
	s_waitcnt lgkmcnt(3)
	v_mul_f32 v24, v142, v28
	v_fmac_f32_e32 v29, v154, v25
	v_mul_f32 v25, v143, v28
	s_waitcnt lgkmcnt(1)
	v_fma_f32 v24, v150, v154, v24
	ds_write_b32 v107, v29 offset:49408
	v_fma_f32 v25, v151, v154, v25
	v_fma_f32 v24, v20, v134, v24
	v_mul_f32 v20, v144, v28
	v_fma_f32 v25, v21, v135, v25
	v_mul_f32 v21, v145, v28
	v_fma_f32 v20, v152, v154, v20
	v_fma_f32 v21, v153, v154, v21
	v_fma_f32 v150, v22, v136, v20
	v_fma_f32 v151, v23, v137, v21
	ds_read_b128 v[20:23], v105 offset:512
	ds_read_b128 v[28:31], v105 offset:4608
	v_mul_f32 v100, v100, v150
	v_mul_f32 v101, v101, v151
	ds_read_b128 v[126:129], v105 offset:8704
	v_fma_f32 v98, v98, v24, v100
	v_fma_f32 v99, v99, v25, v101
	ds_read_b128 v[134:137], v105 offset:12800
	v_mul_f32 v100, v132, v150
	v_mul_f32 v101, v133, v151
	ds_read_b128 v[142:145], v105 offset:16896
	v_fma_f32 v100, v130, v24, v100
	v_fma_f32 v101, v131, v25, v101
	v_add_f32_e32 v98, v98, v99
	ds_read_b32 v96, v106 offset:20992
	v_add_f32_e32 v99, v100, v101
	ds_read_b64 v[152:153], v157 offset:24592
	v_add_f32_dpp v98, v98, v98 quad_perm:[1,0,3,2] row_mask:0xf bank_mask:0xf bound_ctrl:1
	v_add_f32_dpp v99, v99, v99 quad_perm:[1,0,3,2] row_mask:0xf bank_mask:0xf bound_ctrl:1
	v_mov_b32_e32 v100, v155
	v_add_f32_dpp v98, v98, v98 quad_perm:[2,3,0,1] row_mask:0xf bank_mask:0xf bound_ctrl:1
	v_add_f32_dpp v99, v99, v99 quad_perm:[2,3,0,1] row_mask:0xf bank_mask:0xf bound_ctrl:1
	s_waitcnt lgkmcnt(7)
; DI float row16_sum(float v) { v += dppf(v, 0); v += dppf(v, 1); v += dppf(v, 2); v += dppf(v, 3); return v; }
; DI void rwkv_scan(CP p, const Ptrs& w, int l, int item, float* sm) {
;     ...
;   auto run_chunk = [&](int c, const float* bf, float* sy) {
;     flush(max(c - 1, 0));
;     RStep cur = lds_step(bf, 0);
; #pragma unroll
;     for (int j = 0; j < 16; ++j) {
;       RStep nxt = cur;
;       if (j + 1 < 16) nxt = lds_step(bf, j + 1);
;       f2v sa2 = SA * cur.a4.xy + SB * cur.a4.zw;
;       f2v yp2 = SA * cur.wr4.xy + SB * cur.wr4.zw;
;       float sa = sa2.x + sa2.y, yp = yp2.x + yp2.y;
;       sa = row16_sum(sa); yp = row16_sum(yp);
;       float y = yp + sa * cur.sc.x + cur.vv * cur.sc.y;
;       SA = SA * cur.w4.xy + (sa * cur.b4.xy + cur.vv * cur.k4.xy);
;       SB = SB * cur.w4.zw + (sa * cur.b4.zw + cur.vv * cur.k4.zw);
;       sy[(kg == 0 ? j * 16 : 0) + ysel - (c & 1) * 0] = y;
;       cur = nxt;
;     }
	v_mul_f32 v168, v168, v100
	v_add_f32_dpp v98, v98, v98 row_half_mirror row_mask:0xf bank_mask:0xf bound_ctrl:1
	v_add_f32_dpp v99, v99, v99 row_half_mirror row_mask:0xf bank_mask:0xf bound_ctrl:1
	v_mul_f32 v169, v169, v100
	v_add_f32_dpp v98, v98, v98 row_mirror row_mask:0xf bank_mask:0xf bound_ctrl:1
	v_add_f32_dpp v99, v99, v99 row_mirror row_mask:0xf bank_mask:0xf bound_ctrl:1
	v_mul_f32 v170, v170, v100
	v_mul_f32 v171, v171, v100
	v_fmac_f32_e32 v99, v98, v26
	v_fma_f32 v168, v138, v24, v168
	v_fma_f32 v169, v139, v25, v169
	v_fmac_f32_e32 v99, v155, v27
	v_fma_f32 v170, v140, v150, v170
	v_fma_f32 v171, v141, v151, v171
	ds_write_b32 v108, v99 offset:49408
	ds_read_b128 v[24:27], v105 offset:768
	v_fma_f32 v154, v146, v98, v168
	v_fma_f32 v155, v147, v98, v169
	v_fma_f32 v150, v148, v98, v170
	v_fma_f32 v151, v149, v98, v171
	ds_read_b128 v[98:101], v105 offset:4864
	ds_read_b128 v[130:133], v105 offset:8960
	ds_read_b128 v[138:141], v105 offset:13056
	ds_read_b128 v[146:149], v105 offset:17152
	ds_read_b32 v102, v106 offset:21248
	ds_read_b64 v[168:169], v157 offset:24600
	s_waitcnt lgkmcnt(8)
	v_mul_f32 v22, v22, v150
	v_mul_f32 v23, v23, v151
	v_fma_f32 v20, v20, v154, v22
	v_fma_f32 v21, v21, v155, v23
	v_mul_f32 v22, v30, v150
	v_mul_f32 v23, v31, v151
	v_add_f32_e32 v20, v20, v21
	v_fma_f32 v22, v28, v154, v22
	v_fma_f32 v23, v29, v155, v23
	v_add_f32_dpp v20, v20, v20 quad_perm:[1,0,3,2] row_mask:0xf bank_mask:0xf bound_ctrl:1
	v_add_f32_e32 v21, v22, v23
	v_mul_f32 v142, v142, v96
	v_add_f32_dpp v20, v20, v20 quad_perm:[2,3,0,1] row_mask:0xf bank_mask:0xf bound_ctrl:1
	v_add_f32_dpp v21, v21, v21 quad_perm:[1,0,3,2] row_mask:0xf bank_mask:0xf bound_ctrl:1
	v_mul_f32 v143, v143, v96
	v_add_f32_dpp v20, v20, v20 row_half_mirror row_mask:0xf bank_mask:0xf bound_ctrl:1
	v_add_f32_dpp v21, v21, v21 quad_perm:[2,3,0,1] row_mask:0xf bank_mask:0xf bound_ctrl:1
	v_mul_f32 v145, v145, v96
	v_add_f32_dpp v20, v20, v20 row_mirror row_mask:0xf bank_mask:0xf bound_ctrl:1
	v_add_f32_dpp v21, v21, v21 row_half_mirror row_mask:0xf bank_mask:0xf bound_ctrl:1
	v_mul_f32 v144, v144, v96
	v_fma_f32 v142, v126, v154, v142
	v_add_f32_dpp v28, v21, v21 row_mirror row_mask:0xf bank_mask:0xf bound_ctrl:1
	v_fma_f32 v143, v127, v155, v143
	v_fma_f32 v144, v128, v150, v144
	v_fmac_f32_e32 v28, v20, v152
	v_fma_f32 v145, v129, v151, v145
	v_fma_f32 v150, v136, v20, v144
	v_fmac_f32_e32 v28, v96, v153
	v_fma_f32 v151, v137, v20, v145
	v_fma_f32 v152, v134, v20, v142
	ds_write_b32 v109, v28 offset:49408
	v_fma_f32 v153, v135, v20, v143
	ds_read_b128 v[20:23], v105 offset:1024
	ds_read_b128 v[28:31], v105 offset:5120
	s_waitcnt lgkmcnt(3)
	v_mul_f32 v26, v26, v150
	v_mul_f32 v27, v27, v151
	ds_read_b128 v[126:129], v105 offset:9216
	v_fma_f32 v24, v24, v152, v26
	v_fma_f32 v25, v25, v153, v27
	v_mul_f32 v26, v100, v150
	v_mul_f32 v27, v101, v151
	ds_read_b128 v[134:137], v105 offset:13312
	ds_read_b128 v[142:145], v105 offset:17408
	v_fma_f32 v26, v98, v152, v26
	v_fma_f32 v27, v99, v153, v27
	v_add_f32_e32 v24, v24, v25
	ds_read_b32 v96, v106 offset:21504
	v_add_f32_e32 v25, v26, v27
	ds_read_b64 v[154:155], v157 offset:24608
	v_add_f32_dpp v24, v24, v24 quad_perm:[1,0,3,2] row_mask:0xf bank_mask:0xf bound_ctrl:1
	v_add_f32_dpp v25, v25, v25 quad_perm:[1,0,3,2] row_mask:0xf bank_mask:0xf bound_ctrl:1
	v_mul_f32 v146, v146, v102
	v_add_f32_dpp v24, v24, v24 quad_perm:[2,3,0,1] row_mask:0xf bank_mask:0xf bound_ctrl:1
	v_add_f32_dpp v25, v25, v25 quad_perm:[2,3,0,1] row_mask:0xf bank_mask:0xf bound_ctrl:1
	v_mul_f32 v147, v147, v102
	v_add_f32_dpp v24, v24, v24 row_half_mirror row_mask:0xf bank_mask:0xf bound_ctrl:1
	v_add_f32_dpp v25, v25, v25 row_half_mirror row_mask:0xf bank_mask:0xf bound_ctrl:1
	v_mul_f32 v149, v149, v102
	v_add_f32_dpp v24, v24, v24 row_mirror row_mask:0xf bank_mask:0xf bound_ctrl:1
	v_add_f32_dpp v98, v25, v25 row_mirror row_mask:0xf bank_mask:0xf bound_ctrl:1
	v_mul_f32 v148, v148, v102
	v_fma_f32 v146, v130, v152, v146
	v_fmac_f32_e32 v98, v24, v168
	v_fma_f32 v147, v131, v153, v147
	v_fma_f32 v148, v132, v150, v148
	v_fmac_f32_e32 v98, v102, v169
	v_fma_f32 v149, v133, v151, v149
	v_fma_f32 v152, v138, v24, v146
	ds_write_b32 v110, v98 offset:49408
	v_fma_f32 v153, v139, v24, v147
	v_fma_f32 v150, v140, v24, v148
	v_fma_f32 v151, v141, v24, v149
	ds_read_b128 v[24:27], v105 offset:1280
	ds_read_b128 v[98:101], v105 offset:5376
	ds_read_b128 v[130:133], v105 offset:9472
	ds_read_b128 v[138:141], v105 offset:13568
	ds_read_b128 v[146:149], v105 offset:17664
	ds_read_b32 v102, v106 offset:21760
	s_waitcnt lgkmcnt(14)
	ds_read_b64 v[168:169], v157 offset:24616
	s_waitcnt lgkmcnt(8)
	v_mul_f32 v22, v22, v150
	v_mul_f32 v23, v23, v151
	v_fma_f32 v20, v20, v152, v22
	v_fma_f32 v21, v21, v153, v23
	v_mul_f32 v22, v30, v150
	v_mul_f32 v23, v31, v151
	v_add_f32_e32 v20, v20, v21
	v_fma_f32 v22, v28, v152, v22
	v_fma_f32 v23, v29, v153, v23
	v_add_f32_dpp v20, v20, v20 quad_perm:[1,0,3,2] row_mask:0xf bank_mask:0xf bound_ctrl:1
	v_add_f32_e32 v21, v22, v23
	v_mul_f32 v142, v142, v96
	v_add_f32_dpp v20, v20, v20 quad_perm:[2,3,0,1] row_mask:0xf bank_mask:0xf bound_ctrl:1
	v_add_f32_dpp v21, v21, v21 quad_perm:[1,0,3,2] row_mask:0xf bank_mask:0xf bound_ctrl:1
	v_mul_f32 v143, v143, v96
	v_add_f32_dpp v20, v20, v20 row_half_mirror row_mask:0xf bank_mask:0xf bound_ctrl:1
	v_add_f32_dpp v21, v21, v21 quad_perm:[2,3,0,1] row_mask:0xf bank_mask:0xf bound_ctrl:1
	v_mul_f32 v145, v145, v96
	v_add_f32_dpp v20, v20, v20 row_mirror row_mask:0xf bank_mask:0xf bound_ctrl:1
	v_add_f32_dpp v21, v21, v21 row_half_mirror row_mask:0xf bank_mask:0xf bound_ctrl:1
	v_mul_f32 v144, v144, v96
	v_fma_f32 v142, v126, v152, v142
	v_add_f32_dpp v28, v21, v21 row_mirror row_mask:0xf bank_mask:0xf bound_ctrl:1
	v_fma_f32 v143, v127, v153, v143
	v_fma_f32 v144, v128, v150, v144
	v_fmac_f32_e32 v28, v20, v154
	v_fma_f32 v145, v129, v151, v145
	v_fma_f32 v152, v134, v20, v142
	v_fmac_f32_e32 v28, v96, v155
	v_fma_f32 v153, v135, v20, v143
	v_fma_f32 v150, v136, v20, v144
	ds_write_b32 v111, v28 offset:49408
	v_fma_f32 v151, v137, v20, v145
	ds_read_b128 v[20:23], v105 offset:1536
	ds_read_b128 v[28:31], v105 offset:5632
	ds_read_b128 v[126:129], v105 offset:9728
	s_waitcnt lgkmcnt(4)
; DI float row16_sum(float v) { v += dppf(v, 0); v += dppf(v, 1); v += dppf(v, 2); v += dppf(v, 3); return v; }
; DI void rwkv_scan(CP p, const Ptrs& w, int l, int item, float* sm) {
;     ...
;   auto run_chunk = [&](int c, const float* bf, float* sy) {
;     flush(max(c - 1, 0));
;     RStep cur = lds_step(bf, 0);
; #pragma unroll
;     for (int j = 0; j < 16; ++j) {
;       RStep nxt = cur;
;       if (j + 1 < 16) nxt = lds_step(bf, j + 1);
;       f2v sa2 = SA * cur.a4.xy + SB * cur.a4.zw;
;       f2v yp2 = SA * cur.wr4.xy + SB * cur.wr4.zw;
;       float sa = sa2.x + sa2.y, yp = yp2.x + yp2.y;
;       sa = row16_sum(sa); yp = row16_sum(yp);
;       float y = yp + sa * cur.sc.x + cur.vv * cur.sc.y;
;       SA = SA * cur.w4.xy + (sa * cur.b4.xy + cur.vv * cur.k4.xy);
;       SB = SB * cur.w4.zw + (sa * cur.b4.zw + cur.vv * cur.k4.zw);
;       sy[(kg == 0 ? j * 16 : 0) + ysel - (c & 1) * 0] = y;
;       cur = nxt;
;     }
	v_mul_f32 v26, v26, v150
	v_mul_f32 v27, v27, v151
	ds_read_b128 v[134:137], v105 offset:13824
	v_fma_f32 v24, v24, v152, v26
	v_fma_f32 v25, v25, v153, v27
	v_mul_f32 v26, v100, v150
	v_mul_f32 v27, v101, v151
	ds_read_b128 v[142:145], v105 offset:17920
	v_fma_f32 v26, v98, v152, v26
	v_fma_f32 v27, v99, v153, v27
	v_add_f32_e32 v24, v24, v25
	ds_read_b32 v96, v106 offset:22016
	v_add_f32_e32 v25, v26, v27
	ds_read_b64 v[154:155], v157 offset:24624
	v_add_f32_dpp v24, v24, v24 quad_perm:[1,0,3,2] row_mask:0xf bank_mask:0xf bound_ctrl:1
	v_add_f32_dpp v25, v25, v25 quad_perm:[1,0,3,2] row_mask:0xf bank_mask:0xf bound_ctrl:1
	v_mul_f32 v146, v146, v102
	v_add_f32_dpp v24, v24, v24 quad_perm:[2,3,0,1] row_mask:0xf bank_mask:0xf bound_ctrl:1
	v_add_f32_dpp v25, v25, v25 quad_perm:[2,3,0,1] row_mask:0xf bank_mask:0xf bound_ctrl:1
	v_mul_f32 v147, v147, v102
	v_add_f32_dpp v24, v24, v24 row_half_mirror row_mask:0xf bank_mask:0xf bound_ctrl:1
	v_add_f32_dpp v25, v25, v25 row_half_mirror row_mask:0xf bank_mask:0xf bound_ctrl:1
	v_mul_f32 v149, v149, v102
	v_add_f32_dpp v24, v24, v24 row_mirror row_mask:0xf bank_mask:0xf bound_ctrl:1
	v_add_f32_dpp v98, v25, v25 row_mirror row_mask:0xf bank_mask:0xf bound_ctrl:1
	v_mul_f32 v148, v148, v102
	v_fma_f32 v146, v130, v152, v146
	v_fmac_f32_e32 v98, v24, v168
	v_fma_f32 v147, v131, v153, v147
	v_fma_f32 v148, v132, v150, v148
	v_fmac_f32_e32 v98, v102, v169
	v_fma_f32 v149, v133, v151, v149
	v_fma_f32 v152, v138, v24, v146
	ds_write_b32 v112, v98 offset:49408
	v_fma_f32 v153, v139, v24, v147
	v_fma_f32 v150, v140, v24, v148
	v_fma_f32 v151, v141, v24, v149
	ds_read_b128 v[24:27], v105 offset:1792
	ds_read_b128 v[98:101], v105 offset:5888
	ds_read_b128 v[130:133], v105 offset:9984
	ds_read_b128 v[138:141], v105 offset:14080
	ds_read_b128 v[146:149], v105 offset:18176
	ds_read_b32 v102, v106 offset:22272
	s_waitcnt lgkmcnt(14)
	ds_read_b64 v[168:169], v157 offset:24632
	s_waitcnt lgkmcnt(8)
	v_mul_f32 v22, v22, v150
	v_mul_f32 v23, v23, v151
	v_fma_f32 v20, v20, v152, v22
	v_fma_f32 v21, v21, v153, v23
	v_mul_f32 v22, v30, v150
	v_mul_f32 v23, v31, v151
	v_add_f32_e32 v20, v20, v21
	v_fma_f32 v22, v28, v152, v22
	v_fma_f32 v23, v29, v153, v23
	v_add_f32_dpp v20, v20, v20 quad_perm:[1,0,3,2] row_mask:0xf bank_mask:0xf bound_ctrl:1
	v_add_f32_e32 v21, v22, v23
	v_mul_f32 v142, v142, v96
	v_add_f32_dpp v20, v20, v20 quad_perm:[2,3,0,1] row_mask:0xf bank_mask:0xf bound_ctrl:1
	v_add_f32_dpp v21, v21, v21 quad_perm:[1,0,3,2] row_mask:0xf bank_mask:0xf bound_ctrl:1
	v_mul_f32 v143, v143, v96
	v_add_f32_dpp v20, v20, v20 row_half_mirror row_mask:0xf bank_mask:0xf bound_ctrl:1
	v_add_f32_dpp v21, v21, v21 quad_perm:[2,3,0,1] row_mask:0xf bank_mask:0xf bound_ctrl:1
	v_mul_f32 v145, v145, v96
	v_add_f32_dpp v20, v20, v20 row_mirror row_mask:0xf bank_mask:0xf bound_ctrl:1
	v_add_f32_dpp v21, v21, v21 row_half_mirror row_mask:0xf bank_mask:0xf bound_ctrl:1
	v_mul_f32 v144, v144, v96
	v_fma_f32 v142, v126, v152, v142
	v_add_f32_dpp v28, v21, v21 row_mirror row_mask:0xf bank_mask:0xf bound_ctrl:1
	v_fma_f32 v143, v127, v153, v143
	v_fma_f32 v144, v128, v150, v144
	v_fmac_f32_e32 v28, v20, v154
	v_fma_f32 v145, v129, v151, v145
	v_fma_f32 v152, v134, v20, v142
	v_fmac_f32_e32 v28, v96, v155
	v_fma_f32 v153, v135, v20, v143
	v_fma_f32 v150, v136, v20, v144
	ds_write_b32 v113, v28 offset:49408
	v_fma_f32 v151, v137, v20, v145
	ds_read_b128 v[20:23], v105 offset:2048
	ds_read_b128 v[28:31], v105 offset:6144
	ds_read_b128 v[126:129], v105 offset:10240
	s_waitcnt lgkmcnt(4)
	v_mul_f32 v26, v26, v150
	v_mul_f32 v27, v27, v151
	ds_read_b128 v[134:137], v105 offset:14336
	v_fma_f32 v24, v24, v152, v26
	v_fma_f32 v25, v25, v153, v27
	v_mul_f32 v26, v100, v150
	v_mul_f32 v27, v101, v151
	ds_read_b128 v[142:145], v105 offset:18432
	v_fma_f32 v26, v98, v152, v26
	v_fma_f32 v27, v99, v153, v27
	v_add_f32_e32 v24, v24, v25
	ds_read_b32 v96, v106 offset:22528
	v_add_f32_e32 v25, v26, v27
	ds_read_b64 v[154:155], v157 offset:24640
	v_add_f32_dpp v24, v24, v24 quad_perm:[1,0,3,2] row_mask:0xf bank_mask:0xf bound_ctrl:1
	v_add_f32_dpp v25, v25, v25 quad_perm:[1,0,3,2] row_mask:0xf bank_mask:0xf bound_ctrl:1
	v_mul_f32 v146, v146, v102
	v_add_f32_dpp v24, v24, v24 quad_perm:[2,3,0,1] row_mask:0xf bank_mask:0xf bound_ctrl:1
	v_add_f32_dpp v25, v25, v25 quad_perm:[2,3,0,1] row_mask:0xf bank_mask:0xf bound_ctrl:1
	v_mul_f32 v147, v147, v102
	v_add_f32_dpp v24, v24, v24 row_half_mirror row_mask:0xf bank_mask:0xf bound_ctrl:1
	v_add_f32_dpp v25, v25, v25 row_half_mirror row_mask:0xf bank_mask:0xf bound_ctrl:1
	v_mul_f32 v149, v149, v102
	v_add_f32_dpp v24, v24, v24 row_mirror row_mask:0xf bank_mask:0xf bound_ctrl:1
	v_add_f32_dpp v98, v25, v25 row_mirror row_mask:0xf bank_mask:0xf bound_ctrl:1
	v_mul_f32 v148, v148, v102
	v_fma_f32 v146, v130, v152, v146
	v_fmac_f32_e32 v98, v24, v168
	v_fma_f32 v147, v131, v153, v147
	v_fma_f32 v148, v132, v150, v148
	v_fmac_f32_e32 v98, v102, v169
	v_fma_f32 v149, v133, v151, v149
	v_fma_f32 v152, v138, v24, v146
	ds_write_b32 v114, v98 offset:49408
	v_fma_f32 v153, v139, v24, v147
	v_fma_f32 v150, v140, v24, v148
	v_fma_f32 v151, v141, v24, v149
	ds_read_b128 v[24:27], v105 offset:2304
	ds_read_b128 v[98:101], v105 offset:6400
	ds_read_b128 v[130:133], v105 offset:10496
	ds_read_b128 v[138:141], v105 offset:14592
	ds_read_b128 v[146:149], v105 offset:18688
	ds_read_b32 v102, v106 offset:22784
	s_waitcnt lgkmcnt(14)
	ds_read_b64 v[168:169], v157 offset:24648
	s_waitcnt lgkmcnt(8)
; DI float row16_sum(float v) { v += dppf(v, 0); v += dppf(v, 1); v += dppf(v, 2); v += dppf(v, 3); return v; }
; DI void rwkv_scan(CP p, const Ptrs& w, int l, int item, float* sm) {
;     ...
;   auto run_chunk = [&](int c, const float* bf, float* sy) {
;     flush(max(c - 1, 0));
;     RStep cur = lds_step(bf, 0);
; #pragma unroll
;     for (int j = 0; j < 16; ++j) {
;       RStep nxt = cur;
;       if (j + 1 < 16) nxt = lds_step(bf, j + 1);
;       f2v sa2 = SA * cur.a4.xy + SB * cur.a4.zw;
;       f2v yp2 = SA * cur.wr4.xy + SB * cur.wr4.zw;
;       float sa = sa2.x + sa2.y, yp = yp2.x + yp2.y;
;       sa = row16_sum(sa); yp = row16_sum(yp);
;       float y = yp + sa * cur.sc.x + cur.vv * cur.sc.y;
;       SA = SA * cur.w4.xy + (sa * cur.b4.xy + cur.vv * cur.k4.xy);
;       SB = SB * cur.w4.zw + (sa * cur.b4.zw + cur.vv * cur.k4.zw);
;       sy[(kg == 0 ? j * 16 : 0) + ysel - (c & 1) * 0] = y;
;       cur = nxt;
;     }
	v_mul_f32 v22, v22, v150
	v_mul_f32 v23, v23, v151
	v_fma_f32 v20, v20, v152, v22
	v_fma_f32 v21, v21, v153, v23
	v_mul_f32 v22, v30, v150
	v_mul_f32 v23, v31, v151
	v_add_f32_e32 v20, v20, v21
	v_fma_f32 v22, v28, v152, v22
	v_fma_f32 v23, v29, v153, v23
	v_add_f32_dpp v20, v20, v20 quad_perm:[1,0,3,2] row_mask:0xf bank_mask:0xf bound_ctrl:1
	v_add_f32_e32 v21, v22, v23
	v_mul_f32 v142, v142, v96
	v_add_f32_dpp v20, v20, v20 quad_perm:[2,3,0,1] row_mask:0xf bank_mask:0xf bound_ctrl:1
	v_add_f32_dpp v21, v21, v21 quad_perm:[1,0,3,2] row_mask:0xf bank_mask:0xf bound_ctrl:1
	v_mul_f32 v143, v143, v96
	v_add_f32_dpp v20, v20, v20 row_half_mirror row_mask:0xf bank_mask:0xf bound_ctrl:1
	v_add_f32_dpp v21, v21, v21 quad_perm:[2,3,0,1] row_mask:0xf bank_mask:0xf bound_ctrl:1
	v_mul_f32 v145, v145, v96
	v_add_f32_dpp v20, v20, v20 row_mirror row_mask:0xf bank_mask:0xf bound_ctrl:1
	v_add_f32_dpp v21, v21, v21 row_half_mirror row_mask:0xf bank_mask:0xf bound_ctrl:1
	v_mul_f32 v144, v144, v96
	v_fma_f32 v142, v126, v152, v142
	v_add_f32_dpp v28, v21, v21 row_mirror row_mask:0xf bank_mask:0xf bound_ctrl:1
	v_fma_f32 v143, v127, v153, v143
	v_fma_f32 v144, v128, v150, v144
	v_fmac_f32_e32 v28, v20, v154
	v_fma_f32 v145, v129, v151, v145
	v_fma_f32 v152, v134, v20, v142
	v_fmac_f32_e32 v28, v96, v155
	v_fma_f32 v153, v135, v20, v143
	v_fma_f32 v150, v136, v20, v144
	ds_write_b32 v115, v28 offset:49408
	v_fma_f32 v151, v137, v20, v145
	ds_read_b128 v[20:23], v105 offset:2560
	ds_read_b128 v[28:31], v105 offset:6656
	ds_read_b128 v[126:129], v105 offset:10752
	s_waitcnt lgkmcnt(4)
	v_mul_f32 v26, v26, v150
	v_mul_f32 v27, v27, v151
	ds_read_b128 v[134:137], v105 offset:14848
	v_fma_f32 v24, v24, v152, v26
	v_fma_f32 v25, v25, v153, v27
	v_mul_f32 v26, v100, v150
	v_mul_f32 v27, v101, v151
	ds_read_b128 v[142:145], v105 offset:18944
	v_fma_f32 v26, v98, v152, v26
	v_fma_f32 v27, v99, v153, v27
	v_add_f32_e32 v24, v24, v25
	ds_read_b32 v96, v106 offset:23040
	v_add_f32_e32 v25, v26, v27
	ds_read_b64 v[154:155], v157 offset:24656
	v_add_f32_dpp v24, v24, v24 quad_perm:[1,0,3,2] row_mask:0xf bank_mask:0xf bound_ctrl:1
	v_add_f32_dpp v25, v25, v25 quad_perm:[1,0,3,2] row_mask:0xf bank_mask:0xf bound_ctrl:1
	v_mul_f32 v146, v146, v102
	v_add_f32_dpp v24, v24, v24 quad_perm:[2,3,0,1] row_mask:0xf bank_mask:0xf bound_ctrl:1
	v_add_f32_dpp v25, v25, v25 quad_perm:[2,3,0,1] row_mask:0xf bank_mask:0xf bound_ctrl:1
	v_mul_f32 v147, v147, v102
	v_add_f32_dpp v24, v24, v24 row_half_mirror row_mask:0xf bank_mask:0xf bound_ctrl:1
	v_add_f32_dpp v25, v25, v25 row_half_mirror row_mask:0xf bank_mask:0xf bound_ctrl:1
	v_mul_f32 v149, v149, v102
	v_add_f32_dpp v24, v24, v24 row_mirror row_mask:0xf bank_mask:0xf bound_ctrl:1
	v_add_f32_dpp v98, v25, v25 row_mirror row_mask:0xf bank_mask:0xf bound_ctrl:1
	v_mul_f32 v148, v148, v102
	v_fma_f32 v146, v130, v152, v146
	v_fmac_f32_e32 v98, v24, v168
	v_fma_f32 v147, v131, v153, v147
	v_fma_f32 v148, v132, v150, v148
	v_fmac_f32_e32 v98, v102, v169
	v_fma_f32 v149, v133, v151, v149
	v_fma_f32 v152, v138, v24, v146
	ds_write_b32 v116, v98 offset:49408
	v_fma_f32 v153, v139, v24, v147
	v_fma_f32 v150, v140, v24, v148
	v_fma_f32 v151, v141, v24, v149
	ds_read_b128 v[24:27], v105 offset:2816
	ds_read_b128 v[98:101], v105 offset:6912
	ds_read_b128 v[130:133], v105 offset:11008
	ds_read_b128 v[138:141], v105 offset:15104
	ds_read_b128 v[146:149], v105 offset:19200
	ds_read_b32 v102, v106 offset:23296
	s_waitcnt lgkmcnt(14)
	ds_read_b64 v[168:169], v157 offset:24664
	s_waitcnt lgkmcnt(8)
	v_mul_f32 v22, v22, v150
	v_mul_f32 v23, v23, v151
	v_fma_f32 v20, v20, v152, v22
	v_fma_f32 v21, v21, v153, v23
	v_mul_f32 v22, v30, v150
	v_mul_f32 v23, v31, v151
	v_add_f32_e32 v20, v20, v21
	v_fma_f32 v22, v28, v152, v22
	v_fma_f32 v23, v29, v153, v23
	v_add_f32_dpp v20, v20, v20 quad_perm:[1,0,3,2] row_mask:0xf bank_mask:0xf bound_ctrl:1
	v_add_f32_e32 v21, v22, v23
	v_mul_f32 v142, v142, v96
	v_add_f32_dpp v20, v20, v20 quad_perm:[2,3,0,1] row_mask:0xf bank_mask:0xf bound_ctrl:1
	v_add_f32_dpp v21, v21, v21 quad_perm:[1,0,3,2] row_mask:0xf bank_mask:0xf bound_ctrl:1
	v_mul_f32 v143, v143, v96
	v_add_f32_dpp v20, v20, v20 row_half_mirror row_mask:0xf bank_mask:0xf bound_ctrl:1
	v_add_f32_dpp v21, v21, v21 quad_perm:[2,3,0,1] row_mask:0xf bank_mask:0xf bound_ctrl:1
	v_mul_f32 v145, v145, v96
	v_add_f32_dpp v20, v20, v20 row_mirror row_mask:0xf bank_mask:0xf bound_ctrl:1
	v_add_f32_dpp v21, v21, v21 row_half_mirror row_mask:0xf bank_mask:0xf bound_ctrl:1
	v_mul_f32 v144, v144, v96
	v_fma_f32 v142, v126, v152, v142
	v_add_f32_dpp v28, v21, v21 row_mirror row_mask:0xf bank_mask:0xf bound_ctrl:1
	v_fma_f32 v143, v127, v153, v143
	v_fma_f32 v144, v128, v150, v144
	v_fmac_f32_e32 v28, v20, v154
	v_fma_f32 v145, v129, v151, v145
	v_fma_f32 v152, v134, v20, v142
	v_fmac_f32_e32 v28, v96, v155
	v_fma_f32 v153, v135, v20, v143
	v_fma_f32 v150, v136, v20, v144
	ds_write_b32 v117, v28 offset:49408
	v_fma_f32 v151, v137, v20, v145
	ds_read_b128 v[20:23], v105 offset:3072
	ds_read_b128 v[28:31], v105 offset:7168
	ds_read_b128 v[126:129], v105 offset:11264
	s_waitcnt lgkmcnt(4)
; DI float row16_sum(float v) { v += dppf(v, 0); v += dppf(v, 1); v += dppf(v, 2); v += dppf(v, 3); return v; }
; DI void rwkv_scan(CP p, const Ptrs& w, int l, int item, float* sm) {
;     ...
;   auto run_chunk = [&](int c, const float* bf, float* sy) {
;     flush(max(c - 1, 0));
;     RStep cur = lds_step(bf, 0);
; #pragma unroll
;     for (int j = 0; j < 16; ++j) {
;       RStep nxt = cur;
;       if (j + 1 < 16) nxt = lds_step(bf, j + 1);
;       f2v sa2 = SA * cur.a4.xy + SB * cur.a4.zw;
;       f2v yp2 = SA * cur.wr4.xy + SB * cur.wr4.zw;
;       float sa = sa2.x + sa2.y, yp = yp2.x + yp2.y;
;       sa = row16_sum(sa); yp = row16_sum(yp);
;       float y = yp + sa * cur.sc.x + cur.vv * cur.sc.y;
;       SA = SA * cur.w4.xy + (sa * cur.b4.xy + cur.vv * cur.k4.xy);
;       SB = SB * cur.w4.zw + (sa * cur.b4.zw + cur.vv * cur.k4.zw);
;       sy[(kg == 0 ? j * 16 : 0) + ysel - (c & 1) * 0] = y;
;       cur = nxt;
;     }
	v_mul_f32 v26, v26, v150
	v_mul_f32 v27, v27, v151
	ds_read_b128 v[134:137], v105 offset:15360
	v_fma_f32 v24, v24, v152, v26
	v_fma_f32 v25, v25, v153, v27
	v_mul_f32 v26, v100, v150
	v_mul_f32 v27, v101, v151
	ds_read_b128 v[142:145], v105 offset:19456
	v_fma_f32 v26, v98, v152, v26
	v_fma_f32 v27, v99, v153, v27
	v_add_f32_e32 v24, v24, v25
	ds_read_b32 v96, v106 offset:23552
	v_add_f32_e32 v25, v26, v27
	ds_read_b64 v[154:155], v157 offset:24672
	v_add_f32_dpp v24, v24, v24 quad_perm:[1,0,3,2] row_mask:0xf bank_mask:0xf bound_ctrl:1
	v_add_f32_dpp v25, v25, v25 quad_perm:[1,0,3,2] row_mask:0xf bank_mask:0xf bound_ctrl:1
	v_mul_f32 v146, v146, v102
	v_add_f32_dpp v24, v24, v24 quad_perm:[2,3,0,1] row_mask:0xf bank_mask:0xf bound_ctrl:1
	v_add_f32_dpp v25, v25, v25 quad_perm:[2,3,0,1] row_mask:0xf bank_mask:0xf bound_ctrl:1
	v_mul_f32 v147, v147, v102
	v_add_f32_dpp v24, v24, v24 row_half_mirror row_mask:0xf bank_mask:0xf bound_ctrl:1
	v_add_f32_dpp v25, v25, v25 row_half_mirror row_mask:0xf bank_mask:0xf bound_ctrl:1
	v_mul_f32 v149, v149, v102
	v_add_f32_dpp v24, v24, v24 row_mirror row_mask:0xf bank_mask:0xf bound_ctrl:1
	v_add_f32_dpp v98, v25, v25 row_mirror row_mask:0xf bank_mask:0xf bound_ctrl:1
	v_mul_f32 v148, v148, v102
	v_fma_f32 v146, v130, v152, v146
	v_fmac_f32_e32 v98, v24, v168
	v_fma_f32 v147, v131, v153, v147
	v_fma_f32 v148, v132, v150, v148
	v_fmac_f32_e32 v98, v102, v169
	v_fma_f32 v149, v133, v151, v149
	v_fma_f32 v152, v138, v24, v146
	ds_write_b32 v118, v98 offset:49408
	v_fma_f32 v153, v139, v24, v147
	v_fma_f32 v150, v140, v24, v148
	v_fma_f32 v151, v141, v24, v149
	ds_read_b128 v[24:27], v105 offset:3328
	ds_read_b128 v[98:101], v105 offset:7424
	ds_read_b128 v[130:133], v105 offset:11520
	ds_read_b128 v[138:141], v105 offset:15616
	ds_read_b128 v[146:149], v105 offset:19712
	ds_read_b32 v102, v106 offset:23808
	s_waitcnt lgkmcnt(14)
	ds_read_b64 v[172:173], v157 offset:24680
	s_waitcnt lgkmcnt(8)
	v_mul_f32 v22, v22, v150
	v_mul_f32 v23, v23, v151
	v_fma_f32 v20, v20, v152, v22
	v_fma_f32 v21, v21, v153, v23
	v_mul_f32 v22, v30, v150
	v_mul_f32 v23, v31, v151
	v_add_f32_e32 v20, v20, v21
	v_fma_f32 v22, v28, v152, v22
	v_fma_f32 v23, v29, v153, v23
	v_add_f32_dpp v20, v20, v20 quad_perm:[1,0,3,2] row_mask:0xf bank_mask:0xf bound_ctrl:1
	v_add_f32_e32 v21, v22, v23
	s_waitcnt lgkmcnt(1)
	v_mul_f32 v146, v146, v102
	v_add_f32_dpp v20, v20, v20 quad_perm:[2,3,0,1] row_mask:0xf bank_mask:0xf bound_ctrl:1
	v_add_f32_dpp v21, v21, v21 quad_perm:[1,0,3,2] row_mask:0xf bank_mask:0xf bound_ctrl:1
	v_mul_f32 v147, v147, v102
	v_add_f32_dpp v20, v20, v20 row_half_mirror row_mask:0xf bank_mask:0xf bound_ctrl:1
	v_add_f32_dpp v21, v21, v21 quad_perm:[2,3,0,1] row_mask:0xf bank_mask:0xf bound_ctrl:1
	v_mul_f32 v148, v148, v102
	v_add_f32_dpp v20, v20, v20 row_mirror row_mask:0xf bank_mask:0xf bound_ctrl:1
	v_add_f32_dpp v21, v21, v21 row_half_mirror row_mask:0xf bank_mask:0xf bound_ctrl:1
	v_mul_f32 v149, v149, v102
	v_mul_f32 v22, v134, v20
	v_add_f32_dpp v28, v21, v21 row_mirror row_mask:0xf bank_mask:0xf bound_ctrl:1
	v_mul_f32 v23, v135, v20
	v_mul_f32 v21, v137, v20
	v_fmac_f32_e32 v28, v20, v154
	v_mul_f32 v20, v136, v20
	v_fma_f32 v22, v142, v96, v22
	v_fmac_f32_e32 v28, v96, v155
	v_fma_f32 v23, v143, v96, v23
	v_fma_f32 v20, v144, v96, v20
	v_fma_f32 v21, v145, v96, v21
	ds_write_b32 v119, v28 offset:49408
	v_fma_f32 v22, v126, v152, v22
	v_fma_f32 v23, v127, v153, v23
	v_fma_f32 v20, v128, v150, v20
	v_fma_f32 v21, v129, v151, v21
	ds_read_b128 v[126:129], v105 offset:3584
	ds_read_b128 v[134:137], v105 offset:7680
	v_mul_f32 v26, v26, v20
	v_mul_f32 v27, v27, v21
	ds_read_b128 v[142:145], v105 offset:11776
	v_fma_f32 v24, v24, v22, v26
	v_fma_f32 v25, v25, v23, v27
	v_mul_f32 v26, v100, v20
	v_mul_f32 v27, v101, v21
	v_add_f32_e32 v24, v24, v25
	v_fma_f32 v26, v98, v22, v26
	v_fma_f32 v27, v99, v23, v27
	v_add_f32_dpp v24, v24, v24 quad_perm:[1,0,3,2] row_mask:0xf bank_mask:0xf bound_ctrl:1
	ds_read_b128 v[150:153], v105 offset:15872
	v_add_f32_e32 v25, v26, v27
	v_add_f32_dpp v24, v24, v24 quad_perm:[2,3,0,1] row_mask:0xf bank_mask:0xf bound_ctrl:1
	ds_read_b128 v[168:171], v105 offset:19968
	v_add_f32_dpp v25, v25, v25 quad_perm:[1,0,3,2] row_mask:0xf bank_mask:0xf bound_ctrl:1
	v_add_f32_dpp v24, v24, v24 row_half_mirror row_mask:0xf bank_mask:0xf bound_ctrl:1
	ds_read_b32 v154, v106 offset:24064
	v_add_f32_dpp v25, v25, v25 quad_perm:[2,3,0,1] row_mask:0xf bank_mask:0xf bound_ctrl:1
	v_add_f32_dpp v24, v24, v24 row_mirror row_mask:0xf bank_mask:0xf bound_ctrl:1
	ds_read_b64 v[174:175], v157 offset:24688
	v_add_f32_dpp v25, v25, v25 row_half_mirror row_mask:0xf bank_mask:0xf bound_ctrl:1
	v_fma_f32 v146, v130, v22, v146
	v_fma_f32 v147, v131, v23, v147
	v_add_f32_dpp v25, v25, v25 row_mirror row_mask:0xf bank_mask:0xf bound_ctrl:1
	v_fma_f32 v148, v132, v20, v148
	v_fma_f32 v149, v133, v21, v149
	s_waitcnt lgkmcnt(5)
	v_fmac_f32_e32 v25, v24, v172
	v_fma_f32 v98, v138, v24, v146
	v_fma_f32 v99, v139, v24, v147
	v_fmac_f32_e32 v25, v102, v173
	v_fma_f32 v100, v140, v24, v148
	v_fma_f32 v101, v141, v24, v149
	ds_write_b32 v120, v25 offset:49408
	ds_read_b128 v[130:133], v105 offset:3840
	ds_read_b128 v[138:141], v105 offset:7936
	ds_read_b128 v[20:23], v105 offset:12032
	ds_read_b128 v[28:31], v105 offset:16128
	ds_read_b128 v[24:27], v105 offset:20224
	ds_read_b32 v96, v106 offset:24320
	ds_read_b64 v[146:147], v157 offset:24696
	v_mul_f32 v128, v128, v100
	v_mul_f32 v129, v129, v101
	v_fma_f32 v126, v126, v98, v128
	v_fma_f32 v127, v127, v99, v129
	v_mul_f32 v128, v136, v100
	v_mul_f32 v129, v137, v101
	v_add_f32_e32 v102, v126, v127
	v_fma_f32 v128, v134, v98, v128
	v_fma_f32 v129, v135, v99, v129
	s_waitcnt vmcnt(21)
; DI float row16_sum(float v) { v += dppf(v, 0); v += dppf(v, 1); v += dppf(v, 2); v += dppf(v, 3); return v; }
; DI void rwkv_scan(CP p, const Ptrs& w, int l, int item, float* sm) {
;     ...
;   auto stage = [&](const RPre& P, float* bufp) {
;     float rc[4], rp[4], rn[4], kc[4], kp[4], kn[4], vc[4], vp[4], vn[4], wd4[4], ad4[4];
;     up4(P.pq[0][0], rc); up4(P.pq[0][1], rp); up4(P.pq[0][2], rn);
;     up4(P.pq[1][0], kc); up4(P.pq[1][1], kp); up4(P.pq[1][2], kn);
;     up4(P.pq[2][0], vc); up4(P.pq[2][1], vp); up4(P.pq[2][2], vn);
;     up4(P.pwd, wd4); up4(P.pad_, ad4);
;     float o0[4], o1[4], o2[4], o3[4], o4[4], o5[4];
; #pragma unroll
;     for (int j = 0; j < 4; ++j) {
;       float r_s = rc[j] + ((P.pmk[0] * rp[j] + P.pmk[1] * rn[j]) - rc[j]) * mu_r[j];
;       float k_s = kc[j] + ((P.pmk[0] * kp[j] + P.pmk[1] * kn[j]) - kc[j]) * mu_k[j];
;       float v_s = vc[j] + ((P.pmk[0] * vp[j] + P.pmk[1] * vn[j]) - vc[j]) * mu_v[j];
;       float kk = k_s * kk_c[j] * P.psc[0];
;       float a = ad4[j], wv = 1.f - wd4[j];
;       o0[j] = -kk; o1[j] = wv * r_s; o2[j] = wv; o3[j] = kk * a; o4[j] = k_s * (1.f + (a - 1.f) * ka_c[j]); o5[j] = v_s;
;     }
;     float* d = bufp + sj * 64 + skq;
;     *(float4*)(d + 0 * 1024) = make_float4(o0[0], o0[1], o0[2], o0[3]);
;     *(float4*)(d + 1 * 1024) = make_float4(o1[0], o1[1], o1[2], o1[3]);
;     *(float4*)(d + 2 * 1024) = make_float4(o2[0], o2[1], o2[2], o2[3]);
;     *(float4*)(d + 3 * 1024) = make_float4(o3[0], o3[1], o3[2], o3[3]);
;     *(float4*)(d + 4 * 1024) = make_float4(o4[0], o4[1], o4[2], o4[3]);
;     *(float4*)(d + 5 * 1024) = make_float4(o5[0], o5[1], o5[2], o5[3]);
;     if (skq == 0) *(float2*)(bufp + 6 * 1024 + sj * 2) = make_float2(P.psc[1], P.psc[2]);
;   };
;     ...
;       f2v sa2 = SA * cur.a4.xy + SB * cur.a4.zw;
;       f2v yp2 = SA * cur.wr4.xy + SB * cur.wr4.zw;
;       float sa = sa2.x + sa2.y, yp = yp2.x + yp2.y;
;       sa = row16_sum(sa); yp = row16_sum(yp);
;       float y = yp + sa * cur.sc.x + cur.vv * cur.sc.y;
;       SA = SA * cur.w4.xy + (sa * cur.b4.xy + cur.vv * cur.k4.xy);
;       SB = SB * cur.w4.zw + (sa * cur.b4.zw + cur.vv * cur.k4.zw);
;       sy[(kg == 0 ? j * 16 : 0) + ysel - (c & 1) * 0] = y;
	v_and_b32_e32 v137, 0xffff0000, v52
	v_add_f32_e32 v126, v128, v129
	v_add_f32_dpp v102, v102, v102 quad_perm:[1,0,3,2] row_mask:0xf bank_mask:0xf bound_ctrl:1
	s_waitcnt vmcnt(20)
	v_lshlrev_b32_e32 v136, 16, v54
	v_add_f32_dpp v126, v126, v126 quad_perm:[1,0,3,2] row_mask:0xf bank_mask:0xf bound_ctrl:1
	v_add_f32_dpp v102, v102, v102 quad_perm:[2,3,0,1] row_mask:0xf bank_mask:0xf bound_ctrl:1
	s_waitcnt vmcnt(16)
	v_lshlrev_b32_e32 v134, 16, v64
	v_add_f32_dpp v126, v126, v126 quad_perm:[2,3,0,1] row_mask:0xf bank_mask:0xf bound_ctrl:1
	v_add_f32_dpp v102, v102, v102 row_half_mirror row_mask:0xf bank_mask:0xf bound_ctrl:1
	v_and_b32_e32 v135, 0xffff0000, v64
	v_add_f32_dpp v126, v126, v126 row_half_mirror row_mask:0xf bank_mask:0xf bound_ctrl:1
	v_add_f32_dpp v102, v102, v102 row_mirror row_mask:0xf bank_mask:0xf bound_ctrl:1
	v_lshlrev_b32_e32 v64, 16, v65
	v_add_f32_dpp v128, v126, v126 row_mirror row_mask:0xf bank_mask:0xf bound_ctrl:1
	s_waitcnt lgkmcnt(11)
	v_mul_f32 v126, v150, v102
	v_mul_f32 v127, v151, v102
	s_waitcnt lgkmcnt(8)
	v_fmac_f32_e32 v128, v102, v174
	v_fma_f32 v126, v168, v154, v126
	v_fma_f32 v127, v169, v154, v127
	v_fmac_f32_e32 v128, v154, v175
	v_fma_f32 v98, v142, v98, v126
	v_fma_f32 v99, v143, v99, v127
	v_mul_f32 v126, v152, v102
	v_mul_f32 v127, v153, v102
	ds_write_b32 v121, v128 offset:49408
	v_fma_f32 v126, v170, v154, v126
	v_fma_f32 v127, v171, v154, v127
	v_and_b32_e32 v65, 0xffff0000, v65
	v_fma_f32 v100, v144, v100, v126
	v_fma_f32 v101, v145, v101, v127
	s_waitcnt lgkmcnt(7)
	v_mul_f32 v126, v132, v100
	v_mul_f32 v127, v133, v101
	s_waitcnt lgkmcnt(6)
	v_mul_f32 v128, v140, v100
	v_mul_f32 v129, v141, v101
	v_fma_f32 v126, v130, v98, v126
	v_fma_f32 v127, v131, v99, v127
	v_fma_f32 v128, v138, v98, v128
	v_fma_f32 v129, v139, v99, v129
	v_add_f32_e32 v102, v126, v127
	v_add_f32_e32 v126, v128, v129
	v_lshlrev_b32_e32 v138, 16, v52
	v_add_f32_dpp v102, v102, v102 quad_perm:[1,0,3,2] row_mask:0xf bank_mask:0xf bound_ctrl:1
	v_add_f32_dpp v126, v126, v126 quad_perm:[1,0,3,2] row_mask:0xf bank_mask:0xf bound_ctrl:1
	v_and_b32_e32 v139, 0xffff0000, v54
	v_add_f32_dpp v102, v102, v102 quad_perm:[2,3,0,1] row_mask:0xf bank_mask:0xf bound_ctrl:1
	v_add_f32_dpp v126, v126, v126 quad_perm:[2,3,0,1] row_mask:0xf bank_mask:0xf bound_ctrl:1
	v_and_b32_e32 v141, 0xffff0000, v53
	v_add_f32_dpp v102, v102, v102 row_half_mirror row_mask:0xf bank_mask:0xf bound_ctrl:1
	v_add_f32_dpp v126, v126, v126 row_half_mirror row_mask:0xf bank_mask:0xf bound_ctrl:1
	v_lshlrev_b32_e32 v52, 16, v53
	v_add_f32_dpp v102, v102, v102 row_mirror row_mask:0xf bank_mask:0xf bound_ctrl:1
	v_add_f32_dpp v126, v126, v126 row_mirror row_mask:0xf bank_mask:0xf bound_ctrl:1
	s_waitcnt lgkmcnt(1)
	v_fmac_f32_e32 v126, v102, v146
	v_and_b32_e32 v53, 0xffff0000, v55
	v_fmac_f32_e32 v126, v96, v147
	v_mul_f32 v138, v95, v138
	v_mul_f32 v139, v94, v139
	v_lshlrev_b32_e32 v140, 16, v55
	v_mul_f32 v52, v95, v52
	v_mul_f32 v53, v94, v53
	ds_write_b32 v122, v126 offset:49408
	v_lshlrev_b32_e32 v126, 16, v58
	v_and_b32_e32 v127, 0xffff0000, v58
	v_lshlrev_b32_e32 v128, 16, v59
	v_and_b32_e32 v129, 0xffff0000, v59
	v_lshlrev_b32_e32 v58, 16, v60
	v_and_b32_e32 v59, 0xffff0000, v60
	v_lshlrev_b32_e32 v60, 16, v61
	v_and_b32_e32 v61, 0xffff0000, v61
	v_fma_f32 v136, v94, v136, v138
	v_fma_f32 v137, v95, v137, v139
	v_fma_f32 v52, v94, v140, v52
	v_fma_f32 v53, v95, v141, v53
	v_sub_f32 v136, v136, v58
	v_sub_f32 v137, v137, v59
	v_sub_f32 v52, v52, v60
	v_sub_f32 v53, v53, v61
	v_fma_f32 v136, v8, v136, v58
	v_fma_f32 v137, v9, v137, v59
	v_fma_f32 v140, v10, v52, v60
	v_fma_f32 v141, v11, v53, v61
	v_mul_f32 v58, v12, v136
	v_mul_f32 v59, v13, v137
	v_mul_f32 v52, v14, v140
	v_mul_f32 v53, v15, v141
	s_waitcnt vmcnt(15)
	v_mul_f32 v138, v56, v58
	v_mul_f32 v139, v56, v59
	v_mul_f32 v142, v56, v52
	v_mul_f32 v143, v56, v53
	v_xor_b32_e32 v59, 0x80000000, v139
	v_xor_b32_e32 v58, 0x80000000, v138
	v_xor_b32_e32 v61, 0x80000000, v143
	v_xor_b32_e32 v60, 0x80000000, v142
	ds_write_b128 v103, v[58:61] offset:24704
	v_lshlrev_b32_e32 v59, 16, v48
	v_and_b32_e32 v61, s0, v48
	v_and_b32_e32 v60, 0xffff0000, v50
	v_pk_mov_b32 v[58:59], v[58:59], v[60:61] op_sel:[1,0]
	v_lshlrev_b32_e32 v54, 16, v50
	v_and_b32_e32 v55, 0xffff0000, v48
	v_mul_f32 v58, v95, v58
	v_mul_f32 v59, v94, v59
	v_fma_f32 v54, v94, v54, v58
	v_fma_f32 v55, v95, v55, v59
	v_lshlrev_b32_e32 v132, 16, v66
	v_and_b32_e32 v133, 0xffff0000, v66
	v_sub_f32 v54, v54, v126
	v_sub_f32 v55, v55, v127
	v_lshlrev_b32_e32 v66, 16, v67
	v_and_b32_e32 v67, 0xffff0000, v67
	v_sub_f32 v52, 1.0, v132
	v_sub_f32 v53, 1.0, v133
	v_fma_f32 v54, v0, v54, v126
	v_fma_f32 v55, v1, v55, v127
	v_and_b32_e32 v61, 0xffff0000, v49
	v_mul_f32 v58, v54, v52
	v_mul_f32 v59, v55, v53
	v_sub_f32 v54, 1.0, v66
	v_sub_f32 v55, 1.0, v67
	v_lshlrev_b32_e32 v67, 16, v49
	v_and_b32_e32 v49, s0, v49
	v_and_b32_e32 v48, 0xffff0000, v51
	v_pk_mov_b32 v[48:49], v[66:67], v[48:49] op_sel:[1,0]
	v_lshlrev_b32_e32 v60, 16, v51
	v_mul_f32 v48, v95, v48
	v_mul_f32 v49, v94, v49
	v_fma_f32 v48, v94, v60, v48
	v_fma_f32 v49, v95, v61, v49
	v_mul_f32 v50, v142, v64
	v_mul_f32 v51, v143, v65
	v_sub_f32 v48, v48, v128
	v_sub_f32 v49, v49, v129
	v_lshlrev_b32_e32 v130, 16, v62
	v_fma_f32 v48, v2, v48, v128
	v_fma_f32 v49, v3, v49, v129
	v_and_b32_e32 v131, 0xffff0000, v62
	v_mul_f32 v60, v48, v54
	v_mul_f32 v61, v49, v55
	v_mul_f32 v48, v138, v134
	v_mul_f32 v49, v139, v135
	ds_write_b128 v103, v[58:61] offset:28800
	ds_write_b128 v103, v[52:55] offset:32896
	ds_write_b128 v103, v[48:51] offset:36992
	v_add_f32 v48, v134, -1.0
	v_add_f32 v49, v135, -1.0
	v_add_f32 v50, v64, -1.0
	v_add_f32 v51, v65, -1.0
	v_fma_f32 v48, v16, v48, 1.0
	v_fma_f32 v49, v17, v49, 1.0
	v_fma_f32 v50, v18, v50, 1.0
	v_fma_f32 v51, v19, v51, 1.0
	v_mul_f32 v48, v48, v136
	v_mul_f32 v49, v49, v137
	v_mul_f32 v50, v50, v140
	v_mul_f32 v51, v51, v141
	ds_write_b128 v103, v[48:51] offset:41088
	v_lshlrev_b32_e32 v51, 16, v40
	v_and_b32_e32 v53, s0, v40
	v_and_b32_e32 v52, 0xffff0000, v46
	v_pk_mov_b32 v[50:51], v[50:51], v[52:53] op_sel:[1,0]
	v_lshlrev_b32_e32 v48, 16, v46
	v_and_b32_e32 v49, 0xffff0000, v40
	v_mul_f32 v50, v95, v50
	v_mul_f32 v51, v94, v51
	v_fma_f32 v48, v94, v48, v50
	v_fma_f32 v49, v95, v49, v51
	v_and_b32_e32 v51, 0xffff0000, v41
	v_lshlrev_b32_e32 v53, 16, v41
	v_and_b32_e32 v41, s0, v41
	v_and_b32_e32 v40, 0xffff0000, v47
	v_pk_mov_b32 v[40:41], v[52:53], v[40:41] op_sel:[1,0]
	v_lshlrev_b32_e32 v50, 16, v47
	v_mul_f32 v40, v95, v40
	v_mul_f32 v41, v94, v41
	v_lshlrev_b32_e32 v62, 16, v63
	v_and_b32_e32 v63, 0xffff0000, v63
	v_fma_f32 v40, v94, v50, v40
	v_fma_f32 v41, v95, v51, v41
	v_sub_f32 v48, v48, v130
	v_sub_f32 v49, v49, v131
	v_sub_f32 v40, v40, v62
	v_sub_f32 v41, v41, v63
	v_fma_f32 v48, v4, v48, v130
	v_fma_f32 v49, v5, v49, v131
	v_fma_f32 v50, v6, v40, v62
	v_fma_f32 v51, v7, v41, v63
	ds_write_b128 v103, v[48:51] offset:45184
	s_and_saveexec_b64 s[4:5], s[40:41]
	s_cbranch_execz .LBB0_556
; DI float row16_sum(float v) { v += dppf(v, 0); v += dppf(v, 1); v += dppf(v, 2); v += dppf(v, 3); return v; }
; DI void rwkv_scan(CP p, const Ptrs& w, int l, int item, float* sm) {
;     ...
;   auto load = [&](int c, RPre& P) {
;     int ii = pos2i(c * 16 + sj, dir);
;     size_t tok = (size_t)b * TPB + ii;
;     const bf16_t* prow = w.pB + tok * SPB + sc_;
;     bool hp = (ii != 0) && (ii != CTXL), hn = (ii != CTXL - 1) && (ii != TPB - 1);
;     const int op = hp ? -SPB : 0, on = hn ? SPB : 0;
;     P.pmk[0] = hp ? 0.5f : 0.f; P.pmk[1] = hn ? 0.5f : 0.f;
; #pragma unroll
;     for (int q = 0; q < 3; ++q) {
;       P.pq[q][0] = *(const uint2*)(prow + q * 512);
;       P.pq[q][1] = *(const uint2*)(prow + q * 512 + op);
;       P.pq[q][2] = *(const uint2*)(prow + q * 512 + on);
;     }
;     P.pwd = *(const uint2*)(Wd + tok * 512 + sc_);
;     P.pad_ = *(const uint2*)(Ad + tok * 512 + sc_);
;     const float* sc = w.bonus + (tok * 8 + hd) * 8;
;     P.psc[0] = sc[0]; P.psc[1] = sc[1 + 3 * dir]; P.psc[2] = sc[2 + 3 * dir];
;   };
;     ...
;     if (skq == 0) *(float2*)(bufp + 6 * 1024 + sj * 2) = make_float2(P.psc[1], P.psc[2]);
;     ...
;   auto flush = [&](int c) {
;     {
;       int j = tid >> 4, rr = tid & 15;
;       int ii = pos2i(c * 16 + j, dir);
;       yout[((size_t)b * TPB + ii) * 512 + hd * 64 + rq * 16 + rr] = f2bf(sY[(c & 1) * 256 + j * 16 + rr]);
;     }
;   };
;   __syncthreads();
;   load(0, PA);
;   stage(PA, sm);
;   load(1, PB);
;   __syncthreads();
;   const int NCH = TPB / 16;
;   auto run_chunk = [&](int c, const float* bf, float* sy) {
;     flush(max(c - 1, 0));
;     RStep cur = lds_step(bf, 0);
; #pragma unroll
;     for (int j = 0; j < 16; ++j) {
;       RStep nxt = cur;
;       if (j + 1 < 16) nxt = lds_step(bf, j + 1);
;       f2v sa2 = SA * cur.a4.xy + SB * cur.a4.zw;
;       f2v yp2 = SA * cur.wr4.xy + SB * cur.wr4.zw;
;       float sa = sa2.x + sa2.y, yp = yp2.x + yp2.y;
;       sa = row16_sum(sa); yp = row16_sum(yp);
;       float y = yp + sa * cur.sc.x + cur.vv * cur.sc.y;
;       SA = SA * cur.w4.xy + (sa * cur.b4.xy + cur.vv * cur.k4.xy);
;       SB = SB * cur.w4.zw + (sa * cur.b4.zw + cur.vv * cur.k4.zw);
;       sy[(kg == 0 ? j * 16 : 0) + ysel - (c & 1) * 0] = y;
;       cur = nxt;
;     }
;     ...
;     stage(PB, sm + BUF);
;     __syncthreads();
;     load(min(c + 3, NCH - 1), PB);
;     run_chunk(c + 1, sm + BUF, sY + 256);
	s_waitcnt vmcnt(14)
	ds_write_b64 v104, v[44:45] offset:49280
.LBB0_556:
	s_or_b64 exec, exec, s[4:5]
	v_mul_f32 v28, v28, v102
	v_mul_f32 v29, v29, v102
	s_add_i32 s17, s17, 2
	v_fma_f32 v24, v24, v96, v28
	v_fma_f32 v25, v25, v96, v29
	s_min_u32 s4, s17, 0x20c
	v_fma_f32 v154, v20, v98, v24
	v_fma_f32 v155, v21, v99, v25
	v_mul_f32 v20, v30, v102
	v_mul_f32 v21, v31, v102
	v_cndmask_b32_e64 v95, 0.5, 0, s[42:43]
	v_fma_f32 v20, v26, v96, v20
	v_fma_f32 v21, v27, v96, v21
	v_cndmask_b32_e64 v94, 0.5, 0, s[44:45]
	v_fma_f32 v168, v22, v100, v20
	v_fma_f32 v169, v23, v101, v21
	v_lshl_add_u32 v20, s4, 4, v123
	v_cmp_lt_i32_e64 s[4:5], s37, v20
	s_waitcnt lgkmcnt(0)
	s_barrier
	v_cndmask_b32_e64 v21, v231, v232, s[4:5]
	v_sub_u32_e32 v21, v21, v20
	v_cndmask_b32_e32 v20, v21, v20, vcc
	v_ashrrev_i32_e32 v21, 31, v20
	v_lshl_add_u64 v[22:23], s[12:13], 0, v[20:21]
	v_mad_u64_u32 v[24:25], s[4:5], v22, s20, v[42:43]
	v_mov_b32_e32 v26, v25
	v_mad_u64_u32 v[26:27], s[4:5], v23, s20, v[26:27]
	v_and_b32_e32 v21, 0xfffffeff, v20
	v_mov_b32_e32 v25, v26
	v_and_b32_e32 v26, 0xffffdfff, v20
	v_cmp_eq_u32_e64 s[42:43], 0, v21
	v_cmp_eq_u32_e64 s[44:45], s37, v26
	s_nop 0
	v_cndmask_b32_e64 v21, -1, 0, s[42:43]
	v_cndmask_b32_e64 v20, v236, 0, s[42:43]
	v_cndmask_b32_e64 v156, v237, 0, s[44:45]
	v_lshl_add_u64 v[20:21], v[24:25], 0, v[20:21]
	v_lshl_add_u64 v[26:27], v[24:25], 0, v[156:157]
	global_load_dwordx2 v[58:59], v[24:25], off
	global_load_dwordx2 v[60:61], v[24:25], off offset:1024
	global_load_dwordx2 v[62:63], v[24:25], off offset:2048
	global_load_dwordx2 v[48:49], v[20:21], off
	global_load_dwordx2 v[50:51], v[26:27], off
	global_load_dwordx2 v[52:53], v[20:21], off offset:1024
	global_load_dwordx2 v[40:41], v[20:21], off offset:2048
	v_lshlrev_b64 v[20:21], 10, v[22:23]
	v_lshl_add_u64 v[24:25], v[34:35], 0, v[20:21]
	v_lshl_add_u64 v[20:21], v[36:37], 0, v[20:21]
	global_load_dwordx2 v[54:55], v[26:27], off offset:1024
	global_load_dwordx2 v[46:47], v[26:27], off offset:2048
	global_load_dwordx2 v[66:67], v[24:25], off
	global_load_dwordx2 v[64:65], v[20:21], off
	v_lshlrev_b64 v[20:21], 8, v[22:23]
	v_lshl_add_u64 v[20:21], s[6:7], 0, v[20:21]
	v_lshl_add_u64 v[22:23], v[20:21], 0, s[90:91]
	global_load_dword v56, v[20:21], off
	global_load_dwordx2 v[44:45], v[22:23], off offset:4
	ds_read_b32 v21, v83 offset:49408
	v_cmp_lt_i32_e64 s[4:5], s37, v125
	s_waitcnt lgkmcnt(0)
	v_cvt_pk_bf16_f32 v22, v21, s0
	v_cndmask_b32_e64 v20, v231, v232, s[4:5]
	v_add_u32_e32 v20, v20, v124
	v_cndmask_b32_e32 v20, v20, v125, vcc
	v_ashrrev_i32_e32 v21, 31, v20
	v_lshl_add_u64 v[20:21], s[12:13], 0, v[20:21]
	v_lshlrev_b64 v[20:21], 10, v[20:21]
	v_lshl_add_u64 v[20:21], v[38:39], 0, v[20:21]
	global_store_short v[20:21], v22, off
	s_waitcnt lgkmcnt(0)
	v_add_u32_e32 v20, 0x80, v106
	ds_read2st64_b32 v[170:171], v20 offset0:176 offset1:177
	v_add_u32_e64 v20, s22, 0
	ds_read2_b64 v[20:23], v20 offset0:16 offset1:17
	ds_read_b128 v[24:27], v105 offset:24704
	ds_read_b128 v[28:31], v105 offset:24960
	ds_read_b128 v[98:101], v105 offset:28800
	ds_read_b128 v[126:129], v105 offset:29056
	ds_read_b128 v[130:133], v105 offset:32896
	ds_read_b128 v[134:137], v105 offset:33152
	ds_read_b128 v[138:141], v105 offset:36992
	ds_read_b128 v[142:145], v105 offset:37248
	ds_read_b128 v[146:149], v105 offset:41088
	ds_read_b128 v[150:153], v105 offset:41344
	s_waitcnt lgkmcnt(9)
	v_mul_f32 v26, v168, v26
	v_mul_f32 v27, v169, v27
	v_fma_f32 v24, v154, v24, v26
	v_fma_f32 v25, v155, v25, v27
	s_waitcnt lgkmcnt(7)
	v_mul_f32 v26, v168, v100
	v_mul_f32 v27, v169, v101
	v_add_f32_e32 v24, v24, v25
	v_fma_f32 v26, v154, v98, v26
	v_fma_f32 v27, v155, v99, v27
	v_add_f32_dpp v24, v24, v24 quad_perm:[1,0,3,2] row_mask:0xf bank_mask:0xf bound_ctrl:1
	v_add_f32_e32 v25, v26, v27
	s_nop 0
	v_add_f32_dpp v24, v24, v24 quad_perm:[2,3,0,1] row_mask:0xf bank_mask:0xf bound_ctrl:1
	v_add_f32_dpp v25, v25, v25 quad_perm:[1,0,3,2] row_mask:0xf bank_mask:0xf bound_ctrl:1
	s_nop 0
	v_add_f32_dpp v24, v24, v24 row_half_mirror row_mask:0xf bank_mask:0xf bound_ctrl:1
	v_add_f32_dpp v25, v25, v25 quad_perm:[2,3,0,1] row_mask:0xf bank_mask:0xf bound_ctrl:1
	s_nop 0
	v_add_f32_dpp v24, v24, v24 row_mirror row_mask:0xf bank_mask:0xf bound_ctrl:1
	v_add_f32_dpp v25, v25, v25 row_half_mirror row_mask:0xf bank_mask:0xf bound_ctrl:1
	s_nop 1
	v_add_f32_dpp v26, v25, v25 row_mirror row_mask:0xf bank_mask:0xf bound_ctrl:1
	s_waitcnt lgkmcnt(3)
	v_mul_f32 v25, v141, v24
	v_fmac_f32_e32 v26, v20, v24
	v_mul_f32 v20, v138, v24
	s_waitcnt lgkmcnt(1)
	v_fma_f32 v25, v149, v170, v25
	v_fmac_f32_e32 v26, v170, v21
	v_mul_f32 v21, v139, v24
	v_mul_f32 v24, v140, v24
	v_fma_f32 v20, v146, v170, v20
	v_fma_f32 v21, v147, v170, v21
	v_fma_f32 v24, v148, v170, v24
	v_fma_f32 v20, v154, v130, v20
	v_fma_f32 v21, v155, v131, v21
	ds_write_b32 v107, v26 offset:50432
	v_fma_f32 v154, v168, v132, v24
	v_fma_f32 v155, v169, v133, v25
	ds_read_b128 v[24:27], v105 offset:33408
	ds_read_b128 v[98:101], v105 offset:37504
	ds_read_b128 v[130:133], v105 offset:25216
	ds_read_b128 v[138:141], v105 offset:41600
	v_mul_f32 v30, v30, v154
	v_mul_f32 v31, v31, v155
	ds_read_b128 v[146:149], v105 offset:29312
	v_fma_f32 v28, v28, v20, v30
	v_fma_f32 v29, v29, v21, v31
	v_mul_f32 v30, v128, v154
	v_mul_f32 v31, v129, v155
	v_add_f32_e32 v28, v28, v29
	v_fma_f32 v30, v126, v20, v30
	v_fma_f32 v31, v127, v21, v31
	v_add_f32_dpp v28, v28, v28 quad_perm:[1,0,3,2] row_mask:0xf bank_mask:0xf bound_ctrl:1
	ds_read_b32 v96, v106 offset:45696
	v_add_f32_e32 v29, v30, v31
	v_add_f32_dpp v28, v28, v28 quad_perm:[2,3,0,1] row_mask:0xf bank_mask:0xf bound_ctrl:1
	ds_read_b64 v[168:169], v157 offset:49296
	v_add_f32_dpp v29, v29, v29 quad_perm:[1,0,3,2] row_mask:0xf bank_mask:0xf bound_ctrl:1
	v_add_f32_dpp v28, v28, v28 row_half_mirror row_mask:0xf bank_mask:0xf bound_ctrl:1
	v_mov_b32_e32 v30, v171
	v_add_f32_dpp v29, v29, v29 quad_perm:[2,3,0,1] row_mask:0xf bank_mask:0xf bound_ctrl:1
	v_add_f32_dpp v28, v28, v28 row_mirror row_mask:0xf bank_mask:0xf bound_ctrl:1
	s_waitcnt lgkmcnt(1)
; DI float row16_sum(float v) { v += dppf(v, 0); v += dppf(v, 1); v += dppf(v, 2); v += dppf(v, 3); return v; }
; DI void rwkv_scan(CP p, const Ptrs& w, int l, int item, float* sm) {
;     ...
;   auto run_chunk = [&](int c, const float* bf, float* sy) {
;     flush(max(c - 1, 0));
;     RStep cur = lds_step(bf, 0);
; #pragma unroll
;     for (int j = 0; j < 16; ++j) {
;       RStep nxt = cur;
;       if (j + 1 < 16) nxt = lds_step(bf, j + 1);
;       f2v sa2 = SA * cur.a4.xy + SB * cur.a4.zw;
;       f2v yp2 = SA * cur.wr4.xy + SB * cur.wr4.zw;
;       float sa = sa2.x + sa2.y, yp = yp2.x + yp2.y;
;       sa = row16_sum(sa); yp = row16_sum(yp);
;       float y = yp + sa * cur.sc.x + cur.vv * cur.sc.y;
;       SA = SA * cur.w4.xy + (sa * cur.b4.xy + cur.vv * cur.k4.xy);
;       SB = SB * cur.w4.zw + (sa * cur.b4.zw + cur.vv * cur.k4.zw);
;       sy[(kg == 0 ? j * 16 : 0) + ysel - (c & 1) * 0] = y;
;       cur = nxt;
;     }
	v_mul_f32 v138, v138, v96
	v_add_f32_dpp v29, v29, v29 row_half_mirror row_mask:0xf bank_mask:0xf bound_ctrl:1
	v_mul_f32 v139, v139, v96
	v_mul_f32 v140, v140, v96
	v_add_f32_dpp v29, v29, v29 row_mirror row_mask:0xf bank_mask:0xf bound_ctrl:1
	v_mul_f32 v141, v141, v96
	v_fmac_f32_e32 v29, v28, v22
	v_mul_f32 v22, v142, v28
	v_fmac_f32_e32 v29, v171, v23
	v_mul_f32 v23, v143, v28
	v_fma_f32 v22, v150, v30, v22
	ds_write_b32 v108, v29 offset:50432
	v_fma_f32 v23, v151, v30, v23
	v_fma_f32 v150, v134, v20, v22
	v_mul_f32 v20, v144, v28
	v_fma_f32 v151, v135, v21, v23
	v_mul_f32 v21, v145, v28
	v_fma_f32 v20, v152, v30, v20
	v_fma_f32 v138, v24, v150, v138
	v_fma_f32 v21, v153, v30, v21
	v_fma_f32 v152, v136, v154, v20
	v_fma_f32 v139, v25, v151, v139
	v_fma_f32 v153, v137, v155, v21
	ds_read_b128 v[20:23], v105 offset:33664
	ds_read_b128 v[28:31], v105 offset:37760
	v_mul_f32 v132, v132, v152
	v_mul_f32 v133, v133, v153
	ds_read_b128 v[126:129], v105 offset:25472
	ds_read_b128 v[134:137], v105 offset:41856
	v_fma_f32 v130, v130, v150, v132
	v_fma_f32 v131, v131, v151, v133
	v_mul_f32 v132, v148, v152
	v_mul_f32 v133, v149, v153
	ds_read_b128 v[142:145], v105 offset:29568
	v_fma_f32 v132, v146, v150, v132
	v_fma_f32 v133, v147, v151, v133
	v_add_f32_e32 v130, v130, v131
	ds_read_b32 v102, v106 offset:45952
	v_add_f32_e32 v131, v132, v133
	v_add_f32_dpp v130, v130, v130 quad_perm:[1,0,3,2] row_mask:0xf bank_mask:0xf bound_ctrl:1
	ds_read_b64 v[154:155], v157 offset:49304
	v_add_f32_dpp v131, v131, v131 quad_perm:[1,0,3,2] row_mask:0xf bank_mask:0xf bound_ctrl:1
	v_add_f32_dpp v130, v130, v130 quad_perm:[2,3,0,1] row_mask:0xf bank_mask:0xf bound_ctrl:1
	v_fma_f32 v140, v26, v152, v140
	v_add_f32_dpp v131, v131, v131 quad_perm:[2,3,0,1] row_mask:0xf bank_mask:0xf bound_ctrl:1
	v_add_f32_dpp v130, v130, v130 row_half_mirror row_mask:0xf bank_mask:0xf bound_ctrl:1
	v_fma_f32 v141, v27, v153, v141
	v_add_f32_dpp v131, v131, v131 row_half_mirror row_mask:0xf bank_mask:0xf bound_ctrl:1
	v_add_f32_dpp v130, v130, v130 row_mirror row_mask:0xf bank_mask:0xf bound_ctrl:1
	v_fma_f32 v150, v98, v130, v138
	v_add_f32_dpp v131, v131, v131 row_mirror row_mask:0xf bank_mask:0xf bound_ctrl:1
	v_fma_f32 v151, v99, v130, v139
	v_fma_f32 v152, v100, v130, v140
	s_waitcnt lgkmcnt(5)
	v_fmac_f32_e32 v131, v130, v168
	v_fma_f32 v153, v101, v130, v141
	v_fmac_f32_e32 v131, v96, v169
	ds_write_b32 v109, v131 offset:50432
	ds_read_b128 v[24:27], v105 offset:33920
	ds_read_b128 v[98:101], v105 offset:38016
	ds_read_b128 v[130:133], v105 offset:25728
	ds_read_b128 v[138:141], v105 offset:42112
	ds_read_b128 v[146:149], v105 offset:29824
	ds_read_b32 v96, v106 offset:46208
	ds_read_b64 v[168:169], v157 offset:49312
	s_waitcnt lgkmcnt(10)
	v_mul_f32 v128, v128, v152
	v_mul_f32 v129, v129, v153
	v_fma_f32 v126, v126, v150, v128
	v_fma_f32 v127, v127, v151, v129
	v_add_f32_e32 v126, v126, v127
	v_mul_f32 v128, v144, v152
	v_mul_f32 v129, v145, v153
	v_add_f32_dpp v126, v126, v126 quad_perm:[1,0,3,2] row_mask:0xf bank_mask:0xf bound_ctrl:1
	v_fma_f32 v128, v142, v150, v128
	v_fma_f32 v129, v143, v151, v129
	v_add_f32_dpp v126, v126, v126 quad_perm:[2,3,0,1] row_mask:0xf bank_mask:0xf bound_ctrl:1
	s_waitcnt lgkmcnt(8)
	v_mul_f32 v134, v134, v102
	v_add_f32_e32 v127, v128, v129
	v_add_f32_dpp v126, v126, v126 row_half_mirror row_mask:0xf bank_mask:0xf bound_ctrl:1
	v_mul_f32 v135, v135, v102
	v_add_f32_dpp v127, v127, v127 quad_perm:[1,0,3,2] row_mask:0xf bank_mask:0xf bound_ctrl:1
	v_add_f32_dpp v126, v126, v126 row_mirror row_mask:0xf bank_mask:0xf bound_ctrl:1
	v_mul_f32 v136, v136, v102
	v_add_f32_dpp v127, v127, v127 quad_perm:[2,3,0,1] row_mask:0xf bank_mask:0xf bound_ctrl:1
	v_mul_f32 v137, v137, v102
	v_fma_f32 v134, v20, v150, v134
	v_add_f32_dpp v127, v127, v127 row_half_mirror row_mask:0xf bank_mask:0xf bound_ctrl:1
	v_fma_f32 v135, v21, v151, v135
	v_fma_f32 v136, v22, v152, v136
	v_add_f32_dpp v127, v127, v127 row_mirror row_mask:0xf bank_mask:0xf bound_ctrl:1
	v_fma_f32 v137, v23, v153, v137
	v_fma_f32 v150, v28, v126, v134
	v_fmac_f32_e32 v127, v126, v154
	v_fma_f32 v151, v29, v126, v135
	v_fma_f32 v152, v30, v126, v136
	v_fmac_f32_e32 v127, v102, v155
	v_fma_f32 v153, v31, v126, v137
	ds_write_b32 v110, v127 offset:50432
	ds_read_b128 v[20:23], v105 offset:34176
	ds_read_b128 v[28:31], v105 offset:38272
	ds_read_b128 v[126:129], v105 offset:25984
	s_waitcnt lgkmcnt(4)
	v_mul_f32 v132, v132, v152
	v_mul_f32 v133, v133, v153
	ds_read_b128 v[134:137], v105 offset:42368
	v_fma_f32 v130, v130, v150, v132
	v_fma_f32 v131, v131, v151, v133
	v_mul_f32 v132, v148, v152
	v_mul_f32 v133, v149, v153
	ds_read_b128 v[142:145], v105 offset:30080
	v_fma_f32 v132, v146, v150, v132
	v_fma_f32 v133, v147, v151, v133
	v_add_f32_e32 v130, v130, v131
	ds_read_b32 v102, v106 offset:46464
	v_add_f32_e32 v131, v132, v133
	v_add_f32_dpp v130, v130, v130 quad_perm:[1,0,3,2] row_mask:0xf bank_mask:0xf bound_ctrl:1
	ds_read_b64 v[154:155], v157 offset:49320
	v_add_f32_dpp v131, v131, v131 quad_perm:[1,0,3,2] row_mask:0xf bank_mask:0xf bound_ctrl:1
	v_add_f32_dpp v130, v130, v130 quad_perm:[2,3,0,1] row_mask:0xf bank_mask:0xf bound_ctrl:1
	v_mul_f32 v138, v138, v96
	v_add_f32_dpp v131, v131, v131 quad_perm:[2,3,0,1] row_mask:0xf bank_mask:0xf bound_ctrl:1
	v_add_f32_dpp v130, v130, v130 row_half_mirror row_mask:0xf bank_mask:0xf bound_ctrl:1
	v_mul_f32 v139, v139, v96
	v_add_f32_dpp v131, v131, v131 row_half_mirror row_mask:0xf bank_mask:0xf bound_ctrl:1
	v_add_f32_dpp v130, v130, v130 row_mirror row_mask:0xf bank_mask:0xf bound_ctrl:1
	v_mul_f32 v140, v140, v96
	v_add_f32_dpp v131, v131, v131 row_mirror row_mask:0xf bank_mask:0xf bound_ctrl:1
	v_mul_f32 v141, v141, v96
	v_fma_f32 v138, v24, v150, v138
	v_fmac_f32_e32 v131, v130, v168
	v_fma_f32 v139, v25, v151, v139
	v_fma_f32 v140, v26, v152, v140
	v_fmac_f32_e32 v131, v96, v169
	v_fma_f32 v141, v27, v153, v141
	v_fma_f32 v150, v98, v130, v138
	ds_write_b32 v111, v131 offset:50432
	ds_read_b128 v[24:27], v105 offset:34432
	v_fma_f32 v151, v99, v130, v139
	v_fma_f32 v152, v100, v130, v140
	v_fma_f32 v153, v101, v130, v141
	ds_read_b128 v[98:101], v105 offset:38528
	ds_read_b128 v[130:133], v105 offset:26240
	ds_read_b128 v[138:141], v105 offset:42624
	ds_read_b128 v[146:149], v105 offset:30336
	ds_read_b32 v96, v106 offset:46720
	s_waitcnt lgkmcnt(14)
; DI float row16_sum(float v) { v += dppf(v, 0); v += dppf(v, 1); v += dppf(v, 2); v += dppf(v, 3); return v; }
; DI void rwkv_scan(CP p, const Ptrs& w, int l, int item, float* sm) {
;     ...
;   auto run_chunk = [&](int c, const float* bf, float* sy) {
;     flush(max(c - 1, 0));
;     RStep cur = lds_step(bf, 0);
; #pragma unroll
;     for (int j = 0; j < 16; ++j) {
;       RStep nxt = cur;
;       if (j + 1 < 16) nxt = lds_step(bf, j + 1);
;       f2v sa2 = SA * cur.a4.xy + SB * cur.a4.zw;
;       f2v yp2 = SA * cur.wr4.xy + SB * cur.wr4.zw;
;       float sa = sa2.x + sa2.y, yp = yp2.x + yp2.y;
;       sa = row16_sum(sa); yp = row16_sum(yp);
;       float y = yp + sa * cur.sc.x + cur.vv * cur.sc.y;
;       SA = SA * cur.w4.xy + (sa * cur.b4.xy + cur.vv * cur.k4.xy);
;       SB = SB * cur.w4.zw + (sa * cur.b4.zw + cur.vv * cur.k4.zw);
;       sy[(kg == 0 ? j * 16 : 0) + ysel - (c & 1) * 0] = y;
;       cur = nxt;
;     }
	ds_read_b64 v[168:169], v157 offset:49328
	s_waitcnt lgkmcnt(8)
	v_mul_f32 v128, v128, v152
	v_mul_f32 v129, v129, v153
	v_fma_f32 v126, v126, v150, v128
	v_fma_f32 v127, v127, v151, v129
	v_add_f32_e32 v126, v126, v127
	v_mul_f32 v128, v144, v152
	v_mul_f32 v129, v145, v153
	v_add_f32_dpp v126, v126, v126 quad_perm:[1,0,3,2] row_mask:0xf bank_mask:0xf bound_ctrl:1
	v_fma_f32 v128, v142, v150, v128
	v_fma_f32 v129, v143, v151, v129
	v_add_f32_dpp v126, v126, v126 quad_perm:[2,3,0,1] row_mask:0xf bank_mask:0xf bound_ctrl:1
	v_mul_f32 v134, v134, v102
	v_add_f32_e32 v127, v128, v129
	v_add_f32_dpp v126, v126, v126 row_half_mirror row_mask:0xf bank_mask:0xf bound_ctrl:1
	v_mul_f32 v135, v135, v102
	v_add_f32_dpp v127, v127, v127 quad_perm:[1,0,3,2] row_mask:0xf bank_mask:0xf bound_ctrl:1
	v_add_f32_dpp v126, v126, v126 row_mirror row_mask:0xf bank_mask:0xf bound_ctrl:1
	v_mul_f32 v136, v136, v102
	v_add_f32_dpp v127, v127, v127 quad_perm:[2,3,0,1] row_mask:0xf bank_mask:0xf bound_ctrl:1
	v_mul_f32 v137, v137, v102
	v_fma_f32 v134, v20, v150, v134
	v_add_f32_dpp v127, v127, v127 row_half_mirror row_mask:0xf bank_mask:0xf bound_ctrl:1
	v_fma_f32 v135, v21, v151, v135
	v_fma_f32 v136, v22, v152, v136
	v_add_f32_dpp v127, v127, v127 row_mirror row_mask:0xf bank_mask:0xf bound_ctrl:1
	v_fma_f32 v137, v23, v153, v137
	v_fma_f32 v150, v28, v126, v134
	v_fmac_f32_e32 v127, v126, v154
	v_fma_f32 v151, v29, v126, v135
	v_fma_f32 v152, v30, v126, v136
	v_fmac_f32_e32 v127, v102, v155
	v_fma_f32 v153, v31, v126, v137
	ds_write_b32 v112, v127 offset:50432
	ds_read_b128 v[20:23], v105 offset:34688
	ds_read_b128 v[28:31], v105 offset:38784
	ds_read_b128 v[126:129], v105 offset:26496
	ds_read_b128 v[134:137], v105 offset:42880
	ds_read_b128 v[142:145], v105 offset:30592
	s_waitcnt lgkmcnt(6)
	v_mul_f32 v132, v132, v152
	v_mul_f32 v133, v133, v153
	ds_read_b32 v102, v106 offset:46976
	v_fma_f32 v130, v130, v150, v132
	v_fma_f32 v131, v131, v151, v133
	v_mul_f32 v132, v148, v152
	v_mul_f32 v133, v149, v153
	v_add_f32_e32 v130, v130, v131
	v_fma_f32 v132, v146, v150, v132
	v_fma_f32 v133, v147, v151, v133
	v_add_f32_dpp v130, v130, v130 quad_perm:[1,0,3,2] row_mask:0xf bank_mask:0xf bound_ctrl:1
	ds_read_b64 v[154:155], v157 offset:49336
	v_add_f32_e32 v131, v132, v133
	v_add_f32_dpp v130, v130, v130 quad_perm:[2,3,0,1] row_mask:0xf bank_mask:0xf bound_ctrl:1
	v_mul_f32 v138, v138, v96
	v_add_f32_dpp v131, v131, v131 quad_perm:[1,0,3,2] row_mask:0xf bank_mask:0xf bound_ctrl:1
	v_add_f32_dpp v130, v130, v130 row_half_mirror row_mask:0xf bank_mask:0xf bound_ctrl:1
	v_mul_f32 v139, v139, v96
	v_add_f32_dpp v131, v131, v131 quad_perm:[2,3,0,1] row_mask:0xf bank_mask:0xf bound_ctrl:1
	v_add_f32_dpp v130, v130, v130 row_mirror row_mask:0xf bank_mask:0xf bound_ctrl:1
	v_mul_f32 v140, v140, v96
	v_add_f32_dpp v131, v131, v131 row_half_mirror row_mask:0xf bank_mask:0xf bound_ctrl:1
	v_mul_f32 v141, v141, v96
	v_fma_f32 v138, v24, v150, v138
	v_add_f32_dpp v131, v131, v131 row_mirror row_mask:0xf bank_mask:0xf bound_ctrl:1
	v_fma_f32 v139, v25, v151, v139
	v_fma_f32 v140, v26, v152, v140
	v_fmac_f32_e32 v131, v130, v168
	v_fma_f32 v141, v27, v153, v141
	v_fma_f32 v150, v98, v130, v138
	v_fmac_f32_e32 v131, v96, v169
	v_fma_f32 v151, v99, v130, v139
	v_fma_f32 v152, v100, v130, v140
	ds_write_b32 v113, v131 offset:50432
	ds_read_b128 v[24:27], v105 offset:34944
	v_fma_f32 v153, v101, v130, v141
	ds_read_b128 v[98:101], v105 offset:39040
	ds_read_b128 v[130:133], v105 offset:26752
	ds_read_b128 v[138:141], v105 offset:43136
	ds_read_b128 v[146:149], v105 offset:30848
	ds_read_b32 v96, v106 offset:47232
	s_waitcnt lgkmcnt(14)
	ds_read_b64 v[168:169], v157 offset:49344
	s_waitcnt lgkmcnt(8)
	v_mul_f32 v128, v128, v152
	v_mul_f32 v129, v129, v153
	v_fma_f32 v126, v126, v150, v128
	v_fma_f32 v127, v127, v151, v129
	v_mul_f32 v128, v144, v152
	v_mul_f32 v129, v145, v153
	v_add_f32_e32 v126, v126, v127
	v_fma_f32 v128, v142, v150, v128
	v_fma_f32 v129, v143, v151, v129
	v_add_f32_dpp v126, v126, v126 quad_perm:[1,0,3,2] row_mask:0xf bank_mask:0xf bound_ctrl:1
	v_mul_f32 v134, v134, v102
	v_add_f32_e32 v127, v128, v129
	v_add_f32_dpp v126, v126, v126 quad_perm:[2,3,0,1] row_mask:0xf bank_mask:0xf bound_ctrl:1
	v_mul_f32 v135, v135, v102
	v_add_f32_dpp v127, v127, v127 quad_perm:[1,0,3,2] row_mask:0xf bank_mask:0xf bound_ctrl:1
	v_add_f32_dpp v126, v126, v126 row_half_mirror row_mask:0xf bank_mask:0xf bound_ctrl:1
	v_mul_f32 v136, v136, v102
	v_add_f32_dpp v127, v127, v127 quad_perm:[2,3,0,1] row_mask:0xf bank_mask:0xf bound_ctrl:1
	v_add_f32_dpp v126, v126, v126 row_mirror row_mask:0xf bank_mask:0xf bound_ctrl:1
	v_mul_f32 v137, v137, v102
	v_add_f32_dpp v127, v127, v127 row_half_mirror row_mask:0xf bank_mask:0xf bound_ctrl:1
	v_fma_f32 v134, v20, v150, v134
	v_fma_f32 v135, v21, v151, v135
	v_add_f32_dpp v127, v127, v127 row_mirror row_mask:0xf bank_mask:0xf bound_ctrl:1
	v_fma_f32 v136, v22, v152, v136
	v_fma_f32 v137, v23, v153, v137
	v_fmac_f32_e32 v127, v126, v154
	v_fma_f32 v150, v28, v126, v134
	v_fma_f32 v151, v29, v126, v135
	v_fmac_f32_e32 v127, v102, v155
	v_fma_f32 v152, v30, v126, v136
	v_fma_f32 v153, v31, v126, v137
	ds_write_b32 v114, v127 offset:50432
	ds_read_b128 v[20:23], v105 offset:35200
	ds_read_b128 v[28:31], v105 offset:39296
	ds_read_b128 v[126:129], v105 offset:27008
	ds_read_b128 v[134:137], v105 offset:43392
	ds_read_b128 v[142:145], v105 offset:31104
	ds_read_b32 v102, v106 offset:47488
	s_waitcnt lgkmcnt(14)
	ds_read_b64 v[154:155], v157 offset:49352
	s_waitcnt lgkmcnt(8)
; DI float row16_sum(float v) { v += dppf(v, 0); v += dppf(v, 1); v += dppf(v, 2); v += dppf(v, 3); return v; }
; DI void rwkv_scan(CP p, const Ptrs& w, int l, int item, float* sm) {
;     ...
;   auto run_chunk = [&](int c, const float* bf, float* sy) {
;     flush(max(c - 1, 0));
;     RStep cur = lds_step(bf, 0);
; #pragma unroll
;     for (int j = 0; j < 16; ++j) {
;       RStep nxt = cur;
;       if (j + 1 < 16) nxt = lds_step(bf, j + 1);
;       f2v sa2 = SA * cur.a4.xy + SB * cur.a4.zw;
;       f2v yp2 = SA * cur.wr4.xy + SB * cur.wr4.zw;
;       float sa = sa2.x + sa2.y, yp = yp2.x + yp2.y;
;       sa = row16_sum(sa); yp = row16_sum(yp);
;       float y = yp + sa * cur.sc.x + cur.vv * cur.sc.y;
;       SA = SA * cur.w4.xy + (sa * cur.b4.xy + cur.vv * cur.k4.xy);
;       SB = SB * cur.w4.zw + (sa * cur.b4.zw + cur.vv * cur.k4.zw);
;       sy[(kg == 0 ? j * 16 : 0) + ysel - (c & 1) * 0] = y;
;       cur = nxt;
;     }
	v_mul_f32 v132, v132, v152
	v_mul_f32 v133, v133, v153
	v_fma_f32 v130, v130, v150, v132
	v_fma_f32 v131, v131, v151, v133
	v_mul_f32 v132, v148, v152
	v_mul_f32 v133, v149, v153
	v_add_f32_e32 v130, v130, v131
	v_fma_f32 v132, v146, v150, v132
	v_fma_f32 v133, v147, v151, v133
	v_add_f32_dpp v130, v130, v130 quad_perm:[1,0,3,2] row_mask:0xf bank_mask:0xf bound_ctrl:1
	v_mul_f32 v138, v138, v96
	v_add_f32_e32 v131, v132, v133
	v_add_f32_dpp v130, v130, v130 quad_perm:[2,3,0,1] row_mask:0xf bank_mask:0xf bound_ctrl:1
	v_mul_f32 v139, v139, v96
	v_add_f32_dpp v131, v131, v131 quad_perm:[1,0,3,2] row_mask:0xf bank_mask:0xf bound_ctrl:1
	v_add_f32_dpp v130, v130, v130 row_half_mirror row_mask:0xf bank_mask:0xf bound_ctrl:1
	v_mul_f32 v140, v140, v96
	v_add_f32_dpp v131, v131, v131 quad_perm:[2,3,0,1] row_mask:0xf bank_mask:0xf bound_ctrl:1
	v_add_f32_dpp v130, v130, v130 row_mirror row_mask:0xf bank_mask:0xf bound_ctrl:1
	v_mul_f32 v141, v141, v96
	v_add_f32_dpp v131, v131, v131 row_half_mirror row_mask:0xf bank_mask:0xf bound_ctrl:1
	v_fma_f32 v138, v24, v150, v138
	v_fma_f32 v139, v25, v151, v139
	v_add_f32_dpp v131, v131, v131 row_mirror row_mask:0xf bank_mask:0xf bound_ctrl:1
	v_fma_f32 v140, v26, v152, v140
	v_fma_f32 v141, v27, v153, v141
	v_fmac_f32_e32 v131, v130, v168
	v_fma_f32 v150, v98, v130, v138
	v_fma_f32 v151, v99, v130, v139
	v_fmac_f32_e32 v131, v96, v169
	v_fma_f32 v152, v100, v130, v140
	v_fma_f32 v153, v101, v130, v141
	ds_write_b32 v115, v131 offset:50432
	ds_read_b128 v[24:27], v105 offset:35456
	ds_read_b128 v[98:101], v105 offset:39552
	ds_read_b128 v[130:133], v105 offset:27264
	ds_read_b128 v[138:141], v105 offset:43648
	ds_read_b128 v[146:149], v105 offset:31360
	ds_read_b32 v96, v106 offset:47744
	s_waitcnt lgkmcnt(14)
	ds_read_b64 v[168:169], v157 offset:49360
	s_waitcnt lgkmcnt(8)
	v_mul_f32 v128, v128, v152
	v_mul_f32 v129, v129, v153
	v_fma_f32 v126, v126, v150, v128
	v_fma_f32 v127, v127, v151, v129
	v_mul_f32 v128, v144, v152
	v_mul_f32 v129, v145, v153
	v_add_f32_e32 v126, v126, v127
	v_fma_f32 v128, v142, v150, v128
	v_fma_f32 v129, v143, v151, v129
	v_add_f32_dpp v126, v126, v126 quad_perm:[1,0,3,2] row_mask:0xf bank_mask:0xf bound_ctrl:1
	v_mul_f32 v134, v134, v102
	v_add_f32_e32 v127, v128, v129
	v_add_f32_dpp v126, v126, v126 quad_perm:[2,3,0,1] row_mask:0xf bank_mask:0xf bound_ctrl:1
	v_mul_f32 v135, v135, v102
	v_add_f32_dpp v127, v127, v127 quad_perm:[1,0,3,2] row_mask:0xf bank_mask:0xf bound_ctrl:1
	v_add_f32_dpp v126, v126, v126 row_half_mirror row_mask:0xf bank_mask:0xf bound_ctrl:1
	v_mul_f32 v136, v136, v102
	v_add_f32_dpp v127, v127, v127 quad_perm:[2,3,0,1] row_mask:0xf bank_mask:0xf bound_ctrl:1
	v_add_f32_dpp v126, v126, v126 row_mirror row_mask:0xf bank_mask:0xf bound_ctrl:1
	v_mul_f32 v137, v137, v102
	v_add_f32_dpp v127, v127, v127 row_half_mirror row_mask:0xf bank_mask:0xf bound_ctrl:1
	v_fma_f32 v134, v20, v150, v134
	v_fma_f32 v135, v21, v151, v135
	v_add_f32_dpp v127, v127, v127 row_mirror row_mask:0xf bank_mask:0xf bound_ctrl:1
	v_fma_f32 v136, v22, v152, v136
	v_fma_f32 v137, v23, v153, v137
	v_fmac_f32_e32 v127, v126, v154
	v_fma_f32 v150, v28, v126, v134
	v_fma_f32 v151, v29, v126, v135
	v_fmac_f32_e32 v127, v102, v155
	v_fma_f32 v152, v30, v126, v136
	v_fma_f32 v153, v31, v126, v137
	ds_write_b32 v116, v127 offset:50432
	ds_read_b128 v[20:23], v105 offset:35712
	ds_read_b128 v[28:31], v105 offset:39808
	ds_read_b128 v[126:129], v105 offset:27520
	ds_read_b128 v[134:137], v105 offset:43904
	ds_read_b128 v[142:145], v105 offset:31616
	ds_read_b32 v102, v106 offset:48000
	s_waitcnt lgkmcnt(14)
	ds_read_b64 v[154:155], v157 offset:49368
	s_waitcnt lgkmcnt(8)
	v_mul_f32 v132, v132, v152
	v_mul_f32 v133, v133, v153
	v_fma_f32 v130, v130, v150, v132
	v_fma_f32 v131, v131, v151, v133
	v_mul_f32 v132, v148, v152
	v_mul_f32 v133, v149, v153
	v_add_f32_e32 v130, v130, v131
	v_fma_f32 v132, v146, v150, v132
	v_fma_f32 v133, v147, v151, v133
	v_add_f32_dpp v130, v130, v130 quad_perm:[1,0,3,2] row_mask:0xf bank_mask:0xf bound_ctrl:1
	v_mul_f32 v138, v138, v96
	v_add_f32_e32 v131, v132, v133
	v_add_f32_dpp v130, v130, v130 quad_perm:[2,3,0,1] row_mask:0xf bank_mask:0xf bound_ctrl:1
	v_mul_f32 v139, v139, v96
	v_add_f32_dpp v131, v131, v131 quad_perm:[1,0,3,2] row_mask:0xf bank_mask:0xf bound_ctrl:1
	v_add_f32_dpp v130, v130, v130 row_half_mirror row_mask:0xf bank_mask:0xf bound_ctrl:1
	v_mul_f32 v140, v140, v96
	v_add_f32_dpp v131, v131, v131 quad_perm:[2,3,0,1] row_mask:0xf bank_mask:0xf bound_ctrl:1
	v_add_f32_dpp v130, v130, v130 row_mirror row_mask:0xf bank_mask:0xf bound_ctrl:1
	v_mul_f32 v141, v141, v96
	v_add_f32_dpp v131, v131, v131 row_half_mirror row_mask:0xf bank_mask:0xf bound_ctrl:1
	v_fma_f32 v138, v24, v150, v138
	v_fma_f32 v139, v25, v151, v139
	v_add_f32_dpp v131, v131, v131 row_mirror row_mask:0xf bank_mask:0xf bound_ctrl:1
	v_fma_f32 v140, v26, v152, v140
	v_fma_f32 v141, v27, v153, v141
	v_fmac_f32_e32 v131, v130, v168
	v_fma_f32 v150, v98, v130, v138
	v_fma_f32 v151, v99, v130, v139
	v_fmac_f32_e32 v131, v96, v169
	v_fma_f32 v152, v100, v130, v140
	v_fma_f32 v153, v101, v130, v141
	ds_write_b32 v117, v131 offset:50432
	ds_read_b128 v[24:27], v105 offset:35968
	ds_read_b128 v[98:101], v105 offset:40064
	ds_read_b128 v[130:133], v105 offset:27776
	ds_read_b128 v[138:141], v105 offset:44160
	ds_read_b128 v[146:149], v105 offset:31872
	ds_read_b32 v96, v106 offset:48256
	s_waitcnt lgkmcnt(14)
	ds_read_b64 v[168:169], v157 offset:49376
	s_waitcnt lgkmcnt(8)
; DI float row16_sum(float v) { v += dppf(v, 0); v += dppf(v, 1); v += dppf(v, 2); v += dppf(v, 3); return v; }
; DI void rwkv_scan(CP p, const Ptrs& w, int l, int item, float* sm) {
;     ...
;   auto run_chunk = [&](int c, const float* bf, float* sy) {
;     flush(max(c - 1, 0));
;     RStep cur = lds_step(bf, 0);
; #pragma unroll
;     for (int j = 0; j < 16; ++j) {
;       RStep nxt = cur;
;       if (j + 1 < 16) nxt = lds_step(bf, j + 1);
;       f2v sa2 = SA * cur.a4.xy + SB * cur.a4.zw;
;       f2v yp2 = SA * cur.wr4.xy + SB * cur.wr4.zw;
;       float sa = sa2.x + sa2.y, yp = yp2.x + yp2.y;
;       sa = row16_sum(sa); yp = row16_sum(yp);
;       float y = yp + sa * cur.sc.x + cur.vv * cur.sc.y;
;       SA = SA * cur.w4.xy + (sa * cur.b4.xy + cur.vv * cur.k4.xy);
;       SB = SB * cur.w4.zw + (sa * cur.b4.zw + cur.vv * cur.k4.zw);
;       sy[(kg == 0 ? j * 16 : 0) + ysel - (c & 1) * 0] = y;
;       cur = nxt;
;     }
	v_mul_f32 v128, v128, v152
	v_mul_f32 v129, v129, v153
	v_fma_f32 v126, v126, v150, v128
	v_fma_f32 v127, v127, v151, v129
	v_mul_f32 v128, v144, v152
	v_mul_f32 v129, v145, v153
	v_add_f32_e32 v126, v126, v127
	v_fma_f32 v128, v142, v150, v128
	v_fma_f32 v129, v143, v151, v129
	v_add_f32_dpp v126, v126, v126 quad_perm:[1,0,3,2] row_mask:0xf bank_mask:0xf bound_ctrl:1
	v_mul_f32 v134, v134, v102
	v_add_f32_e32 v127, v128, v129
	v_add_f32_dpp v126, v126, v126 quad_perm:[2,3,0,1] row_mask:0xf bank_mask:0xf bound_ctrl:1
	v_mul_f32 v135, v135, v102
	v_add_f32_dpp v127, v127, v127 quad_perm:[1,0,3,2] row_mask:0xf bank_mask:0xf bound_ctrl:1
	v_add_f32_dpp v126, v126, v126 row_half_mirror row_mask:0xf bank_mask:0xf bound_ctrl:1
	v_mul_f32 v136, v136, v102
	v_add_f32_dpp v127, v127, v127 quad_perm:[2,3,0,1] row_mask:0xf bank_mask:0xf bound_ctrl:1
	v_add_f32_dpp v126, v126, v126 row_mirror row_mask:0xf bank_mask:0xf bound_ctrl:1
	v_mul_f32 v137, v137, v102
	v_add_f32_dpp v127, v127, v127 row_half_mirror row_mask:0xf bank_mask:0xf bound_ctrl:1
	v_fma_f32 v134, v20, v150, v134
	v_fma_f32 v135, v21, v151, v135
	v_add_f32_dpp v127, v127, v127 row_mirror row_mask:0xf bank_mask:0xf bound_ctrl:1
	v_fma_f32 v136, v22, v152, v136
	v_fma_f32 v137, v23, v153, v137
	v_fmac_f32_e32 v127, v126, v154
	v_fma_f32 v150, v28, v126, v134
	v_fma_f32 v151, v29, v126, v135
	v_fmac_f32_e32 v127, v102, v155
	v_fma_f32 v152, v30, v126, v136
	v_fma_f32 v153, v31, v126, v137
	ds_write_b32 v118, v127 offset:50432
	ds_read_b128 v[20:23], v105 offset:36224
	ds_read_b128 v[28:31], v105 offset:40320
	ds_read_b128 v[126:129], v105 offset:28032
	ds_read_b128 v[134:137], v105 offset:44416
	ds_read_b128 v[142:145], v105 offset:32128
	ds_read_b32 v102, v106 offset:48512
	s_waitcnt lgkmcnt(14)
	ds_read_b64 v[154:155], v157 offset:49384
	s_waitcnt lgkmcnt(8)
	v_mul_f32 v132, v132, v152
	v_mul_f32 v133, v133, v153
	v_fma_f32 v130, v130, v150, v132
	v_fma_f32 v131, v131, v151, v133
	v_mul_f32 v132, v148, v152
	v_mul_f32 v133, v149, v153
	v_add_f32_e32 v130, v130, v131
	v_fma_f32 v132, v146, v150, v132
	v_fma_f32 v133, v147, v151, v133
	v_add_f32_dpp v130, v130, v130 quad_perm:[1,0,3,2] row_mask:0xf bank_mask:0xf bound_ctrl:1
	v_mul_f32 v138, v138, v96
	v_add_f32_e32 v131, v132, v133
	v_add_f32_dpp v130, v130, v130 quad_perm:[2,3,0,1] row_mask:0xf bank_mask:0xf bound_ctrl:1
	v_mul_f32 v139, v139, v96
	v_add_f32_dpp v131, v131, v131 quad_perm:[1,0,3,2] row_mask:0xf bank_mask:0xf bound_ctrl:1
	v_add_f32_dpp v130, v130, v130 row_half_mirror row_mask:0xf bank_mask:0xf bound_ctrl:1
	v_mul_f32 v140, v140, v96
	v_add_f32_dpp v131, v131, v131 quad_perm:[2,3,0,1] row_mask:0xf bank_mask:0xf bound_ctrl:1
	v_add_f32_dpp v130, v130, v130 row_mirror row_mask:0xf bank_mask:0xf bound_ctrl:1
	v_mul_f32 v141, v141, v96
	v_add_f32_dpp v131, v131, v131 row_half_mirror row_mask:0xf bank_mask:0xf bound_ctrl:1
	v_fma_f32 v138, v24, v150, v138
	v_fma_f32 v139, v25, v151, v139
	v_add_f32_dpp v131, v131, v131 row_mirror row_mask:0xf bank_mask:0xf bound_ctrl:1
	v_fma_f32 v140, v26, v152, v140
	v_fma_f32 v141, v27, v153, v141
	v_fmac_f32_e32 v131, v130, v168
	v_fma_f32 v24, v98, v130, v138
	v_fma_f32 v25, v99, v130, v139
	v_fmac_f32_e32 v131, v96, v169
	v_fma_f32 v26, v100, v130, v140
	v_fma_f32 v27, v101, v130, v141
	ds_write_b32 v119, v131 offset:50432
	ds_read_b128 v[98:101], v105 offset:36480
	ds_read_b128 v[130:133], v105 offset:40576
	ds_read_b128 v[138:141], v105 offset:28288
	ds_read_b128 v[146:149], v105 offset:44672
	ds_read_b128 v[150:153], v105 offset:32384
	ds_read_b32 v156, v106 offset:48768
	s_waitcnt lgkmcnt(14)
	ds_read_b64 v[168:169], v157 offset:49392
	s_waitcnt lgkmcnt(8)
	v_mul_f32 v128, v128, v26
	v_mul_f32 v129, v129, v27
	v_fma_f32 v126, v126, v24, v128
	v_fma_f32 v127, v127, v25, v129
	v_mul_f32 v128, v144, v26
	v_mul_f32 v129, v145, v27
	v_add_f32_e32 v96, v126, v127
	v_fma_f32 v128, v142, v24, v128
	v_fma_f32 v129, v143, v25, v129
	v_add_f32_dpp v96, v96, v96 quad_perm:[1,0,3,2] row_mask:0xf bank_mask:0xf bound_ctrl:1
	v_mul_f32 v134, v134, v102
	v_add_f32_e32 v126, v128, v129
	v_add_f32_dpp v96, v96, v96 quad_perm:[2,3,0,1] row_mask:0xf bank_mask:0xf bound_ctrl:1
	v_mul_f32 v135, v135, v102
	v_add_f32_dpp v126, v126, v126 quad_perm:[1,0,3,2] row_mask:0xf bank_mask:0xf bound_ctrl:1
	v_add_f32_dpp v96, v96, v96 row_half_mirror row_mask:0xf bank_mask:0xf bound_ctrl:1
	v_mul_f32 v136, v136, v102
	v_add_f32_dpp v126, v126, v126 quad_perm:[2,3,0,1] row_mask:0xf bank_mask:0xf bound_ctrl:1
	v_add_f32_dpp v96, v96, v96 row_mirror row_mask:0xf bank_mask:0xf bound_ctrl:1
	v_mul_f32 v137, v137, v102
	v_add_f32_dpp v126, v126, v126 row_half_mirror row_mask:0xf bank_mask:0xf bound_ctrl:1
	v_fma_f32 v134, v20, v24, v134
	v_fma_f32 v135, v21, v25, v135
	v_add_f32_dpp v126, v126, v126 row_mirror row_mask:0xf bank_mask:0xf bound_ctrl:1
	v_fma_f32 v136, v22, v26, v136
	v_fma_f32 v137, v23, v27, v137
	v_fmac_f32_e32 v126, v96, v154
	v_fma_f32 v142, v28, v96, v134
	v_fma_f32 v143, v29, v96, v135
	v_fmac_f32_e32 v126, v102, v155
	v_fma_f32 v144, v30, v96, v136
	v_fma_f32 v145, v31, v96, v137
	ds_write_b32 v120, v126 offset:50432
	ds_read_b128 v[20:23], v105 offset:36736
	ds_read_b128 v[28:31], v105 offset:40832
	ds_read_b128 v[126:129], v105 offset:28544
	ds_read_b128 v[24:27], v105 offset:44928
	ds_read_b128 v[134:137], v105 offset:32640
	ds_read_b32 v96, v106 offset:49024
	s_waitcnt lgkmcnt(14)
	ds_read_b64 v[154:155], v157 offset:49400
	s_waitcnt lgkmcnt(8)
; DI float row16_sum(float v) { v += dppf(v, 0); v += dppf(v, 1); v += dppf(v, 2); v += dppf(v, 3); return v; }
; DI void rwkv_scan(CP p, const Ptrs& w, int l, int item, float* sm) {
;     ...
;   auto stage = [&](const RPre& P, float* bufp) {
;     float rc[4], rp[4], rn[4], kc[4], kp[4], kn[4], vc[4], vp[4], vn[4], wd4[4], ad4[4];
;     up4(P.pq[0][0], rc); up4(P.pq[0][1], rp); up4(P.pq[0][2], rn);
;     up4(P.pq[1][0], kc); up4(P.pq[1][1], kp); up4(P.pq[1][2], kn);
;     up4(P.pq[2][0], vc); up4(P.pq[2][1], vp); up4(P.pq[2][2], vn);
;     up4(P.pwd, wd4); up4(P.pad_, ad4);
;     float o0[4], o1[4], o2[4], o3[4], o4[4], o5[4];
; #pragma unroll
;     for (int j = 0; j < 4; ++j) {
;       float r_s = rc[j] + ((P.pmk[0] * rp[j] + P.pmk[1] * rn[j]) - rc[j]) * mu_r[j];
;       float k_s = kc[j] + ((P.pmk[0] * kp[j] + P.pmk[1] * kn[j]) - kc[j]) * mu_k[j];
;       float v_s = vc[j] + ((P.pmk[0] * vp[j] + P.pmk[1] * vn[j]) - vc[j]) * mu_v[j];
;       float kk = k_s * kk_c[j] * P.psc[0];
;       float a = ad4[j], wv = 1.f - wd4[j];
;       o0[j] = -kk; o1[j] = wv * r_s; o2[j] = wv; o3[j] = kk * a; o4[j] = k_s * (1.f + (a - 1.f) * ka_c[j]); o5[j] = v_s;
;     ...
;       f2v sa2 = SA * cur.a4.xy + SB * cur.a4.zw;
;       f2v yp2 = SA * cur.wr4.xy + SB * cur.wr4.zw;
;       float sa = sa2.x + sa2.y, yp = yp2.x + yp2.y;
;       sa = row16_sum(sa); yp = row16_sum(yp);
;       float y = yp + sa * cur.sc.x + cur.vv * cur.sc.y;
;       SA = SA * cur.w4.xy + (sa * cur.b4.xy + cur.vv * cur.k4.xy);
;       SB = SB * cur.w4.zw + (sa * cur.b4.zw + cur.vv * cur.k4.zw);
;       sy[(kg == 0 ? j * 16 : 0) + ysel - (c & 1) * 0] = y;
	v_mul_f32 v140, v140, v144
	v_mul_f32 v141, v141, v145
	v_fma_f32 v138, v138, v142, v140
	v_fma_f32 v139, v139, v143, v141
	v_mul_f32 v140, v152, v144
	v_mul_f32 v141, v153, v145
	v_add_f32_e32 v102, v138, v139
	v_fma_f32 v140, v150, v142, v140
	v_fma_f32 v141, v151, v143, v141
	v_add_f32_dpp v102, v102, v102 quad_perm:[1,0,3,2] row_mask:0xf bank_mask:0xf bound_ctrl:1
	v_add_f32_e32 v138, v140, v141
	s_waitcnt vmcnt(20)
	v_and_b32_e32 v139, 0xffff0000, v80
	v_add_f32_dpp v102, v102, v102 quad_perm:[2,3,0,1] row_mask:0xf bank_mask:0xf bound_ctrl:1
	v_add_f32_dpp v138, v138, v138 quad_perm:[1,0,3,2] row_mask:0xf bank_mask:0xf bound_ctrl:1
	v_and_b32_e32 v141, 0xffff0000, v79
	v_add_f32_dpp v102, v102, v102 row_half_mirror row_mask:0xf bank_mask:0xf bound_ctrl:1
	v_add_f32_dpp v138, v138, v138 quad_perm:[2,3,0,1] row_mask:0xf bank_mask:0xf bound_ctrl:1
	v_lshlrev_b32_e32 v140, 16, v81
	v_add_f32_dpp v102, v102, v102 row_mirror row_mask:0xf bank_mask:0xf bound_ctrl:1
	v_mul_f32 v130, v130, v102
	v_mul_f32 v131, v131, v102
	v_add_f32_dpp v138, v138, v138 row_half_mirror row_mask:0xf bank_mask:0xf bound_ctrl:1
	s_waitcnt lgkmcnt(9)
	v_fma_f32 v130, v146, v156, v130
	v_fma_f32 v131, v147, v156, v131
	s_nop 0
	v_fma_f32 v98, v98, v142, v130
	v_fma_f32 v99, v99, v143, v131
	v_mul_f32 v130, v132, v102
	v_mul_f32 v131, v133, v102
	v_add_f32_dpp v138, v138, v138 row_mirror row_mask:0xf bank_mask:0xf bound_ctrl:1
	v_fma_f32 v130, v148, v156, v130
	v_fma_f32 v131, v149, v156, v131
	s_waitcnt lgkmcnt(8)
	v_fmac_f32_e32 v138, v102, v168
	v_fma_f32 v100, v100, v144, v130
	v_fma_f32 v101, v101, v145, v131
	v_fmac_f32_e32 v138, v156, v169
	s_waitcnt lgkmcnt(4)
	v_mul_f32 v128, v128, v100
	v_mul_f32 v129, v129, v101
	ds_write_b32 v121, v138 offset:50432
	v_fma_f32 v126, v126, v98, v128
	v_fma_f32 v127, v127, v99, v129
	s_waitcnt lgkmcnt(3)
	v_mul_f32 v128, v136, v100
	v_mul_f32 v129, v137, v101
	v_lshlrev_b32_e32 v132, 16, v85
	v_fma_f32 v128, v134, v98, v128
	v_fma_f32 v129, v135, v99, v129
	v_and_b32_e32 v133, 0xffff0000, v85
	v_and_b32_e32 v85, 0xffff0000, v78
	v_lshlrev_b32_e32 v138, 16, v78
	v_lshlrev_b32_e32 v78, 16, v79
	v_and_b32_e32 v79, 0xffff0000, v81
	v_add_f32_e32 v102, v126, v127
	v_add_f32_e32 v126, v128, v129
	v_lshlrev_b32_e32 v130, 16, v84
	v_and_b32_e32 v131, 0xffff0000, v84
	v_lshlrev_b32_e32 v84, 16, v80
	v_mul_f32 v138, v95, v138
	v_mul_f32 v139, v94, v139
	v_mul_f32 v78, v95, v78
	v_mul_f32 v79, v94, v79
	v_add_f32_dpp v102, v102, v102 quad_perm:[1,0,3,2] row_mask:0xf bank_mask:0xf bound_ctrl:1
	v_add_f32_dpp v126, v126, v126 quad_perm:[1,0,3,2] row_mask:0xf bank_mask:0xf bound_ctrl:1
	v_lshlrev_b32_e32 v128, 16, v86
	v_and_b32_e32 v129, 0xffff0000, v86
	v_lshlrev_b32_e32 v86, 16, v87
	v_and_b32_e32 v87, 0xffff0000, v87
	v_fma_f32 v84, v94, v84, v138
	v_fma_f32 v85, v95, v85, v139
	v_fma_f32 v78, v94, v140, v78
	v_fma_f32 v79, v95, v141, v79
	v_add_f32_dpp v102, v102, v102 quad_perm:[2,3,0,1] row_mask:0xf bank_mask:0xf bound_ctrl:1
	v_add_f32_dpp v126, v126, v126 quad_perm:[2,3,0,1] row_mask:0xf bank_mask:0xf bound_ctrl:1
	v_sub_f32 v84, v84, v128
	v_sub_f32 v85, v85, v129
	v_sub_f32 v78, v78, v86
	v_sub_f32 v79, v79, v87
	v_add_f32_dpp v102, v102, v102 row_half_mirror row_mask:0xf bank_mask:0xf bound_ctrl:1
	v_add_f32_dpp v126, v126, v126 row_half_mirror row_mask:0xf bank_mask:0xf bound_ctrl:1
	v_fma_f32 v128, v8, v84, v128
	v_fma_f32 v129, v9, v85, v129
	v_fma_f32 v140, v10, v78, v86
	v_fma_f32 v141, v11, v79, v87
	v_add_f32_dpp v102, v102, v102 row_mirror row_mask:0xf bank_mask:0xf bound_ctrl:1
	v_add_f32_dpp v126, v126, v126 row_mirror row_mask:0xf bank_mask:0xf bound_ctrl:1
	v_mul_f32 v84, v12, v128
	v_mul_f32 v85, v13, v129
	v_mul_f32 v78, v14, v140
	v_mul_f32 v79, v15, v141
	s_waitcnt lgkmcnt(1)
; DI void rwkv_scan(CP p, const Ptrs& w, int l, int item, float* sm) {
;     ...
;   auto stage = [&](const RPre& P, float* bufp) {
;     float rc[4], rp[4], rn[4], kc[4], kp[4], kn[4], vc[4], vp[4], vn[4], wd4[4], ad4[4];
;     up4(P.pq[0][0], rc); up4(P.pq[0][1], rp); up4(P.pq[0][2], rn);
;     up4(P.pq[1][0], kc); up4(P.pq[1][1], kp); up4(P.pq[1][2], kn);
;     up4(P.pq[2][0], vc); up4(P.pq[2][1], vp); up4(P.pq[2][2], vn);
;     up4(P.pwd, wd4); up4(P.pad_, ad4);
;     float o0[4], o1[4], o2[4], o3[4], o4[4], o5[4];
; #pragma unroll
;     for (int j = 0; j < 4; ++j) {
;       float r_s = rc[j] + ((P.pmk[0] * rp[j] + P.pmk[1] * rn[j]) - rc[j]) * mu_r[j];
;       float k_s = kc[j] + ((P.pmk[0] * kp[j] + P.pmk[1] * kn[j]) - kc[j]) * mu_k[j];
;       float v_s = vc[j] + ((P.pmk[0] * vp[j] + P.pmk[1] * vn[j]) - vc[j]) * mu_v[j];
;       float kk = k_s * kk_c[j] * P.psc[0];
;       float a = ad4[j], wv = 1.f - wd4[j];
;       o0[j] = -kk; o1[j] = wv * r_s; o2[j] = wv; o3[j] = kk * a; o4[j] = k_s * (1.f + (a - 1.f) * ka_c[j]); o5[j] = v_s;
;     }
;     float* d = bufp + sj * 64 + skq;
;     *(float4*)(d + 0 * 1024) = make_float4(o0[0], o0[1], o0[2], o0[3]);
;     *(float4*)(d + 1 * 1024) = make_float4(o1[0], o1[1], o1[2], o1[3]);
;     *(float4*)(d + 2 * 1024) = make_float4(o2[0], o2[1], o2[2], o2[3]);
;     *(float4*)(d + 3 * 1024) = make_float4(o3[0], o3[1], o3[2], o3[3]);
;     *(float4*)(d + 4 * 1024) = make_float4(o4[0], o4[1], o4[2], o4[3]);
;     *(float4*)(d + 5 * 1024) = make_float4(o5[0], o5[1], o5[2], o5[3]);
;     if (skq == 0) *(float2*)(bufp + 6 * 1024 + sj * 2) = make_float2(P.psc[1], P.psc[2]);
;   };
;     ...
;     stage(PA, sm);
	v_fmac_f32_e32 v126, v102, v154
	s_waitcnt vmcnt(16)
	v_mul_f32 v138, v82, v84
	v_mul_f32 v139, v82, v85
	v_mul_f32 v142, v82, v78
	v_mul_f32 v143, v82, v79
	v_fmac_f32_e32 v126, v96, v155
	v_xor_b32_e32 v85, 0x80000000, v139
	v_xor_b32_e32 v84, 0x80000000, v138
	v_xor_b32_e32 v87, 0x80000000, v143
	v_xor_b32_e32 v86, 0x80000000, v142
	ds_write_b32 v122, v126 offset:50432
	ds_write_b128 v103, v[84:87]
	v_lshlrev_b32_e32 v84, 16, v74
	v_and_b32_e32 v85, 0xffff0000, v76
	v_lshlrev_b32_e32 v80, 16, v76
	v_and_b32_e32 v81, 0xffff0000, v74
	v_mul_f32 v84, v95, v84
	v_mul_f32 v85, v94, v85
	v_lshlrev_b32_e32 v126, 16, v88
	v_and_b32_e32 v127, 0xffff0000, v88
	v_fma_f32 v80, v94, v80, v84
	v_fma_f32 v81, v95, v81, v85
	v_lshlrev_b32_e32 v134, 16, v92
	v_and_b32_e32 v135, 0xffff0000, v92
	v_sub_f32 v80, v80, v126
	v_sub_f32 v81, v81, v127
	v_lshlrev_b32_e32 v92, 16, v93
	v_and_b32_e32 v93, 0xffff0000, v93
	v_sub_f32 v78, 1.0, v134
	v_sub_f32 v79, 1.0, v135
	v_fma_f32 v80, v0, v80, v126
	v_fma_f32 v81, v1, v81, v127
	v_and_b32_e32 v87, 0xffff0000, v75
	v_mul_f32 v84, v80, v78
	v_mul_f32 v85, v81, v79
	v_sub_f32 v80, 1.0, v92
	v_sub_f32 v81, 1.0, v93
	v_lshlrev_b32_e32 v93, 16, v75
	v_and_b32_e32 v75, s0, v75
	v_and_b32_e32 v74, 0xffff0000, v77
	v_pk_mov_b32 v[74:75], v[92:93], v[74:75] op_sel:[1,0]
	v_lshlrev_b32_e32 v86, 16, v77
	v_mul_f32 v74, v95, v74
	v_mul_f32 v75, v94, v75
	v_lshlrev_b32_e32 v88, 16, v89
	v_and_b32_e32 v89, 0xffff0000, v89
	v_fma_f32 v74, v94, v86, v74
	v_fma_f32 v75, v95, v87, v75
	v_lshlrev_b32_e32 v136, 16, v90
	v_sub_f32 v74, v74, v88
	v_sub_f32 v75, v75, v89
	v_and_b32_e32 v137, 0xffff0000, v90
	v_lshlrev_b32_e32 v90, 16, v91
	v_and_b32_e32 v91, 0xffff0000, v91
	v_fma_f32 v74, v2, v74, v88
	v_fma_f32 v75, v3, v75, v89
	v_mul_f32 v76, v142, v90
	v_mul_f32 v77, v143, v91
	v_mul_f32 v86, v74, v80
	v_mul_f32 v87, v75, v81
	v_mul_f32 v74, v138, v136
	v_mul_f32 v75, v139, v137
	ds_write_b128 v103, v[84:87] offset:4096
	ds_write_b128 v103, v[78:81] offset:8192
	ds_write_b128 v103, v[74:77] offset:12288
	v_add_f32 v74, v136, -1.0
	v_add_f32 v75, v137, -1.0
	v_add_f32 v76, v90, -1.0
	v_add_f32 v77, v91, -1.0
	v_fma_f32 v74, v16, v74, 1.0
	v_fma_f32 v75, v17, v75, 1.0
	v_fma_f32 v76, v18, v76, 1.0
	v_fma_f32 v77, v19, v77, 1.0
	v_mul_f32 v74, v128, v74
	v_mul_f32 v75, v129, v75
	v_mul_f32 v76, v140, v76
	v_mul_f32 v77, v141, v77
	ds_write_b128 v103, v[74:77] offset:16384
	v_lshlrev_b32_e32 v76, 16, v70
	v_and_b32_e32 v77, 0xffff0000, v72
	v_lshlrev_b32_e32 v74, 16, v72
	v_and_b32_e32 v75, 0xffff0000, v70
	v_mul_f32 v76, v95, v76
	v_mul_f32 v77, v94, v77
	v_fma_f32 v74, v94, v74, v76
	v_fma_f32 v75, v95, v75, v77
	v_and_b32_e32 v77, 0xffff0000, v71
	v_lshlrev_b32_e32 v79, 16, v71
	v_and_b32_e32 v71, s0, v71
	v_and_b32_e32 v70, 0xffff0000, v73
	v_pk_mov_b32 v[70:71], v[78:79], v[70:71] op_sel:[1,0]
	v_lshlrev_b32_e32 v76, 16, v73
	v_mul_f32 v70, v95, v70
	v_mul_f32 v71, v94, v71
	v_fma_f32 v70, v94, v76, v70
	v_fma_f32 v71, v95, v77, v71
	v_sub_f32 v74, v74, v130
	v_sub_f32 v75, v75, v131
	v_sub_f32 v70, v70, v132
	v_sub_f32 v71, v71, v133
	v_fma_f32 v74, v4, v74, v130
	v_fma_f32 v75, v5, v75, v131
	v_fma_f32 v76, v6, v70, v132
	v_fma_f32 v77, v7, v71, v133
	ds_write_b128 v103, v[74:77] offset:20480
	s_and_saveexec_b64 s[4:5], s[40:41]
	s_cbranch_execz .LBB0_553
	s_waitcnt vmcnt(15)
	ds_write_b64 v104, v[68:69] offset:24576
	s_branch .LBB0_553

; #define TIDX ltid()
; DI void gemm_128_2set(const bf16_t* __restrict__ A, int lda, const bf16_t* __restrict__ B, int ldb, int K, f32x16 (&acc)[2][2], bf16_t* sA, bf16_t* sB) {
;   const int tid = TIDX, lane = tid & 63, wid = tid >> 6, wm = wid >> 1, wn = wid & 1, r = lane & 31, h = lane >> 5;
;   const int lrow = tid >> 3, lkc = (tid & 7) * 8;
;   const bf16_t* ga = A + (size_t)lrow * lda + lkc;
;   const bf16_t* gb = B + (size_t)lrow * ldb + lkc;
;   uint4 pa0, pa1, pa2, pa3, pb0, pb1, pb2, pb3, qa0, qa1, qa2, qa3, qb0, qb1, qb2, qb3;
;     ...
;   GL2_P(0)
;   GL2_Q(64)
; DI void phase_merge(CP p, const Ptrs& w, int l, bf16_t* sA, bf16_t* sB, unsigned* sU) {
;     ...
;     for (int br = 0; br < 4; ++br) {
;       const bf16_t* ys; int lds_;
;       if (br == 0) { ys = w.pA; lds_ = SPA; } else if (br == 1) { ys = w.pB + 1792; lds_ = SPB; } else if (br == 2) { ys = w.pC + 1040; lds_ = SPC; } else { ys = w.pD; lds_ = SPD; }
;       {
;         f32x16 U[2][2];
;         zero_acc(U);
;         gemm_128_2set(ys + (size_t)m0 * lds_, lds_, up_t + (size_t)(br * 2048 + n0) * 512, 512, 512, U, sA, sB);
.LBB0_880:
	s_mul_i32 s52, s54, s39
	s_mul_hi_u32 s53, s54, s38
	s_add_i32 s52, s53, s52
	s_mul_i32 s53, s55, s38
	s_ashr_i32 s51, s50, 31
	s_add_i32 s53, s52, s53
	s_mul_i32 s52, s54, s38
	s_lshl_b64 s[58:59], s[50:51], 10
	s_lshl_b64 s[52:53], s[52:53], 1
	s_add_u32 s76, s56, s52
	s_waitcnt vmcnt(3)
	v_mov_b32_e32 v16, v214
	s_addc_u32 s77, s57, s53
	s_lshl_b32 s52, s73, 11
	s_add_i32 s52, s52, s72
	v_ashrrev_i32_e32 v0, 3, v16
	v_lshlrev_b32_e32 v1, 3, v16
	v_and_b32_e32 v4, 56, v1
	v_ashrrev_i32_e32 v1, 31, v0
	s_ashr_i32 s53, s52, 31
	v_mul_lo_u32 v5, s54, v1
	v_mul_lo_u32 v6, s55, v0
	v_mad_u64_u32 v[2:3], vcc, s54, v0, 0
	s_lshl_b64 s[78:79], s[52:53], 10
	v_add3_u32 v3, v3, v5, v6
	s_add_u32 s78, s65, s78
	v_lshl_add_u64 v[130:131], v[2:3], 1, s[76:77]
	v_lshlrev_b32_e32 v156, 1, v4
	s_addc_u32 s79, s66, s79
	v_lshl_add_u64 v[2:3], v[130:131], 0, v[156:157]
	v_lshlrev_b64 v[4:5], 10, v[0:1]
	s_lshl_b64 s[76:77], s[54:55], 6
	v_lshl_add_u64 v[6:7], s[78:79], 0, v[4:5]
	v_lshl_add_u64 v[8:9], v[2:3], 0, s[76:77]
	v_lshl_add_u64 v[6:7], v[6:7], 0, v[156:157]
	v_lshl_add_u64 v[10:11], v[8:9], 0, s[76:77]
	s_lshl_b64 s[78:79], s[54:55], 7
	global_load_dwordx4 v[96:99], v[8:9], off
	global_load_dwordx4 v[100:103], v[10:11], off
	v_lshl_add_u64 v[8:9], v[10:11], 0, s[76:77]
	v_add_co_u32_e32 v10, vcc, s35, v6
	s_sub_u32 s78, 0, s78
	s_nop 0
	v_addc_co_u32_e32 v11, vcc, 0, v7, vcc
	s_subb_u32 s79, 0, s79
	global_load_dwordx4 v[104:107], v[8:9], off
	v_add_co_u32_e32 v12, vcc, s36, v6
	global_load_dwordx4 v[108:111], v[2:3], off
	global_load_dwordx4 v[64:67], v[2:3], off offset:128
	v_lshl_add_u64 v[2:3], v[8:9], 0, s[78:79]
	v_addc_co_u32_e32 v13, vcc, 0, v7, vcc
	v_lshl_add_u64 v[8:9], v[2:3], 0, s[76:77]
	v_add_co_u32_e32 v14, vcc, s23, v6
	global_load_dwordx4 v[68:71], v[2:3], off offset:128
	global_load_dwordx4 v[72:75], v[8:9], off offset:128
	v_lshl_add_u64 v[2:3], v[8:9], 0, s[76:77]
	v_addc_co_u32_e32 v15, vcc, 0, v7, vcc
	global_load_dwordx4 v[80:83], v[2:3], off offset:128
	global_load_dwordx4 v[112:115], v[6:7], off
	global_load_dwordx4 v[76:79], v[6:7], off offset:128
	global_load_dwordx4 v[116:119], v[10:11], off
	global_load_dwordx4 v[84:87], v[10:11], off offset:128
	global_load_dwordx4 v[120:123], v[12:13], off
	global_load_dwordx4 v[88:91], v[12:13], off offset:128
	global_load_dwordx4 v[124:127], v[14:15], off
	global_load_dwordx4 v[92:95], v[14:15], off offset:128
	v_mul_lo_u32 v2, v0, s88
	v_and_b32_e32 v17, 31, v16
	v_lshl_add_u32 v184, v2, 1, v156
	v_lshrrev_b32_e32 v2, 1, v16
	v_and_or_b32 v3, v2, s82, v17
	v_and_b32_e32 v2, 16, v2
	v_mad_u64_u32 v[128:129], s[76:77], v3, s81, v[2:3]
	v_and_b32_e32 v3, 0x5f, v16
	s_add_u32 s58, s2, s58
	v_mad_u32_u24 v129, v3, s81, v2
	v_and_b32_e32 v2, 7, v16
	s_addc_u32 s59, s3, s59
	v_lshlrev_b64 v[0:1], 1, v[0:1]
	v_lshlrev_b32_e32 v156, 4, v2
	v_lshl_add_u64 v[132:133], s[58:59], 0, v[4:5]
	v_lshl_add_u64 v[2:3], s[44:45], 0, v[0:1]
	v_mov_b64_e32 v[4:5], s[56:57]
	v_mul_lo_u32 v3, s54, v3
	v_mul_lo_u32 v6, s55, v2
	v_mad_u64_u32 v[134:135], s[56:57], s54, v2, v[4:5]
	v_add3_u32 v135, v6, v135, v3
	v_lshl_add_u64 v[2:3], s[46:47], 0, v[0:1]
	v_lshl_add_u64 v[0:1], s[42:43], 0, v[0:1]
	v_mul_lo_u32 v3, s54, v3
	v_mul_lo_u32 v6, s55, v2
	v_mad_u64_u32 v[136:137], s[56:57], s54, v2, v[4:5]
	v_mul_lo_u32 v1, s54, v1
	v_mul_lo_u32 v2, s55, v0
	v_mad_u64_u32 v[138:139], s[54:55], s54, v0, v[4:5]
	v_mov_b32_e32 v0, 0
	v_add3_u32 v137, v6, v137, v3
	v_add3_u32 v139, v2, v139, v1
	s_movk_i32 s54, 0xff80
	v_mov_b32_e32 v1, v0
	v_mov_b32_e32 v2, v0
	v_mov_b32_e32 v3, v0
	v_mov_b32_e32 v4, v0
	v_mov_b32_e32 v5, v0
	v_mov_b32_e32 v6, v0
	v_mov_b32_e32 v7, v0
	v_mov_b32_e32 v8, v0
	v_mov_b32_e32 v9, v0
	v_mov_b32_e32 v10, v0
	v_mov_b32_e32 v11, v0
	v_mov_b32_e32 v12, v0
	v_mov_b32_e32 v13, v0
	v_mov_b32_e32 v14, v0
	v_mov_b32_e32 v15, v0
	v_mov_b32_e32 v16, v0
	v_mov_b32_e32 v17, v0
	v_mov_b32_e32 v18, v0
	v_mov_b32_e32 v19, v0
	s_waitcnt vmcnt(18)
	v_mov_b32_e32 v20, v0
	v_mov_b32_e32 v21, v0
	v_mov_b32_e32 v22, v0
	v_mov_b32_e32 v23, v0
	s_waitcnt vmcnt(17)
	v_mov_b32_e32 v24, v0
	v_mov_b32_e32 v25, v0
	v_mov_b32_e32 v26, v0
	v_mov_b32_e32 v27, v0
	s_waitcnt vmcnt(16)
	v_mov_b32_e32 v28, v0
	v_mov_b32_e32 v29, v0
	v_mov_b32_e32 v30, v0
	v_mov_b32_e32 v31, v0
	v_mov_b32_e32 v32, v0
	v_mov_b32_e32 v33, v0
	v_mov_b32_e32 v34, v0
	v_mov_b32_e32 v35, v0
	v_mov_b32_e32 v36, v0
	v_mov_b32_e32 v37, v0
	v_mov_b32_e32 v38, v0
	v_mov_b32_e32 v39, v0
	v_mov_b32_e32 v40, v0
	v_mov_b32_e32 v41, v0
	v_mov_b32_e32 v42, v0
	v_mov_b32_e32 v43, v0
	v_mov_b32_e32 v44, v0
	v_mov_b32_e32 v45, v0
	v_mov_b32_e32 v46, v0
	v_mov_b32_e32 v47, v0
	v_mov_b32_e32 v48, v0
	v_mov_b32_e32 v49, v0
	v_mov_b32_e32 v50, v0
	v_mov_b32_e32 v51, v0
	v_mov_b32_e32 v52, v0
	v_mov_b32_e32 v53, v0
	v_mov_b32_e32 v54, v0
	v_mov_b32_e32 v55, v0
	v_mov_b32_e32 v56, v0
	v_mov_b32_e32 v57, v0
	v_mov_b32_e32 v58, v0
	v_mov_b32_e32 v59, v0
	v_mov_b32_e32 v60, v0
	v_mov_b32_e32 v61, v0
	v_mov_b32_e32 v62, v0
	v_mov_b32_e32 v63, v0
	s_waitcnt vmcnt(1)
; DI void gemm_128_2set(const bf16_t* __restrict__ A, int lda, const bf16_t* __restrict__ B, int ldb, int K, f32x16 (&acc)[2][2], bf16_t* sA, bf16_t* sB) {
;     ...
;   for (int k0 = 0; k0 < K - 128; k0 += 128) {
;     __syncthreads();
;     ST2(pa0, pa1, pa2, pa3, pb0, pb1, pb2, pb3)
;     __syncthreads();
;     GL2_P(k0 + 128)
;     MMA2()
;     __syncthreads();
;     ST2(qa0, qa1, qa2, qa3, qb0, qb1, qb2, qb3)
;     __syncthreads();
;     GL2_Q(k0 + 192)
;     MMA2()
;   }
.LBB0_881:
	s_barrier
	s_waitcnt vmcnt(12)
	ds_write_b128 v184, v[108:111]
	ds_write_b128 v184, v[96:99] offset:4608
	ds_write_b128 v184, v[100:103] offset:9216
	ds_write_b128 v184, v[104:107] offset:13824
	s_waitcnt vmcnt(11)
	ds_write_b128 v184, v[112:115] offset:18432
	s_waitcnt vmcnt(10)
	ds_write_b128 v184, v[116:119] offset:23040
	s_waitcnt vmcnt(9)
	ds_write_b128 v184, v[120:123] offset:27648
	s_waitcnt vmcnt(8)
	ds_write_b128 v184, v[124:127] offset:32256
	s_waitcnt lgkmcnt(0)
	s_barrier
	ds_read_b128 v[96:99], v128
	ds_read_b128 v[100:103], v129 offset:18432
	ds_read_b128 v[104:107], v128 offset:32
	ds_read_b128 v[108:111], v129 offset:18464
	ds_read_b128 v[112:115], v129 offset:23040
	ds_read_b128 v[116:119], v129 offset:23072
	s_waitcnt lgkmcnt(4)
	v_mfma_f32_32x32x16_bf16 v[48:63], v[96:99], v[100:103], v[48:63]
	s_mov_b32 s55, 0x19864000
	v_lshl_add_u64 v[202:203], v[130:131], 0, v[156:157]
	v_lshl_add_u64 v[204:205], v[138:139], 0, v[156:157]
	v_lshl_add_u64 v[206:207], v[134:135], 0, v[156:157]
	v_lshl_add_u64 v[208:209], v[136:137], 0, v[156:157]
	s_addk_i32 s54, 0x80
	v_lshl_add_u64 v[130:131], v[130:131], 0, s[94:95]
	s_waitcnt lgkmcnt(1)
	v_mfma_f32_32x32x16_bf16 v[32:47], v[96:99], v[112:115], v[32:47]
	ds_read_b128 v[96:99], v128 offset:4608
	ds_read_b128 v[120:123], v128 offset:4640
	v_lshl_add_u64 v[134:135], v[134:135], 0, s[94:95]
	v_lshl_add_u64 v[136:137], v[136:137], 0, s[94:95]
	s_cmpk_lt_u32 s54, 0x100
	v_lshl_add_u64 v[138:139], v[138:139], 0, s[94:95]
	s_waitcnt lgkmcnt(1)
	v_mfma_f32_32x32x16_bf16 v[16:31], v[96:99], v[100:103], v[16:31]
	v_mfma_f32_32x32x16_bf16 v[0:15], v[96:99], v[112:115], v[0:15]
	ds_read_b128 v[96:99], v128 offset:64
	ds_read_b128 v[100:103], v129 offset:18496
	ds_read_b128 v[186:189], v128 offset:96
	ds_read_b128 v[190:193], v129 offset:18528
	v_mfma_f32_32x32x16_bf16 v[48:63], v[104:107], v[108:111], v[48:63]
	v_mfma_f32_32x32x16_bf16 v[32:47], v[104:107], v[116:119], v[32:47]
	s_waitcnt lgkmcnt(4)
	v_mfma_f32_32x32x16_bf16 v[16:31], v[120:123], v[108:111], v[16:31]
	v_mfma_f32_32x32x16_bf16 v[0:15], v[120:123], v[116:119], v[0:15]
	ds_read_b128 v[112:115], v129 offset:23104
	ds_read_b128 v[116:119], v128 offset:4672
	ds_read_b128 v[194:197], v129 offset:23136
	ds_read_b128 v[198:201], v128 offset:4704
	v_lshl_add_u64 v[120:121], v[132:133], 0, v[156:157]
	v_add_co_u32_e32 v210, vcc, s55, v120
	s_mov_b32 s55, 0x1986c000
	s_nop 0
	v_addc_co_u32_e32 v211, vcc, 0, v121, vcc
	s_waitcnt lgkmcnt(6)
	v_mfma_f32_32x32x16_bf16 v[48:63], v[96:99], v[100:103], v[48:63]
	v_add_co_u32_e32 v212, vcc, s55, v120
	s_mov_b32 s55, 0x19874000
	s_nop 0
	v_addc_co_u32_e32 v213, vcc, 0, v121, vcc
	v_add_co_u32_e32 v226, vcc, s55, v120
	s_waitcnt lgkmcnt(3)
	v_mfma_f32_32x32x16_bf16 v[32:47], v[96:99], v[112:115], v[32:47]
	v_addc_co_u32_e32 v227, vcc, 0, v121, vcc
	s_mov_b32 s55, 0x1987c000
	v_add_co_u32_e32 v238, vcc, s55, v120
	global_load_dwordx4 v[108:111], v[202:203], off offset:256
	s_nop 0
	v_addc_co_u32_e32 v239, vcc, 0, v121, vcc
	s_waitcnt lgkmcnt(2)
	v_mfma_f32_32x32x16_bf16 v[16:31], v[116:119], v[100:103], v[16:31]
	global_load_dwordx4 v[96:99], v[204:205], off offset:256
	global_load_dwordx4 v[100:103], v[206:207], off offset:256
	global_load_dwordx4 v[104:107], v[208:209], off offset:256
	v_lshl_add_u64 v[132:133], v[132:133], 0, s[94:95]
	v_mfma_f32_32x32x16_bf16 v[0:15], v[116:119], v[112:115], v[0:15]
	global_load_dwordx4 v[112:115], v[210:211], off offset:2048
	global_load_dwordx4 v[116:119], v[212:213], off offset:2048
	global_load_dwordx4 v[120:123], v[226:227], off offset:2048
	global_load_dwordx4 v[124:127], v[238:239], off offset:2048
	s_waitcnt lgkmcnt(0)
	s_barrier
	s_waitcnt vmcnt(15)
	ds_write_b128 v184, v[64:67]
	s_waitcnt vmcnt(14)
	ds_write_b128 v184, v[68:71] offset:4608
	s_waitcnt vmcnt(13)
	ds_write_b128 v184, v[72:75] offset:9216
	s_waitcnt vmcnt(12)
	ds_write_b128 v184, v[80:83] offset:13824
	s_waitcnt vmcnt(11)
	ds_write_b128 v184, v[76:79] offset:18432
	s_waitcnt vmcnt(10)
	ds_write_b128 v184, v[84:87] offset:23040
	s_waitcnt vmcnt(9)
	ds_write_b128 v184, v[88:91] offset:27648
	s_waitcnt vmcnt(8)
	ds_write_b128 v184, v[92:95] offset:32256
	s_waitcnt lgkmcnt(0)
	v_mfma_f32_32x32x16_bf16 v[48:63], v[186:189], v[190:193], v[48:63]
	s_barrier
	ds_read_b128 v[64:67], v128
	ds_read_b128 v[68:71], v129 offset:18432
	ds_read_b128 v[72:75], v128 offset:32
	ds_read_b128 v[76:79], v129 offset:18464
	ds_read_b128 v[80:83], v129 offset:23040
	ds_read_b128 v[84:87], v129 offset:23072
	v_mfma_f32_32x32x16_bf16 v[32:47], v[186:189], v[194:197], v[32:47]
	v_mfma_f32_32x32x16_bf16 v[16:31], v[198:201], v[190:193], v[16:31]
	v_mfma_f32_32x32x16_bf16 v[0:15], v[198:201], v[194:197], v[0:15]
	s_waitcnt lgkmcnt(4)
	v_mfma_f32_32x32x16_bf16 v[48:63], v[64:67], v[68:71], v[48:63]
	s_waitcnt lgkmcnt(1)
	v_mfma_f32_32x32x16_bf16 v[32:47], v[64:67], v[80:83], v[32:47]
	ds_read_b128 v[64:67], v128 offset:4608
	ds_read_b128 v[88:91], v128 offset:4640
	s_waitcnt lgkmcnt(1)
	v_mfma_f32_32x32x16_bf16 v[16:31], v[64:67], v[68:71], v[16:31]
	v_mfma_f32_32x32x16_bf16 v[0:15], v[64:67], v[80:83], v[0:15]
	v_mfma_f32_32x32x16_bf16 v[48:63], v[72:75], v[76:79], v[48:63]
	v_mfma_f32_32x32x16_bf16 v[32:47], v[72:75], v[84:87], v[32:47]
	ds_read_b128 v[64:67], v128 offset:64
	ds_read_b128 v[68:71], v129 offset:18496
	ds_read_b128 v[72:75], v128 offset:96
	ds_read_b128 v[92:95], v129 offset:18528
	s_waitcnt lgkmcnt(4)
	v_mfma_f32_32x32x16_bf16 v[16:31], v[88:91], v[76:79], v[16:31]
	ds_read_b128 v[76:79], v129 offset:23104
	ds_read_b128 v[186:189], v129 offset:23136
	v_mfma_f32_32x32x16_bf16 v[0:15], v[88:91], v[84:87], v[0:15]
	s_waitcnt lgkmcnt(4)
	v_mfma_f32_32x32x16_bf16 v[48:63], v[64:67], v[68:71], v[48:63]
	s_waitcnt lgkmcnt(1)
	v_mfma_f32_32x32x16_bf16 v[32:47], v[64:67], v[76:79], v[32:47]
	ds_read_b128 v[64:67], v128 offset:4672
	ds_read_b128 v[190:193], v128 offset:4704
	s_waitcnt lgkmcnt(1)
	v_mfma_f32_32x32x16_bf16 v[16:31], v[64:67], v[68:71], v[16:31]
	v_mfma_f32_32x32x16_bf16 v[0:15], v[64:67], v[76:79], v[0:15]
	v_mfma_f32_32x32x16_bf16 v[48:63], v[72:75], v[92:95], v[48:63]
	v_mfma_f32_32x32x16_bf16 v[32:47], v[72:75], v[186:189], v[32:47]
	global_load_dwordx4 v[64:67], v[202:203], off offset:384
	global_load_dwordx4 v[68:71], v[204:205], off offset:384
	global_load_dwordx4 v[72:75], v[206:207], off offset:384
	global_load_dwordx4 v[80:83], v[208:209], off offset:384
	global_load_dwordx4 v[76:79], v[210:211], off offset:2176
	global_load_dwordx4 v[84:87], v[212:213], off offset:2176
	global_load_dwordx4 v[88:91], v[226:227], off offset:2176
	s_waitcnt lgkmcnt(0)
	v_mfma_f32_32x32x16_bf16 v[16:31], v[190:193], v[92:95], v[16:31]
	global_load_dwordx4 v[92:95], v[238:239], off offset:2176
	v_mfma_f32_32x32x16_bf16 v[0:15], v[190:193], v[186:189], v[0:15]
	s_cbranch_scc1 .LBB0_881
; DI void gemm_128_2set(const bf16_t* __restrict__ A, int lda, const bf16_t* __restrict__ B, int ldb, int K, f32x16 (&acc)[2][2], bf16_t* sA, bf16_t* sB) {
;     ...
;   __syncthreads();
;   ST2(pa0, pa1, pa2, pa3, pb0, pb1, pb2, pb3)
;   __syncthreads();
;   MMA2()
;   __syncthreads();
;   ST2(qa0, qa1, qa2, qa3, qb0, qb1, qb2, qb3)
;   __syncthreads();
;   MMA2()
	s_barrier
	s_waitcnt vmcnt(15)
	ds_write_b128 v184, v[108:111]
	s_waitcnt vmcnt(14)
	ds_write_b128 v184, v[96:99] offset:4608
	s_waitcnt vmcnt(13)
	ds_write_b128 v184, v[100:103] offset:9216
	s_waitcnt vmcnt(12)
	ds_write_b128 v184, v[104:107] offset:13824
	s_waitcnt vmcnt(11)
	ds_write_b128 v184, v[112:115] offset:18432
	s_waitcnt vmcnt(10)
	ds_write_b128 v184, v[116:119] offset:23040
	s_waitcnt vmcnt(9)
	ds_write_b128 v184, v[120:123] offset:27648
	s_waitcnt vmcnt(8)
	ds_write_b128 v184, v[124:127] offset:32256
	s_waitcnt lgkmcnt(0)
	s_barrier
	ds_read_b128 v[96:99], v128
	ds_read_b128 v[100:103], v129 offset:18432
	ds_read_b128 v[104:107], v128 offset:32
	ds_read_b128 v[108:111], v129 offset:18464
	ds_read_b128 v[112:115], v129 offset:23040
	ds_read_b128 v[116:119], v129 offset:23072
	s_waitcnt lgkmcnt(4)
	v_mfma_f32_32x32x16_bf16 v[48:63], v[96:99], v[100:103], v[48:63]
	s_lshl_b64 s[54:55], s[50:51], 12
	s_lshl_b64 s[52:53], s[52:53], 12
	s_add_u32 s52, s63, s52
	s_addc_u32 s53, s64, s53
	s_movk_i32 s51, 0xff80
	s_waitcnt lgkmcnt(1)
	v_mfma_f32_32x32x16_bf16 v[32:47], v[96:99], v[112:115], v[32:47]
	ds_read_b128 v[96:99], v128 offset:4608
	ds_read_b128 v[120:123], v128 offset:4640
	s_waitcnt lgkmcnt(1)
	v_mfma_f32_32x32x16_bf16 v[16:31], v[96:99], v[100:103], v[16:31]
	v_mfma_f32_32x32x16_bf16 v[0:15], v[96:99], v[112:115], v[0:15]
	v_mfma_f32_32x32x16_bf16 v[48:63], v[104:107], v[108:111], v[48:63]
	v_mfma_f32_32x32x16_bf16 v[32:47], v[104:107], v[116:119], v[32:47]
	s_waitcnt lgkmcnt(0)
	v_mfma_f32_32x32x16_bf16 v[16:31], v[120:123], v[108:111], v[16:31]
	ds_read_b128 v[96:99], v128 offset:64
	ds_read_b128 v[100:103], v129 offset:18496
	ds_read_b128 v[104:107], v128 offset:96
	ds_read_b128 v[108:111], v129 offset:18528
	v_mfma_f32_32x32x16_bf16 v[0:15], v[120:123], v[116:119], v[0:15]
	ds_read_b128 v[112:115], v129 offset:23104
	ds_read_b128 v[116:119], v129 offset:23136
	s_waitcnt lgkmcnt(4)
	v_mfma_f32_32x32x16_bf16 v[48:63], v[96:99], v[100:103], v[48:63]
	s_waitcnt lgkmcnt(1)
	v_mfma_f32_32x32x16_bf16 v[32:47], v[96:99], v[112:115], v[32:47]
	ds_read_b128 v[96:99], v128 offset:4672
	ds_read_b128 v[120:123], v128 offset:4704
	s_waitcnt lgkmcnt(0)
	s_barrier
	s_waitcnt vmcnt(7)
	ds_write_b128 v184, v[64:67]
	s_waitcnt vmcnt(6)
	ds_write_b128 v184, v[68:71] offset:4608
	s_waitcnt vmcnt(5)
	ds_write_b128 v184, v[72:75] offset:9216
	s_waitcnt vmcnt(4)
	ds_write_b128 v184, v[80:83] offset:13824
	s_waitcnt vmcnt(3)
	ds_write_b128 v184, v[76:79] offset:18432
	s_waitcnt vmcnt(2)
	ds_write_b128 v184, v[84:87] offset:23040
	s_waitcnt vmcnt(1)
	ds_write_b128 v184, v[88:91] offset:27648
	s_waitcnt vmcnt(0)
	ds_write_b128 v184, v[92:95] offset:32256
	s_waitcnt lgkmcnt(0)
	v_mfma_f32_32x32x16_bf16 v[16:31], v[96:99], v[100:103], v[16:31]
	s_barrier
	ds_read_b128 v[64:67], v128
	ds_read_b128 v[68:71], v129 offset:18432
	ds_read_b128 v[72:75], v128 offset:32
	ds_read_b128 v[76:79], v129 offset:18464
	ds_read_b128 v[80:83], v129 offset:23040
	ds_read_b128 v[84:87], v129 offset:23072
	v_mfma_f32_32x32x16_bf16 v[0:15], v[96:99], v[112:115], v[0:15]
	v_mfma_f32_32x32x16_bf16 v[48:63], v[104:107], v[108:111], v[48:63]
	v_mfma_f32_32x32x16_bf16 v[32:47], v[104:107], v[116:119], v[32:47]
	v_mfma_f32_32x32x16_bf16 v[16:31], v[120:123], v[108:111], v[16:31]
	v_mfma_f32_32x32x16_bf16 v[0:15], v[120:123], v[116:119], v[0:15]
	s_waitcnt lgkmcnt(4)
	v_mfma_f32_32x32x16_bf16 v[48:63], v[64:67], v[68:71], v[48:63]
	s_waitcnt lgkmcnt(1)
	v_mfma_f32_32x32x16_bf16 v[32:47], v[64:67], v[80:83], v[32:47]
	ds_read_b128 v[64:67], v128 offset:4608
	ds_read_b128 v[88:91], v128 offset:4640
	s_waitcnt lgkmcnt(1)
	v_mfma_f32_32x32x16_bf16 v[16:31], v[64:67], v[68:71], v[16:31]
	v_mfma_f32_32x32x16_bf16 v[0:15], v[64:67], v[80:83], v[0:15]
	v_mfma_f32_32x32x16_bf16 v[48:63], v[72:75], v[76:79], v[48:63]
	v_mfma_f32_32x32x16_bf16 v[32:47], v[72:75], v[84:87], v[32:47]
	s_waitcnt lgkmcnt(0)
	v_mfma_f32_32x32x16_bf16 v[16:31], v[88:91], v[76:79], v[16:31]
	ds_read_b128 v[64:67], v128 offset:64
	ds_read_b128 v[68:71], v129 offset:18496
	ds_read_b128 v[72:75], v128 offset:96
	ds_read_b128 v[76:79], v129 offset:18528
	v_mfma_f32_32x32x16_bf16 v[0:15], v[88:91], v[84:87], v[0:15]
	ds_read_b128 v[80:83], v129 offset:23104
	ds_read_b128 v[84:87], v128 offset:4672
	ds_read_b128 v[88:91], v128 offset:4704
	ds_read_b128 v[92:95], v129 offset:23136
	s_waitcnt lgkmcnt(6)
	v_mfma_f32_32x32x16_bf16 v[48:63], v[64:67], v[68:71], v[48:63]
	s_waitcnt lgkmcnt(3)
	v_mfma_f32_32x32x16_bf16 v[32:47], v[64:67], v[80:83], v[32:47]
	s_waitcnt lgkmcnt(2)
	v_mfma_f32_32x32x16_bf16 v[16:31], v[84:87], v[68:71], v[16:31]
	v_mfma_f32_32x32x16_bf16 v[0:15], v[84:87], v[80:83], v[0:15]
	v_mfma_f32_32x32x16_bf16 v[48:63], v[72:75], v[76:79], v[48:63]
	s_waitcnt lgkmcnt(0)
; #define TIDX ltid()
; DI void gemm_128_2set(const bf16_t* __restrict__ A, int lda, const bf16_t* __restrict__ B, int ldb, int K, f32x16 (&acc)[2][2], bf16_t* sA, bf16_t* sB) {
;   const int tid = TIDX, lane = tid & 63, wid = tid >> 6, wm = wid >> 1, wn = wid & 1, r = lane & 31, h = lane >> 5;
;   const int lrow = tid >> 3, lkc = (tid & 7) * 8;
;   const bf16_t* ga = A + (size_t)lrow * lda + lkc;
;   const bf16_t* gb = B + (size_t)lrow * ldb + lkc;
;   uint4 pa0, pa1, pa2, pa3, pb0, pb1, pb2, pb3, qa0, qa1, qa2, qa3, qb0, qb1, qb2, qb3;
;     ...
;   GL2_P(0)
;   GL2_Q(64)
; DI void phase_merge(CP p, const Ptrs& w, int l, bf16_t* sA, bf16_t* sB, unsigned* sU) {
;     ...
; #pragma unroll
;         for (int a = 0; a < 2; ++a)
; #pragma unroll
;           for (int c = 0; c < 2; ++c)
; #pragma unroll
;             for (int i = 0; i < 8; ++i) sU[((a * 2 + c) * 8 + i) * 256 + tid] = pack2(U[a][c][2 * i], U[a][c][2 * i + 1]);
;       }
;       f32x16 G[2][2];
;       zero_acc(G);
;       gemm_128_2set(w.H + (size_t)m0 * 2048, 2048, gate_t + (size_t)(br * 2048 + n0) * 2048, 2048, 2048, G, sA, sB);
	v_mfma_f32_32x32x16_bf16 v[32:47], v[72:75], v[92:95], v[32:47]
	s_nop 9
	v_cvt_pk_bf16_f32 v48, v48, v49
	v_cvt_pk_bf16_f32 v49, v50, v51
	ds_write2st64_b32 v140, v48, v49 offset0:144 offset1:148
	v_cvt_pk_bf16_f32 v48, v52, v53
	v_cvt_pk_bf16_f32 v49, v54, v55
	ds_write2st64_b32 v140, v48, v49 offset0:152 offset1:156
	v_cvt_pk_bf16_f32 v48, v56, v57
	v_mfma_f32_32x32x16_bf16 v[16:31], v[88:91], v[76:79], v[16:31]
	v_cvt_pk_bf16_f32 v32, v32, v33
	v_cvt_pk_bf16_f32 v33, v34, v35
	ds_write2st64_b32 v140, v32, v33 offset0:176 offset1:180
	v_cvt_pk_bf16_f32 v32, v36, v37
	v_cvt_pk_bf16_f32 v33, v38, v39
	v_cvt_pk_bf16_f32 v49, v58, v59
	ds_write2st64_b32 v140, v32, v33 offset0:184 offset1:188
	v_mfma_f32_32x32x16_bf16 v[0:15], v[88:91], v[92:95], v[0:15]
	s_nop 3
	v_cvt_pk_bf16_f32 v16, v16, v17
	v_cvt_pk_bf16_f32 v17, v18, v19
	ds_write2st64_b32 v140, v16, v17 offset0:208 offset1:212
	v_cvt_pk_bf16_f32 v16, v20, v21
	v_cvt_pk_bf16_f32 v17, v22, v23
	v_cvt_pk_bf16_f32 v32, v40, v41
	v_cvt_pk_bf16_f32 v33, v42, v43
	s_nop 0
	v_cvt_pk_bf16_f32 v0, v0, v1
	v_cvt_pk_bf16_f32 v1, v2, v3
	ds_write2st64_b32 v140, v0, v1 offset0:240 offset1:244
	v_cvt_pk_bf16_f32 v0, v4, v5
	v_cvt_pk_bf16_f32 v1, v6, v7
	ds_write2st64_b32 v140, v16, v17 offset0:216 offset1:220
	v_cvt_pk_bf16_f32 v16, v24, v25
	v_cvt_pk_bf16_f32 v17, v26, v27
	ds_write2st64_b32 v140, v0, v1 offset0:248 offset1:252
	v_cvt_pk_bf16_f32 v0, v8, v9
	v_cvt_pk_bf16_f32 v1, v10, v11
	ds_write2st64_b32 v140, v48, v49 offset0:160 offset1:164
	v_cvt_pk_bf16_f32 v48, v60, v61
	v_cvt_pk_bf16_f32 v49, v62, v63
	ds_write2st64_b32 v140, v32, v33 offset0:192 offset1:196
	v_cvt_pk_bf16_f32 v32, v44, v45
	v_cvt_pk_bf16_f32 v33, v46, v47
	ds_write2st64_b32 v140, v16, v17 offset0:224 offset1:228
	v_cvt_pk_bf16_f32 v16, v28, v29
	v_cvt_pk_bf16_f32 v17, v30, v31
	ds_write2st64_b32 v141, v0, v1 offset0:112 offset1:116
	v_cvt_pk_bf16_f32 v0, v12, v13
	v_cvt_pk_bf16_f32 v1, v14, v15
	v_mov_b32_e32 v20, v214
	ds_write2st64_b32 v140, v48, v49 offset0:168 offset1:172
	ds_write2st64_b32 v140, v32, v33 offset0:200 offset1:204
	ds_write2st64_b32 v140, v16, v17 offset0:232 offset1:236
	ds_write2st64_b32 v141, v0, v1 offset0:120 offset1:124
	s_nop 0
	v_ashrrev_i32_e32 v0, 3, v20
	v_lshlrev_b32_e32 v1, 3, v20
	v_and_b32_e32 v6, 56, v1
	v_ashrrev_i32_e32 v1, 31, v0
	v_lshlrev_b64 v[2:3], 12, v[0:1]
	v_lshl_add_u64 v[4:5], s[40:41], 0, v[2:3]
	v_lshlrev_b32_e32 v156, 1, v6
	v_lshl_add_u64 v[4:5], v[4:5], 0, v[156:157]
	v_add_co_u32_e32 v8, vcc, s75, v4
	v_lshl_add_u64 v[6:7], s[52:53], 0, v[2:3]
	s_nop 0
	v_addc_co_u32_e32 v9, vcc, 0, v5, vcc
	v_add_co_u32_e32 v10, vcc, s80, v4
	v_lshl_add_u64 v[6:7], v[6:7], 0, v[156:157]
	s_nop 0
	v_addc_co_u32_e32 v11, vcc, 0, v5, vcc
	v_add_co_u32_e32 v12, vcc, s28, v4
	v_mul_lo_u32 v0, v0, s88
	s_nop 0
	v_addc_co_u32_e32 v13, vcc, 0, v5, vcc
	v_add_co_u32_e32 v14, vcc, s75, v6
	v_and_b32_e32 v1, 31, v20
	s_nop 0
	v_addc_co_u32_e32 v15, vcc, 0, v7, vcc
	v_add_co_u32_e32 v16, vcc, s80, v6
	v_lshl_add_u32 v134, v0, 1, v156
	s_nop 0
	v_addc_co_u32_e32 v17, vcc, 0, v7, vcc
	v_add_co_u32_e32 v18, vcc, s28, v6
	v_lshrrev_b32_e32 v0, 1, v20
	s_nop 0
	v_addc_co_u32_e32 v19, vcc, 0, v7, vcc
	global_load_dwordx4 v[96:99], v[4:5], off
	global_load_dwordx4 v[80:83], v[4:5], off offset:128
	global_load_dwordx4 v[100:103], v[8:9], off
	global_load_dwordx4 v[64:67], v[8:9], off offset:128
	global_load_dwordx4 v[104:107], v[10:11], off
	global_load_dwordx4 v[68:71], v[10:11], off offset:128
	global_load_dwordx4 v[108:111], v[12:13], off
	global_load_dwordx4 v[72:75], v[12:13], off offset:128
	global_load_dwordx4 v[112:115], v[6:7], off
	global_load_dwordx4 v[76:79], v[6:7], off offset:128
	global_load_dwordx4 v[116:119], v[14:15], off
	global_load_dwordx4 v[84:87], v[14:15], off offset:128
	global_load_dwordx4 v[120:123], v[16:17], off
	global_load_dwordx4 v[88:91], v[16:17], off offset:128
	global_load_dwordx4 v[124:127], v[18:19], off
	global_load_dwordx4 v[92:95], v[18:19], off offset:128
	v_and_or_b32 v1, v0, s82, v1
	v_and_b32_e32 v0, 16, v0
	v_mad_u64_u32 v[128:129], s[52:53], v1, s81, v[0:1]
	v_and_b32_e32 v1, 0x5f, v20
	v_mad_u32_u24 v129, v1, s81, v0
	v_and_b32_e32 v0, 7, v20
	s_add_u32 s52, s2, s54
	v_lshlrev_b32_e32 v156, 4, v0
	s_addc_u32 s53, s3, s55
	v_mov_b32_e32 v0, 0
	v_lshl_add_u64 v[130:131], s[52:53], 0, v[2:3]
	v_lshl_add_u64 v[132:133], s[48:49], 0, v[2:3]
	v_mov_b32_e32 v1, v0
	v_mov_b32_e32 v2, v0
	v_mov_b32_e32 v3, v0
	v_mov_b32_e32 v4, v0
	v_mov_b32_e32 v5, v0
	v_mov_b32_e32 v6, v0
	v_mov_b32_e32 v7, v0
	v_mov_b32_e32 v8, v0
	v_mov_b32_e32 v9, v0
	v_mov_b32_e32 v10, v0
	v_mov_b32_e32 v11, v0
	v_mov_b32_e32 v12, v0
	v_mov_b32_e32 v13, v0
	v_mov_b32_e32 v14, v0
	v_mov_b32_e32 v15, v0
	v_mov_b32_e32 v16, v0
	v_mov_b32_e32 v17, v0
	v_mov_b32_e32 v18, v0
	v_mov_b32_e32 v19, v0
	v_mov_b32_e32 v20, v0
	v_mov_b32_e32 v21, v0
	v_mov_b32_e32 v22, v0
	v_mov_b32_e32 v23, v0
	v_mov_b32_e32 v24, v0
	v_mov_b32_e32 v25, v0
	v_mov_b32_e32 v26, v0
	v_mov_b32_e32 v27, v0
	v_mov_b32_e32 v28, v0
	v_mov_b32_e32 v29, v0
	v_mov_b32_e32 v30, v0
	v_mov_b32_e32 v31, v0
	v_mov_b32_e32 v32, v0
	v_mov_b32_e32 v33, v0
	v_mov_b32_e32 v34, v0
	v_mov_b32_e32 v35, v0
	v_mov_b32_e32 v36, v0
	v_mov_b32_e32 v37, v0
	v_mov_b32_e32 v38, v0
	v_mov_b32_e32 v39, v0
	v_mov_b32_e32 v40, v0
	v_mov_b32_e32 v41, v0
	v_mov_b32_e32 v42, v0
	v_mov_b32_e32 v43, v0
	v_mov_b32_e32 v44, v0
	v_mov_b32_e32 v45, v0
	v_mov_b32_e32 v46, v0
	v_mov_b32_e32 v47, v0
	v_mov_b32_e32 v48, v0
	v_mov_b32_e32 v49, v0
	v_mov_b32_e32 v50, v0
	v_mov_b32_e32 v51, v0
	v_mov_b32_e32 v52, v0
	v_mov_b32_e32 v53, v0
	v_mov_b32_e32 v54, v0
	v_mov_b32_e32 v55, v0
	v_mov_b32_e32 v56, v0
	v_mov_b32_e32 v57, v0
	v_mov_b32_e32 v58, v0
	v_mov_b32_e32 v59, v0
	v_mov_b32_e32 v60, v0
	v_mov_b32_e32 v61, v0
	v_mov_b32_e32 v62, v0
	v_mov_b32_e32 v63, v0
	s_waitcnt vmcnt(1)
; DI void gemm_128_2set(const bf16_t* __restrict__ A, int lda, const bf16_t* __restrict__ B, int ldb, int K, f32x16 (&acc)[2][2], bf16_t* sA, bf16_t* sB) {
;     ...
;   for (int k0 = 0; k0 < K - 128; k0 += 128) {
;     __syncthreads();
;     ST2(pa0, pa1, pa2, pa3, pb0, pb1, pb2, pb3)
;     __syncthreads();
;     GL2_P(k0 + 128)
;     MMA2()
;     __syncthreads();
;     ST2(qa0, qa1, qa2, qa3, qb0, qb1, qb2, qb3)
;     __syncthreads();
;     GL2_Q(k0 + 192)
;     MMA2()
;   }
.LBB0_883:
	s_waitcnt lgkmcnt(0)
	s_barrier
	s_waitcnt vmcnt(15)
	ds_write_b128 v134, v[96:99]
	s_waitcnt vmcnt(14)
	ds_write_b128 v134, v[100:103] offset:4608
	s_waitcnt vmcnt(13)
	ds_write_b128 v134, v[104:107] offset:9216
	s_waitcnt vmcnt(12)
	ds_write_b128 v134, v[108:111] offset:13824
	s_waitcnt vmcnt(11)
	ds_write_b128 v134, v[112:115] offset:18432
	s_waitcnt vmcnt(10)
	ds_write_b128 v134, v[116:119] offset:23040
	s_waitcnt vmcnt(9)
	ds_write_b128 v134, v[120:123] offset:27648
	s_waitcnt vmcnt(8)
	ds_write_b128 v134, v[124:127] offset:32256
	s_waitcnt lgkmcnt(0)
	s_barrier
	ds_read_b128 v[96:99], v128
	ds_read_b128 v[100:103], v129 offset:18432
	ds_read_b128 v[104:107], v128 offset:32
	ds_read_b128 v[108:111], v129 offset:18464
	ds_read_b128 v[112:115], v129 offset:23040
	ds_read_b128 v[116:119], v129 offset:23072
	s_waitcnt lgkmcnt(4)
	v_mfma_f32_32x32x16_bf16 v[48:63], v[96:99], v[100:103], v[48:63]
	s_mov_b32 s52, 0x17864000
	s_addk_i32 s51, 0x80
	s_cmpk_lt_u32 s51, 0x700
	s_waitcnt lgkmcnt(1)
	v_mfma_f32_32x32x16_bf16 v[32:47], v[96:99], v[112:115], v[32:47]
	ds_read_b128 v[96:99], v128 offset:4608
	ds_read_b128 v[120:123], v128 offset:4640
	s_waitcnt lgkmcnt(1)
	v_mfma_f32_32x32x16_bf16 v[16:31], v[96:99], v[100:103], v[16:31]
	v_mfma_f32_32x32x16_bf16 v[0:15], v[96:99], v[112:115], v[0:15]
	v_lshl_add_u64 v[112:113], v[132:133], 0, v[156:157]
	ds_read_b128 v[96:99], v128 offset:4672
	ds_read_b128 v[100:103], v128 offset:64
	ds_read_b128 v[136:139], v128 offset:96
	v_add_co_u32_e32 v196, vcc, s83, v112
	v_lshl_add_u64 v[114:115], v[130:131], 0, v[156:157]
	s_nop 0
	v_addc_co_u32_e32 v197, vcc, 0, v113, vcc
	v_mfma_f32_32x32x16_bf16 v[48:63], v[104:107], v[108:111], v[48:63]
	v_add_co_u32_e32 v198, vcc, s84, v112
	v_lshl_add_u64 v[130:131], v[130:131], 0, s[94:95]
	s_nop 0
	v_addc_co_u32_e32 v199, vcc, 0, v113, vcc
	v_add_co_u32_e32 v200, vcc, s85, v112
	v_mfma_f32_32x32x16_bf16 v[32:47], v[104:107], v[116:119], v[32:47]
	s_nop 0
	v_addc_co_u32_e32 v201, vcc, 0, v113, vcc
	v_add_co_u32_e32 v202, vcc, s86, v112
	v_lshl_add_u64 v[132:133], v[132:133], 0, s[94:95]
	s_nop 0
	v_addc_co_u32_e32 v203, vcc, 0, v113, vcc
	s_waitcnt lgkmcnt(3)
	v_mfma_f32_32x32x16_bf16 v[16:31], v[120:123], v[108:111], v[16:31]
	ds_read_b128 v[184:187], v128 offset:4704
	ds_read_b128 v[104:107], v129 offset:18496
	ds_read_b128 v[188:191], v129 offset:18528
	ds_read_b128 v[108:111], v129 offset:23104
	ds_read_b128 v[192:195], v129 offset:23136
	v_add_co_u32_e32 v204, vcc, s52, v114
	s_mov_b32 s52, 0x17884000
	s_nop 0
	v_addc_co_u32_e32 v205, vcc, 0, v115, vcc
	v_add_co_u32_e32 v206, vcc, s52, v114
	v_mfma_f32_32x32x16_bf16 v[0:15], v[120:123], v[116:119], v[0:15]
	s_nop 0
	v_addc_co_u32_e32 v207, vcc, 0, v115, vcc
	s_mov_b32 s52, 0x178a4000
	v_add_co_u32_e32 v208, vcc, s52, v114
	s_mov_b32 s52, 0x178c4000
	s_nop 0
	v_addc_co_u32_e32 v209, vcc, 0, v115, vcc
	s_waitcnt lgkmcnt(3)
	v_mfma_f32_32x32x16_bf16 v[48:63], v[100:103], v[104:107], v[48:63]
	v_add_co_u32_e32 v210, vcc, s52, v114
	s_nop 1
	v_addc_co_u32_e32 v211, vcc, 0, v115, vcc
	s_waitcnt lgkmcnt(1)
	v_mfma_f32_32x32x16_bf16 v[32:47], v[100:103], v[108:111], v[32:47]
	v_mfma_f32_32x32x16_bf16 v[16:31], v[96:99], v[104:107], v[16:31]
	v_mfma_f32_32x32x16_bf16 v[0:15], v[96:99], v[108:111], v[0:15]
	global_load_dwordx4 v[96:99], v[196:197], off offset:2048
	global_load_dwordx4 v[100:103], v[198:199], off offset:2048
	global_load_dwordx4 v[104:107], v[200:201], off offset:2048
	global_load_dwordx4 v[108:111], v[202:203], off offset:2048
	global_load_dwordx4 v[112:115], v[204:205], off offset:2048
	global_load_dwordx4 v[116:119], v[206:207], off offset:2048
	global_load_dwordx4 v[120:123], v[208:209], off offset:2048
	global_load_dwordx4 v[124:127], v[210:211], off offset:2048
	s_waitcnt lgkmcnt(0)
	s_barrier
	s_waitcnt vmcnt(15)
	ds_write_b128 v134, v[80:83]
	s_waitcnt vmcnt(14)
	ds_write_b128 v134, v[64:67] offset:4608
	s_waitcnt vmcnt(13)
	ds_write_b128 v134, v[68:71] offset:9216
	s_waitcnt vmcnt(12)
	ds_write_b128 v134, v[72:75] offset:13824
	s_waitcnt vmcnt(11)
	ds_write_b128 v134, v[76:79] offset:18432
	s_waitcnt vmcnt(10)
	ds_write_b128 v134, v[84:87] offset:23040
	s_waitcnt vmcnt(9)
	ds_write_b128 v134, v[88:91] offset:27648
	s_waitcnt vmcnt(8)
	ds_write_b128 v134, v[92:95] offset:32256
	v_mfma_f32_32x32x16_bf16 v[48:63], v[136:139], v[188:191], v[48:63]
	s_waitcnt lgkmcnt(0)
	s_barrier
; DI void gemm_128_2set(const bf16_t* __restrict__ A, int lda, const bf16_t* __restrict__ B, int ldb, int K, f32x16 (&acc)[2][2], bf16_t* sA, bf16_t* sB) {
;     ...
;     GL2_P(k0 + 128)
;     MMA2()
;     __syncthreads();
;     ST2(qa0, qa1, qa2, qa3, qb0, qb1, qb2, qb3)
;     __syncthreads();
;     GL2_Q(k0 + 192)
;     MMA2()
;   }
;   __syncthreads();
;   ST2(pa0, pa1, pa2, pa3, pb0, pb1, pb2, pb3)
;   __syncthreads();
;   MMA2()
;   __syncthreads();
;   ST2(qa0, qa1, qa2, qa3, qb0, qb1, qb2, qb3)
;   __syncthreads();
;   MMA2()
	ds_read_b128 v[64:67], v128
	ds_read_b128 v[68:71], v129 offset:18432
	ds_read_b128 v[72:75], v128 offset:32
	ds_read_b128 v[76:79], v129 offset:18464
	ds_read_b128 v[80:83], v129 offset:23040
	ds_read_b128 v[84:87], v129 offset:23072
	v_mfma_f32_32x32x16_bf16 v[32:47], v[136:139], v[192:195], v[32:47]
	v_mfma_f32_32x32x16_bf16 v[16:31], v[184:187], v[188:191], v[16:31]
	v_mfma_f32_32x32x16_bf16 v[0:15], v[184:187], v[192:195], v[0:15]
	s_waitcnt lgkmcnt(4)
	v_mfma_f32_32x32x16_bf16 v[48:63], v[64:67], v[68:71], v[48:63]
	s_waitcnt lgkmcnt(1)
	v_mfma_f32_32x32x16_bf16 v[32:47], v[64:67], v[80:83], v[32:47]
	ds_read_b128 v[64:67], v128 offset:4608
	ds_read_b128 v[88:91], v128 offset:4640
	s_waitcnt lgkmcnt(1)
	v_mfma_f32_32x32x16_bf16 v[16:31], v[64:67], v[68:71], v[16:31]
	v_mfma_f32_32x32x16_bf16 v[0:15], v[64:67], v[80:83], v[0:15]
	v_mfma_f32_32x32x16_bf16 v[48:63], v[72:75], v[76:79], v[48:63]
	v_mfma_f32_32x32x16_bf16 v[32:47], v[72:75], v[84:87], v[32:47]
	ds_read_b128 v[64:67], v128 offset:64
	ds_read_b128 v[68:71], v129 offset:18496
	ds_read_b128 v[72:75], v128 offset:96
	ds_read_b128 v[92:95], v129 offset:18528
	s_waitcnt lgkmcnt(4)
	v_mfma_f32_32x32x16_bf16 v[16:31], v[88:91], v[76:79], v[16:31]
	ds_read_b128 v[76:79], v129 offset:23104
	ds_read_b128 v[136:139], v129 offset:23136
	v_mfma_f32_32x32x16_bf16 v[0:15], v[88:91], v[84:87], v[0:15]
	s_waitcnt lgkmcnt(4)
	v_mfma_f32_32x32x16_bf16 v[48:63], v[64:67], v[68:71], v[48:63]
	s_waitcnt lgkmcnt(1)
	v_mfma_f32_32x32x16_bf16 v[32:47], v[64:67], v[76:79], v[32:47]
	ds_read_b128 v[64:67], v128 offset:4672
	ds_read_b128 v[184:187], v128 offset:4704
	s_waitcnt lgkmcnt(1)
	v_mfma_f32_32x32x16_bf16 v[16:31], v[64:67], v[68:71], v[16:31]
	v_mfma_f32_32x32x16_bf16 v[0:15], v[64:67], v[76:79], v[0:15]
	v_mfma_f32_32x32x16_bf16 v[48:63], v[72:75], v[92:95], v[48:63]
	v_mfma_f32_32x32x16_bf16 v[32:47], v[72:75], v[136:139], v[32:47]
	global_load_dwordx4 v[80:83], v[196:197], off offset:2176
	global_load_dwordx4 v[64:67], v[198:199], off offset:2176
	global_load_dwordx4 v[68:71], v[200:201], off offset:2176
	global_load_dwordx4 v[72:75], v[202:203], off offset:2176
	global_load_dwordx4 v[76:79], v[204:205], off offset:2176
	global_load_dwordx4 v[84:87], v[206:207], off offset:2176
	global_load_dwordx4 v[88:91], v[208:209], off offset:2176
	s_waitcnt lgkmcnt(0)
	v_mfma_f32_32x32x16_bf16 v[16:31], v[184:187], v[92:95], v[16:31]
	global_load_dwordx4 v[92:95], v[210:211], off offset:2176
	v_mfma_f32_32x32x16_bf16 v[0:15], v[184:187], v[136:139], v[0:15]
	s_cbranch_scc1 .LBB0_883
	s_barrier
	s_waitcnt vmcnt(15)
	ds_write_b128 v134, v[96:99]
	s_waitcnt vmcnt(14)
	ds_write_b128 v134, v[100:103] offset:4608
	s_waitcnt vmcnt(13)
	ds_write_b128 v134, v[104:107] offset:9216
	s_waitcnt vmcnt(12)
	ds_write_b128 v134, v[108:111] offset:13824
	s_waitcnt vmcnt(11)
	ds_write_b128 v134, v[112:115] offset:18432
	s_waitcnt vmcnt(10)
	ds_write_b128 v134, v[116:119] offset:23040
	s_waitcnt vmcnt(9)
	ds_write_b128 v134, v[120:123] offset:27648
	s_waitcnt vmcnt(8)
	ds_write_b128 v134, v[124:127] offset:32256
	s_waitcnt lgkmcnt(0)
	s_barrier
	ds_read_b128 v[96:99], v128 offset:4608
	ds_read_b128 v[100:103], v129 offset:23040
	ds_read_b128 v[104:107], v128
	ds_read_b128 v[108:111], v128 offset:32
	ds_read_b128 v[112:115], v129 offset:18432
	ds_read_b128 v[116:119], v129 offset:18464
	s_waitcnt lgkmcnt(1)
	v_mfma_f32_32x32x16_bf16 v[48:63], v[104:107], v[112:115], v[48:63]
	s_add_i32 s73, s73, 1
	s_addk_i32 s50, 0x800
	s_cmp_eq_u32 s73, 4
	v_mfma_f32_32x32x16_bf16 v[32:47], v[104:107], v[100:103], v[32:47]
	v_mfma_f32_32x32x16_bf16 v[16:31], v[96:99], v[112:115], v[16:31]
	v_mfma_f32_32x32x16_bf16 v[0:15], v[96:99], v[100:103], v[0:15]
	ds_read_b128 v[96:99], v128 offset:4640
	ds_read_b128 v[100:103], v129 offset:23072
	s_waitcnt lgkmcnt(2)
	v_mfma_f32_32x32x16_bf16 v[48:63], v[108:111], v[116:119], v[48:63]
	s_waitcnt lgkmcnt(0)
	v_mfma_f32_32x32x16_bf16 v[32:47], v[108:111], v[100:103], v[32:47]
	v_mfma_f32_32x32x16_bf16 v[16:31], v[96:99], v[116:119], v[16:31]
	v_mfma_f32_32x32x16_bf16 v[0:15], v[96:99], v[100:103], v[0:15]
	ds_read_b128 v[96:99], v128 offset:64
	ds_read_b128 v[100:103], v128 offset:4672
	ds_read_b128 v[104:107], v129 offset:18496
	ds_read_b128 v[108:111], v129 offset:23104
	s_waitcnt lgkmcnt(1)
	v_mfma_f32_32x32x16_bf16 v[48:63], v[96:99], v[104:107], v[48:63]
	s_waitcnt lgkmcnt(0)
	v_mfma_f32_32x32x16_bf16 v[32:47], v[96:99], v[108:111], v[32:47]
	v_mfma_f32_32x32x16_bf16 v[16:31], v[100:103], v[104:107], v[16:31]
	v_mfma_f32_32x32x16_bf16 v[0:15], v[100:103], v[108:111], v[0:15]
	ds_read_b128 v[96:99], v128 offset:96
	ds_read_b128 v[100:103], v128 offset:4704
	ds_read_b128 v[104:107], v129 offset:18528
	ds_read_b128 v[108:111], v129 offset:23136
	s_waitcnt lgkmcnt(0)
	s_barrier
	s_waitcnt vmcnt(7)
	ds_write_b128 v134, v[80:83]
	s_waitcnt vmcnt(6)
	ds_write_b128 v134, v[64:67] offset:4608
	s_waitcnt vmcnt(5)
	ds_write_b128 v134, v[68:71] offset:9216
	s_waitcnt vmcnt(4)
	ds_write_b128 v134, v[72:75] offset:13824
	s_waitcnt vmcnt(3)
	ds_write_b128 v134, v[76:79] offset:18432
	s_waitcnt vmcnt(2)
	ds_write_b128 v134, v[84:87] offset:23040
	s_waitcnt vmcnt(1)
	ds_write_b128 v134, v[88:91] offset:27648
	s_waitcnt vmcnt(0)
	ds_write_b128 v134, v[92:95] offset:32256
	s_waitcnt lgkmcnt(0)
	s_barrier
; DI float sigmf(float x) { return __builtin_amdgcn_rcpf(1.f + __expf(-x)); }
; DI void phase_merge(CP p, const Ptrs& w, int l, bf16_t* sA, bf16_t* sB, unsigned* sU) {
;     ...
;       for (int a = 0; a < 2; ++a)
; #pragma unroll
;         for (int c = 0; c < 2; ++c)
; #pragma unroll
;           for (int i = 0; i < 8; ++i) {
;             unsigned uv = sU[((a * 2 + c) * 8 + i) * 256 + tid];
;             float u0 = __uint_as_float(uv << 16), u1 = __uint_as_float(uv & 0xffff0000u);
;             const unsigned tv = totp[a][c][i];
;             float t0 = __uint_as_float(tv << 16) + sigmf(G[a][c][2 * i]) * u0;
;             float t1 = __uint_as_float(tv & 0xffff0000u) + sigmf(G[a][c][2 * i + 1]) * u1;
;             totp[a][c][i] = pack2(t0, t1);
;           }
	v_mfma_f32_32x32x16_bf16 v[48:63], v[96:99], v[104:107], v[48:63]
	ds_read_b128 v[64:67], v128 offset:4608
	ds_read_b128 v[68:71], v129 offset:23040
	ds_read_b128 v[72:75], v128
	ds_read_b128 v[76:79], v128 offset:32
	ds_read_b128 v[80:83], v129 offset:18432
	ds_read_b128 v[84:87], v129 offset:18464
	v_mfma_f32_32x32x16_bf16 v[32:47], v[96:99], v[108:111], v[32:47]
	v_mfma_f32_32x32x16_bf16 v[16:31], v[100:103], v[104:107], v[16:31]
	v_mfma_f32_32x32x16_bf16 v[0:15], v[100:103], v[108:111], v[0:15]
	s_waitcnt lgkmcnt(1)
	v_mfma_f32_32x32x16_bf16 v[48:63], v[72:75], v[80:83], v[48:63]
	v_mfma_f32_32x32x16_bf16 v[32:47], v[72:75], v[68:71], v[32:47]
	v_mfma_f32_32x32x16_bf16 v[16:31], v[64:67], v[80:83], v[16:31]
	v_mfma_f32_32x32x16_bf16 v[0:15], v[64:67], v[68:71], v[0:15]
	ds_read_b128 v[64:67], v128 offset:4640
	ds_read_b128 v[68:71], v129 offset:23072
	s_waitcnt lgkmcnt(2)
	v_mfma_f32_32x32x16_bf16 v[48:63], v[76:79], v[84:87], v[48:63]
	s_waitcnt lgkmcnt(0)
	v_mfma_f32_32x32x16_bf16 v[32:47], v[76:79], v[68:71], v[32:47]
	v_mfma_f32_32x32x16_bf16 v[16:31], v[64:67], v[84:87], v[16:31]
	v_mfma_f32_32x32x16_bf16 v[0:15], v[64:67], v[68:71], v[0:15]
	ds_read_b128 v[64:67], v128 offset:64
	ds_read_b128 v[68:71], v128 offset:4672
	ds_read_b128 v[72:75], v129 offset:18496
	ds_read_b128 v[76:79], v129 offset:23104
	s_waitcnt lgkmcnt(1)
	v_mfma_f32_32x32x16_bf16 v[48:63], v[64:67], v[72:75], v[48:63]
	s_waitcnt lgkmcnt(0)
	v_mfma_f32_32x32x16_bf16 v[32:47], v[64:67], v[76:79], v[32:47]
	v_mfma_f32_32x32x16_bf16 v[16:31], v[68:71], v[72:75], v[16:31]
	v_mfma_f32_32x32x16_bf16 v[0:15], v[68:71], v[76:79], v[0:15]
	ds_read_b128 v[64:67], v128 offset:96
	ds_read_b128 v[68:71], v128 offset:4704
	ds_read_b128 v[72:75], v129 offset:18528
	ds_read_b128 v[76:79], v129 offset:23136
	s_waitcnt lgkmcnt(1)
	v_mfma_f32_32x32x16_bf16 v[48:63], v[64:67], v[72:75], v[48:63]
	s_waitcnt lgkmcnt(0)
	v_mfma_f32_32x32x16_bf16 v[32:47], v[64:67], v[76:79], v[32:47]
	s_nop 9
	v_mul_f32_e32 v48, 0xbfb8aa3b, v48
	v_mul_f32_e32 v49, 0xbfb8aa3b, v49
	v_exp_f32_e32 v48, v48
	v_exp_f32_e32 v49, v49
	v_mul_f32_e32 v50, 0xbfb8aa3b, v50
	v_mul_f32_e32 v51, 0xbfb8aa3b, v51
	v_exp_f32_e32 v50, v50
	v_exp_f32_e32 v51, v51
	ds_read2st64_b32 v[64:65], v140 offset0:144 offset1:148
	v_add_f32_e32 v48, 1.0, v48
	v_add_f32_e32 v49, 1.0, v49
	v_rcp_f32_e32 v48, v48
	v_rcp_f32_e32 v49, v49
	v_add_f32_e32 v50, 1.0, v50
	v_add_f32_e32 v51, 1.0, v51
	v_rcp_f32_e32 v50, v50
	v_rcp_f32_e32 v51, v51
	v_mfma_f32_32x32x16_bf16 v[16:31], v[68:71], v[72:75], v[16:31]
	s_waitcnt lgkmcnt(0)
	v_lshlrev_b32_e32 v66, 16, v64
	v_and_b32_e32 v67, 0xffff0000, v64
	v_lshlrev_b32_e32 v64, 16, v182
	v_mul_f32_e32 v32, 0xbfb8aa3b, v32
	v_mul_f32_e32 v33, 0xbfb8aa3b, v33
	v_exp_f32_e32 v32, v32
	v_exp_f32_e32 v33, v33
	v_mfma_f32_32x32x16_bf16 v[0:15], v[68:71], v[76:79], v[0:15]
	v_lshlrev_b32_e32 v68, 16, v183
	v_and_b32_e32 v69, 0xffff0000, v183
	v_fma_f32 v48, v48, v66, v68
	v_fma_f32 v49, v49, v67, v69
	v_mul_f32_e32 v34, 0xbfb8aa3b, v34
	v_cvt_pk_bf16_f32 v183, v48, v49
	v_lshlrev_b32_e32 v48, 16, v65
	v_and_b32_e32 v49, 0xffff0000, v65
	v_and_b32_e32 v65, 0xffff0000, v182
	v_pk_fma_f32 v[48:49], v[50:51], v[48:49], v[64:65]
	v_lshlrev_b32_e32 v64, 16, v181
	v_cvt_pk_bf16_f32 v182, v48, v49
	ds_read2st64_b32 v[48:49], v140 offset0:152 offset1:156
	v_and_b32_e32 v65, 0xffff0000, v181
	v_mul_f32_e32 v35, 0xbfb8aa3b, v35
	v_exp_f32_e32 v34, v34
	v_exp_f32_e32 v35, v35
	s_waitcnt lgkmcnt(0)
	v_lshlrev_b32_e32 v50, 16, v48
	v_and_b32_e32 v51, 0xffff0000, v48
	v_mul_f32_e32 v48, 0xbfb8aa3b, v52
	v_exp_f32_e32 v48, v48
	v_add_f32_e32 v32, 1.0, v32
	v_add_f32_e32 v33, 1.0, v33
	v_rcp_f32_e32 v32, v32
	v_add_f32_e32 v48, 1.0, v48
	v_rcp_f32_e32 v52, v48
	v_mul_f32_e32 v48, 0xbfb8aa3b, v53
	v_exp_f32_e32 v48, v48
	v_rcp_f32_e32 v33, v33
	v_add_f32_e32 v34, 1.0, v34
	v_add_f32_e32 v35, 1.0, v35
	v_add_f32_e32 v48, 1.0, v48
	v_rcp_f32_e32 v53, v48
	v_lshlrev_b32_e32 v48, 16, v49
	v_and_b32_e32 v49, 0xffff0000, v49
	v_rcp_f32_e32 v34, v34
	v_pk_fma_f32 v[50:51], v[52:53], v[50:51], v[64:65]
	v_mul_f32_e32 v53, 0xbfb8aa3b, v55
	v_cvt_pk_bf16_f32 v181, v50, v51
	v_mul_f32_e32 v51, 0xbfb8aa3b, v54
	v_exp_f32_e32 v51, v51
	v_exp_f32_e32 v53, v53
	v_lshlrev_b32_e32 v50, 16, v180
	v_rcp_f32_e32 v35, v35
	v_add_f32_e32 v51, 1.0, v51
	v_add_f32_e32 v53, 1.0, v53
	v_rcp_f32_e32 v52, v51
	v_rcp_f32_e32 v53, v53
	v_and_b32_e32 v51, 0xffff0000, v180
	v_mul_f32_e32 v16, 0xbfb8aa3b, v16
	v_mul_f32_e32 v17, 0xbfb8aa3b, v17
	v_pk_fma_f32 v[48:49], v[52:53], v[48:49], v[50:51]
	v_lshlrev_b32_e32 v52, 16, v179
	v_cvt_pk_bf16_f32 v180, v48, v49
	ds_read2st64_b32 v[48:49], v140 offset0:160 offset1:164
	v_and_b32_e32 v53, 0xffff0000, v179
	v_exp_f32_e32 v16, v16
	v_exp_f32_e32 v17, v17
	v_mul_f32_e32 v18, 0xbfb8aa3b, v18
	s_waitcnt lgkmcnt(0)
	v_lshlrev_b32_e32 v50, 16, v48
	v_and_b32_e32 v51, 0xffff0000, v48
	v_mul_f32_e32 v48, 0xbfb8aa3b, v56
	v_exp_f32_e32 v48, v48
	v_mul_f32_e32 v19, 0xbfb8aa3b, v19
	v_exp_f32_e32 v18, v18
	v_exp_f32_e32 v19, v19
	v_add_f32_e32 v48, 1.0, v48
	v_rcp_f32_e32 v54, v48
	v_mul_f32_e32 v48, 0xbfb8aa3b, v57
	v_exp_f32_e32 v48, v48
	v_add_f32_e32 v16, 1.0, v16
	v_add_f32_e32 v17, 1.0, v17
	v_rcp_f32_e32 v16, v16
	v_add_f32_e32 v48, 1.0, v48
	v_rcp_f32_e32 v55, v48
	v_lshlrev_b32_e32 v48, 16, v49
	v_and_b32_e32 v49, 0xffff0000, v49
	v_rcp_f32_e32 v17, v17
	v_pk_fma_f32 v[50:51], v[54:55], v[50:51], v[52:53]
	v_mul_f32_e32 v53, 0xbfb8aa3b, v59
	v_cvt_pk_bf16_f32 v179, v50, v51
	v_mul_f32_e32 v51, 0xbfb8aa3b, v58
	v_exp_f32_e32 v51, v51
	v_exp_f32_e32 v53, v53
	v_lshlrev_b32_e32 v50, 16, v177
	v_add_f32_e32 v18, 1.0, v18
	v_add_f32_e32 v51, 1.0, v51
	v_add_f32_e32 v53, 1.0, v53
	v_rcp_f32_e32 v52, v51
	v_rcp_f32_e32 v53, v53
	v_and_b32_e32 v51, 0xffff0000, v177
	v_add_f32_e32 v19, 1.0, v19
	v_rcp_f32_e32 v18, v18
	v_pk_fma_f32 v[48:49], v[52:53], v[48:49], v[50:51]
	v_lshlrev_b32_e32 v52, 16, v178
	v_cvt_pk_bf16_f32 v177, v48, v49
	ds_read2st64_b32 v[48:49], v140 offset0:168 offset1:172
	v_and_b32_e32 v53, 0xffff0000, v178
	v_rcp_f32_e32 v19, v19
	v_mul_f32_e32 v0, 0xbfb8aa3b, v0
	v_mul_f32_e32 v1, 0xbfb8aa3b, v1
	s_waitcnt lgkmcnt(0)
; DI float sigmf(float x) { return __builtin_amdgcn_rcpf(1.f + __expf(-x)); }
; DI void phase_merge(CP p, const Ptrs& w, int l, bf16_t* sA, bf16_t* sB, unsigned* sU) {
;     ...
;       for (int a = 0; a < 2; ++a)
; #pragma unroll
;         for (int c = 0; c < 2; ++c)
; #pragma unroll
;           for (int i = 0; i < 8; ++i) {
;             unsigned uv = sU[((a * 2 + c) * 8 + i) * 256 + tid];
;             float u0 = __uint_as_float(uv << 16), u1 = __uint_as_float(uv & 0xffff0000u);
;             const unsigned tv = totp[a][c][i];
;             float t0 = __uint_as_float(tv << 16) + sigmf(G[a][c][2 * i]) * u0;
;             float t1 = __uint_as_float(tv & 0xffff0000u) + sigmf(G[a][c][2 * i + 1]) * u1;
;             totp[a][c][i] = pack2(t0, t1);
;           }
	v_lshlrev_b32_e32 v50, 16, v48
	v_and_b32_e32 v51, 0xffff0000, v48
	v_mul_f32_e32 v48, 0xbfb8aa3b, v60
	v_exp_f32_e32 v48, v48
	v_exp_f32_e32 v0, v0
	v_exp_f32_e32 v1, v1
	v_mul_f32_e32 v2, 0xbfb8aa3b, v2
	v_add_f32_e32 v48, 1.0, v48
	v_rcp_f32_e32 v54, v48
	v_mul_f32_e32 v48, 0xbfb8aa3b, v61
	v_exp_f32_e32 v48, v48
	v_mul_f32_e32 v3, 0xbfb8aa3b, v3
	v_exp_f32_e32 v2, v2
	v_exp_f32_e32 v3, v3
	v_add_f32_e32 v48, 1.0, v48
	v_rcp_f32_e32 v55, v48
	v_lshlrev_b32_e32 v48, 16, v49
	v_and_b32_e32 v49, 0xffff0000, v49
	v_add_f32_e32 v0, 1.0, v0
	v_pk_fma_f32 v[50:51], v[54:55], v[50:51], v[52:53]
	v_mul_f32_e32 v53, 0xbfb8aa3b, v63
	v_cvt_pk_bf16_f32 v178, v50, v51
	v_mul_f32_e32 v51, 0xbfb8aa3b, v62
	v_exp_f32_e32 v51, v51
	v_exp_f32_e32 v53, v53
	v_lshlrev_b32_e32 v50, 16, v173
	v_add_f32_e32 v1, 1.0, v1
	v_add_f32_e32 v51, 1.0, v51
	v_add_f32_e32 v53, 1.0, v53
	v_rcp_f32_e32 v52, v51
	v_rcp_f32_e32 v53, v53
	v_and_b32_e32 v51, 0xffff0000, v173
	v_rcp_f32_e32 v0, v0
	v_rcp_f32_e32 v1, v1
	v_pk_fma_f32 v[48:49], v[52:53], v[48:49], v[50:51]
	v_lshlrev_b32_e32 v52, 16, v176
	v_cvt_pk_bf16_f32 v173, v48, v49
	ds_read2st64_b32 v[48:49], v140 offset0:176 offset1:180
	v_and_b32_e32 v53, 0xffff0000, v176
	v_add_f32_e32 v2, 1.0, v2
	v_add_f32_e32 v3, 1.0, v3
	v_rcp_f32_e32 v2, v2
	s_waitcnt lgkmcnt(0)
	v_lshlrev_b32_e32 v50, 16, v48
	v_and_b32_e32 v51, 0xffff0000, v48
	v_pk_fma_f32 v[32:33], v[32:33], v[50:51], v[52:53]
	v_lshlrev_b32_e32 v48, 16, v170
	v_cvt_pk_bf16_f32 v176, v32, v33
	v_lshlrev_b32_e32 v32, 16, v49
	v_and_b32_e32 v33, 0xffff0000, v49
	v_and_b32_e32 v49, 0xffff0000, v170
	v_pk_fma_f32 v[32:33], v[34:35], v[32:33], v[48:49]
	v_lshlrev_b32_e32 v48, 16, v175
	v_cvt_pk_bf16_f32 v170, v32, v33
	ds_read2st64_b32 v[32:33], v140 offset0:184 offset1:188
	v_and_b32_e32 v49, 0xffff0000, v175
	v_rcp_f32_e32 v3, v3
	s_waitcnt lgkmcnt(0)
	v_lshlrev_b32_e32 v34, 16, v32
	v_and_b32_e32 v35, 0xffff0000, v32
	v_mul_f32_e32 v32, 0xbfb8aa3b, v36
	v_exp_f32_e32 v32, v32
	s_nop 0
	v_add_f32_e32 v32, 1.0, v32
	v_rcp_f32_e32 v36, v32
	v_mul_f32_e32 v32, 0xbfb8aa3b, v37
	v_exp_f32_e32 v32, v32
	s_nop 0
	v_add_f32_e32 v32, 1.0, v32
	v_rcp_f32_e32 v37, v32
	v_lshlrev_b32_e32 v32, 16, v33
	v_and_b32_e32 v33, 0xffff0000, v33
	v_pk_fma_f32 v[34:35], v[36:37], v[34:35], v[48:49]
	s_nop 0
	v_cvt_pk_bf16_f32 v175, v34, v35
	v_mul_f32_e32 v35, 0xbfb8aa3b, v38
	v_mul_f32_e32 v37, 0xbfb8aa3b, v39
	v_exp_f32_e32 v35, v35
	v_exp_f32_e32 v37, v37
	v_lshlrev_b32_e32 v34, 16, v174
	v_add_f32_e32 v35, 1.0, v35
	v_add_f32_e32 v37, 1.0, v37
	v_rcp_f32_e32 v36, v35
	v_rcp_f32_e32 v37, v37
	v_and_b32_e32 v35, 0xffff0000, v174
	v_pk_fma_f32 v[32:33], v[36:37], v[32:33], v[34:35]
	s_nop 0
	v_cvt_pk_bf16_f32 v174, v32, v33
	ds_read2st64_b32 v[32:33], v140 offset0:192 offset1:196
	v_lshlrev_b32_e32 v36, 16, v172
	v_and_b32_e32 v37, 0xffff0000, v172
	s_waitcnt lgkmcnt(0)
	v_lshlrev_b32_e32 v34, 16, v32
	v_and_b32_e32 v35, 0xffff0000, v32
	v_mul_f32_e32 v32, 0xbfb8aa3b, v40
	v_exp_f32_e32 v32, v32
	s_nop 0
	v_add_f32_e32 v32, 1.0, v32
	v_rcp_f32_e32 v38, v32
	v_mul_f32_e32 v32, 0xbfb8aa3b, v41
	v_exp_f32_e32 v32, v32
	s_nop 0
	v_add_f32_e32 v32, 1.0, v32
	v_rcp_f32_e32 v39, v32
	v_lshlrev_b32_e32 v32, 16, v33
	v_and_b32_e32 v33, 0xffff0000, v33
	v_pk_fma_f32 v[34:35], v[38:39], v[34:35], v[36:37]
	s_nop 0
	v_cvt_pk_bf16_f32 v172, v34, v35
	v_mul_f32_e32 v35, 0xbfb8aa3b, v42
	v_mul_f32_e32 v37, 0xbfb8aa3b, v43
	v_exp_f32_e32 v35, v35
	v_exp_f32_e32 v37, v37
	v_lshlrev_b32_e32 v34, 16, v171
	v_add_f32_e32 v35, 1.0, v35
	v_add_f32_e32 v37, 1.0, v37
	v_rcp_f32_e32 v36, v35
	v_rcp_f32_e32 v37, v37
	v_and_b32_e32 v35, 0xffff0000, v171
	v_pk_fma_f32 v[32:33], v[36:37], v[32:33], v[34:35]
	s_nop 0
	v_cvt_pk_bf16_f32 v171, v32, v33
	ds_read2st64_b32 v[32:33], v140 offset0:200 offset1:204
	v_lshlrev_b32_e32 v36, 16, v169
	v_and_b32_e32 v37, 0xffff0000, v169
	s_waitcnt lgkmcnt(0)
	v_lshlrev_b32_e32 v34, 16, v32
	v_and_b32_e32 v35, 0xffff0000, v32
	v_mul_f32_e32 v32, 0xbfb8aa3b, v44
	v_exp_f32_e32 v32, v32
	s_nop 0
	v_add_f32_e32 v32, 1.0, v32
	v_rcp_f32_e32 v38, v32
	v_mul_f32_e32 v32, 0xbfb8aa3b, v45
	v_exp_f32_e32 v32, v32
	s_nop 0
	v_add_f32_e32 v32, 1.0, v32
	v_rcp_f32_e32 v39, v32
	v_lshlrev_b32_e32 v32, 16, v33
	v_and_b32_e32 v33, 0xffff0000, v33
	v_pk_fma_f32 v[34:35], v[38:39], v[34:35], v[36:37]
	s_nop 0
	v_cvt_pk_bf16_f32 v169, v34, v35
	v_mul_f32_e32 v35, 0xbfb8aa3b, v46
	v_mul_f32_e32 v37, 0xbfb8aa3b, v47
	v_exp_f32_e32 v35, v35
	v_exp_f32_e32 v37, v37
	v_lshlrev_b32_e32 v34, 16, v168
	v_add_f32_e32 v35, 1.0, v35
	v_add_f32_e32 v37, 1.0, v37
	v_rcp_f32_e32 v36, v35
	v_rcp_f32_e32 v37, v37
	v_and_b32_e32 v35, 0xffff0000, v168
	v_pk_fma_f32 v[32:33], v[36:37], v[32:33], v[34:35]
	s_nop 0
	v_cvt_pk_bf16_f32 v168, v32, v33
	ds_read2st64_b32 v[32:33], v140 offset0:208 offset1:212
	v_lshlrev_b32_e32 v36, 16, v167
	v_and_b32_e32 v37, 0xffff0000, v167
	s_waitcnt lgkmcnt(0)
	v_lshlrev_b32_e32 v34, 16, v32
	v_and_b32_e32 v35, 0xffff0000, v32
	v_pk_fma_f32 v[16:17], v[16:17], v[34:35], v[36:37]
	v_lshlrev_b32_e32 v32, 16, v164
	v_cvt_pk_bf16_f32 v167, v16, v17
	v_lshlrev_b32_e32 v16, 16, v33
	v_and_b32_e32 v17, 0xffff0000, v33
	v_and_b32_e32 v33, 0xffff0000, v164
	v_pk_fma_f32 v[16:17], v[18:19], v[16:17], v[32:33]
	v_lshlrev_b32_e32 v32, 16, v163
	v_cvt_pk_bf16_f32 v164, v16, v17
	ds_read2st64_b32 v[16:17], v140 offset0:216 offset1:220
	v_and_b32_e32 v33, 0xffff0000, v163
	s_waitcnt lgkmcnt(0)
; DI float sigmf(float x) { return __builtin_amdgcn_rcpf(1.f + __expf(-x)); }
; DI void phase_merge(CP p, const Ptrs& w, int l, bf16_t* sA, bf16_t* sB, unsigned* sU) {
;     ...
;       for (int a = 0; a < 2; ++a)
; #pragma unroll
;         for (int c = 0; c < 2; ++c)
; #pragma unroll
;           for (int i = 0; i < 8; ++i) {
;             unsigned uv = sU[((a * 2 + c) * 8 + i) * 256 + tid];
;             float u0 = __uint_as_float(uv << 16), u1 = __uint_as_float(uv & 0xffff0000u);
;             const unsigned tv = totp[a][c][i];
;             float t0 = __uint_as_float(tv << 16) + sigmf(G[a][c][2 * i]) * u0;
;             float t1 = __uint_as_float(tv & 0xffff0000u) + sigmf(G[a][c][2 * i + 1]) * u1;
;             totp[a][c][i] = pack2(t0, t1);
;           }
	v_lshlrev_b32_e32 v18, 16, v16
	v_and_b32_e32 v19, 0xffff0000, v16
	v_mul_f32_e32 v16, 0xbfb8aa3b, v20
	v_exp_f32_e32 v16, v16
	s_nop 0
	v_add_f32_e32 v16, 1.0, v16
	v_rcp_f32_e32 v20, v16
	v_mul_f32_e32 v16, 0xbfb8aa3b, v21
	v_exp_f32_e32 v16, v16
	s_nop 0
	v_add_f32_e32 v16, 1.0, v16
	v_rcp_f32_e32 v21, v16
	v_lshlrev_b32_e32 v16, 16, v17
	v_and_b32_e32 v17, 0xffff0000, v17
	v_pk_fma_f32 v[18:19], v[20:21], v[18:19], v[32:33]
	s_nop 0
	v_cvt_pk_bf16_f32 v163, v18, v19
	v_mul_f32_e32 v19, 0xbfb8aa3b, v22
	v_mul_f32_e32 v21, 0xbfb8aa3b, v23
	v_exp_f32_e32 v19, v19
	v_exp_f32_e32 v21, v21
	v_lshlrev_b32_e32 v18, 16, v161
	v_add_f32_e32 v19, 1.0, v19
	v_add_f32_e32 v21, 1.0, v21
	v_rcp_f32_e32 v20, v19
	v_rcp_f32_e32 v21, v21
	v_and_b32_e32 v19, 0xffff0000, v161
	v_pk_fma_f32 v[16:17], v[20:21], v[16:17], v[18:19]
	s_nop 0
	v_cvt_pk_bf16_f32 v161, v16, v17
	ds_read2st64_b32 v[16:17], v140 offset0:224 offset1:228
	v_lshlrev_b32_e32 v20, 16, v155
	v_and_b32_e32 v21, 0xffff0000, v155
	s_waitcnt lgkmcnt(0)
	v_lshlrev_b32_e32 v18, 16, v16
	v_and_b32_e32 v19, 0xffff0000, v16
	v_mul_f32_e32 v16, 0xbfb8aa3b, v24
	v_exp_f32_e32 v16, v16
	s_nop 0
	v_add_f32_e32 v16, 1.0, v16
	v_rcp_f32_e32 v22, v16
	v_mul_f32_e32 v16, 0xbfb8aa3b, v25
	v_exp_f32_e32 v16, v16
	s_nop 0
	v_add_f32_e32 v16, 1.0, v16
	v_rcp_f32_e32 v23, v16
	v_lshlrev_b32_e32 v16, 16, v17
	v_and_b32_e32 v17, 0xffff0000, v17
	v_pk_fma_f32 v[18:19], v[22:23], v[18:19], v[20:21]
	s_nop 0
	v_cvt_pk_bf16_f32 v155, v18, v19
	v_mul_f32_e32 v19, 0xbfb8aa3b, v26
	v_mul_f32_e32 v21, 0xbfb8aa3b, v27
	v_exp_f32_e32 v19, v19
	v_exp_f32_e32 v21, v21
	v_lshlrev_b32_e32 v18, 16, v154
	v_add_f32_e32 v19, 1.0, v19
	v_add_f32_e32 v21, 1.0, v21
	v_rcp_f32_e32 v20, v19
	v_rcp_f32_e32 v21, v21
	v_and_b32_e32 v19, 0xffff0000, v154
	v_pk_fma_f32 v[16:17], v[20:21], v[16:17], v[18:19]
	s_nop 0
	v_cvt_pk_bf16_f32 v154, v16, v17
	ds_read2st64_b32 v[16:17], v140 offset0:232 offset1:236
	v_lshlrev_b32_e32 v20, 16, v153
	v_and_b32_e32 v21, 0xffff0000, v153
	s_waitcnt lgkmcnt(0)
	v_lshlrev_b32_e32 v18, 16, v16
	v_and_b32_e32 v19, 0xffff0000, v16
	v_mul_f32_e32 v16, 0xbfb8aa3b, v28
	v_exp_f32_e32 v16, v16
	s_nop 0
	v_add_f32_e32 v16, 1.0, v16
	v_rcp_f32_e32 v22, v16
	v_mul_f32_e32 v16, 0xbfb8aa3b, v29
	v_exp_f32_e32 v16, v16
	s_nop 0
	v_add_f32_e32 v16, 1.0, v16
	v_rcp_f32_e32 v23, v16
	v_lshlrev_b32_e32 v16, 16, v17
	v_and_b32_e32 v17, 0xffff0000, v17
	v_pk_fma_f32 v[18:19], v[22:23], v[18:19], v[20:21]
	s_nop 0
	v_cvt_pk_bf16_f32 v153, v18, v19
	v_mul_f32_e32 v19, 0xbfb8aa3b, v30
	v_mul_f32_e32 v21, 0xbfb8aa3b, v31
	v_exp_f32_e32 v19, v19
	v_exp_f32_e32 v21, v21
	v_lshlrev_b32_e32 v18, 16, v152
	v_add_f32_e32 v19, 1.0, v19
	v_add_f32_e32 v21, 1.0, v21
	v_rcp_f32_e32 v20, v19
	v_rcp_f32_e32 v21, v21
	v_and_b32_e32 v19, 0xffff0000, v152
	v_pk_fma_f32 v[16:17], v[20:21], v[16:17], v[18:19]
	s_nop 0
	v_cvt_pk_bf16_f32 v152, v16, v17
	ds_read2st64_b32 v[16:17], v140 offset0:240 offset1:244
	v_lshlrev_b32_e32 v20, 16, v151
	v_and_b32_e32 v21, 0xffff0000, v151
	s_waitcnt lgkmcnt(0)
	v_lshlrev_b32_e32 v18, 16, v16
	v_and_b32_e32 v19, 0xffff0000, v16
	v_pk_fma_f32 v[0:1], v[0:1], v[18:19], v[20:21]
	v_lshlrev_b32_e32 v16, 16, v150
	v_cvt_pk_bf16_f32 v151, v0, v1
	v_lshlrev_b32_e32 v0, 16, v17
	v_and_b32_e32 v1, 0xffff0000, v17
	v_and_b32_e32 v17, 0xffff0000, v150
	v_pk_fma_f32 v[0:1], v[2:3], v[0:1], v[16:17]
	v_lshlrev_b32_e32 v16, 16, v149
	v_cvt_pk_bf16_f32 v150, v0, v1
	ds_read2st64_b32 v[0:1], v140 offset0:248 offset1:252
	v_and_b32_e32 v17, 0xffff0000, v149
	s_waitcnt lgkmcnt(0)
	v_lshlrev_b32_e32 v2, 16, v0
	v_and_b32_e32 v3, 0xffff0000, v0
	v_mul_f32_e32 v0, 0xbfb8aa3b, v4
	v_exp_f32_e32 v0, v0
	s_nop 0
	v_add_f32_e32 v0, 1.0, v0
	v_rcp_f32_e32 v4, v0
	v_mul_f32_e32 v0, 0xbfb8aa3b, v5
	v_exp_f32_e32 v0, v0
	s_nop 0
	v_add_f32_e32 v0, 1.0, v0
	v_rcp_f32_e32 v5, v0
	v_lshlrev_b32_e32 v0, 16, v1
	v_and_b32_e32 v1, 0xffff0000, v1
	v_pk_fma_f32 v[2:3], v[4:5], v[2:3], v[16:17]
	s_nop 0
	v_cvt_pk_bf16_f32 v149, v2, v3
	v_mul_f32_e32 v3, 0xbfb8aa3b, v6
	v_mul_f32_e32 v5, 0xbfb8aa3b, v7
	v_exp_f32_e32 v3, v3
	v_exp_f32_e32 v5, v5
	v_lshlrev_b32_e32 v2, 16, v148
	v_add_f32_e32 v3, 1.0, v3
	v_add_f32_e32 v5, 1.0, v5
	v_rcp_f32_e32 v4, v3
	v_rcp_f32_e32 v5, v5
	v_and_b32_e32 v3, 0xffff0000, v148
	v_pk_fma_f32 v[0:1], v[4:5], v[0:1], v[2:3]
	s_nop 0
	v_cvt_pk_bf16_f32 v148, v0, v1
	ds_read2st64_b32 v[0:1], v141 offset0:112 offset1:116
	v_lshlrev_b32_e32 v4, 16, v147
	v_and_b32_e32 v5, 0xffff0000, v147
	s_waitcnt lgkmcnt(0)
	v_lshlrev_b32_e32 v2, 16, v0
	v_and_b32_e32 v3, 0xffff0000, v0
	v_mul_f32_e32 v0, 0xbfb8aa3b, v8
	v_exp_f32_e32 v0, v0
	s_nop 0
	v_add_f32_e32 v0, 1.0, v0
	v_rcp_f32_e32 v6, v0
	v_mul_f32_e32 v0, 0xbfb8aa3b, v9
	v_exp_f32_e32 v0, v0
	s_nop 0
	v_add_f32_e32 v0, 1.0, v0
	v_rcp_f32_e32 v7, v0
	v_lshlrev_b32_e32 v0, 16, v1
	v_and_b32_e32 v1, 0xffff0000, v1
	v_pk_fma_f32 v[2:3], v[6:7], v[2:3], v[4:5]
	s_nop 0
	v_cvt_pk_bf16_f32 v147, v2, v3
	v_mul_f32_e32 v3, 0xbfb8aa3b, v10
	v_mul_f32_e32 v5, 0xbfb8aa3b, v11
	v_exp_f32_e32 v3, v3
	v_exp_f32_e32 v5, v5
	v_lshlrev_b32_e32 v2, 16, v146
	v_add_f32_e32 v3, 1.0, v3
	v_add_f32_e32 v5, 1.0, v5
	v_rcp_f32_e32 v4, v3
	v_rcp_f32_e32 v5, v5
	v_and_b32_e32 v3, 0xffff0000, v146
	v_pk_fma_f32 v[0:1], v[4:5], v[0:1], v[2:3]
	s_nop 0
	v_cvt_pk_bf16_f32 v146, v0, v1
	ds_read2st64_b32 v[0:1], v141 offset0:120 offset1:124
	v_lshlrev_b32_e32 v4, 16, v145
	v_and_b32_e32 v5, 0xffff0000, v145
	s_waitcnt lgkmcnt(0)
	v_lshlrev_b32_e32 v2, 16, v0
	v_and_b32_e32 v3, 0xffff0000, v0
	v_mul_f32_e32 v0, 0xbfb8aa3b, v12
	v_exp_f32_e32 v0, v0
	s_nop 0
	v_add_f32_e32 v0, 1.0, v0
	v_rcp_f32_e32 v6, v0
	v_mul_f32_e32 v0, 0xbfb8aa3b, v13
	v_exp_f32_e32 v0, v0
	s_nop 0
	v_add_f32_e32 v0, 1.0, v0
	v_rcp_f32_e32 v7, v0
	v_lshlrev_b32_e32 v0, 16, v1
	v_and_b32_e32 v1, 0xffff0000, v1
	v_pk_fma_f32 v[2:3], v[6:7], v[2:3], v[4:5]
	s_nop 0
	v_cvt_pk_bf16_f32 v145, v2, v3
	v_mul_f32_e32 v3, 0xbfb8aa3b, v14
	v_mul_f32_e32 v5, 0xbfb8aa3b, v15
	v_exp_f32_e32 v3, v3
	v_exp_f32_e32 v5, v5
	v_lshlrev_b32_e32 v2, 16, v144
	v_add_f32_e32 v3, 1.0, v3
	v_add_f32_e32 v5, 1.0, v5
	v_rcp_f32_e32 v4, v3
	v_rcp_f32_e32 v5, v5
	v_and_b32_e32 v3, 0xffff0000, v144
	v_pk_fma_f32 v[0:1], v[4:5], v[0:1], v[2:3]
	s_nop 0
	v_cvt_pk_bf16_f32 v144, v0, v1
	s_cbranch_scc0 .LBB0_871
; DI int crow(int i, int h) { return (i & 3) + 8 * (i >> 2) + 4 * h; }
; DI void phase_merge(CP p, const Ptrs& w, int l, bf16_t* sA, bf16_t* sB, unsigned* sU) {
;     ...
;     bf16_t* dst = w.R2;
; #pragma unroll
;     for (int mi = 0; mi < 2; ++mi)
; #pragma unroll
;       for (int ni = 0; ni < 2; ++ni)
; #pragma unroll
;         for (int i = 0; i < 16; ++i) {
;           int row = m0 + wm * 64 + mi * 32 + crow(i, h), col = n0 + wn * 64 + ni * 32 + r;
;           const unsigned tv = totp[mi][ni][i >> 1];
;           dst[(size_t)row * 2048 + col] = (bf16_t)((i & 1) ? (tv >> 16) : (tv & 0xffffu));
;         }
	v_add_u32_e32 v0, s38, v142
	v_or_b32_e32 v2, s72, v143
	v_or_b32_e32 v6, 1, v0
	v_or_b32_e32 v8, 2, v0
	v_or_b32_e32 v10, 3, v0
	v_or_b32_e32 v12, 8, v0
	v_or_b32_e32 v14, 9, v0
	v_or_b32_e32 v16, 10, v0
	v_or_b32_e32 v18, 11, v0
	v_or_b32_e32 v20, 16, v0
	v_or_b32_e32 v22, 17, v0
	v_or_b32_e32 v24, 18, v0
	v_or_b32_e32 v26, 19, v0
	v_or_b32_e32 v28, 24, v0
	v_or_b32_e32 v30, 25, v0
	v_or_b32_e32 v32, 26, v0
	v_or_b32_e32 v34, 27, v0
	v_ashrrev_i32_e32 v3, 31, v2
	v_ashrrev_i32_e32 v1, 31, v0
	v_ashrrev_i32_e32 v7, 31, v6
	v_ashrrev_i32_e32 v9, 31, v8
	v_ashrrev_i32_e32 v11, 31, v10
	v_ashrrev_i32_e32 v13, 31, v12
	v_ashrrev_i32_e32 v15, 31, v14
	v_ashrrev_i32_e32 v17, 31, v16
	v_ashrrev_i32_e32 v19, 31, v18
	v_ashrrev_i32_e32 v21, 31, v20
	v_ashrrev_i32_e32 v23, 31, v22
	v_ashrrev_i32_e32 v25, 31, v24
	v_ashrrev_i32_e32 v27, 31, v26
	v_ashrrev_i32_e32 v29, 31, v28
	v_ashrrev_i32_e32 v31, 31, v30
	v_ashrrev_i32_e32 v33, 31, v32
	v_ashrrev_i32_e32 v35, 31, v34
	v_lshl_add_u64 v[2:3], v[2:3], 1, s[10:11]
	v_lshlrev_b64 v[4:5], 12, v[0:1]
	v_lshlrev_b64 v[6:7], 12, v[6:7]
	v_lshlrev_b64 v[8:9], 12, v[8:9]
	v_lshlrev_b64 v[10:11], 12, v[10:11]
	v_lshlrev_b64 v[12:13], 12, v[12:13]
	v_lshlrev_b64 v[14:15], 12, v[14:15]
	v_lshlrev_b64 v[16:17], 12, v[16:17]
	v_lshlrev_b64 v[18:19], 12, v[18:19]
	v_lshlrev_b64 v[20:21], 12, v[20:21]
	v_lshlrev_b64 v[22:23], 12, v[22:23]
	v_lshlrev_b64 v[24:25], 12, v[24:25]
	v_lshlrev_b64 v[26:27], 12, v[26:27]
	v_lshlrev_b64 v[28:29], 12, v[28:29]
	v_lshlrev_b64 v[30:31], 12, v[30:31]
	v_lshlrev_b64 v[32:33], 12, v[32:33]
	v_lshlrev_b64 v[34:35], 12, v[34:35]
	v_lshl_add_u64 v[4:5], v[2:3], 0, v[4:5]
	v_lshl_add_u64 v[6:7], v[2:3], 0, v[6:7]
	v_lshl_add_u64 v[8:9], v[2:3], 0, v[8:9]
	v_lshl_add_u64 v[10:11], v[2:3], 0, v[10:11]
	v_lshl_add_u64 v[12:13], v[2:3], 0, v[12:13]
	v_lshl_add_u64 v[14:15], v[2:3], 0, v[14:15]
	v_lshl_add_u64 v[16:17], v[2:3], 0, v[16:17]
	v_lshl_add_u64 v[18:19], v[2:3], 0, v[18:19]
	v_lshl_add_u64 v[20:21], v[2:3], 0, v[20:21]
	v_lshl_add_u64 v[22:23], v[2:3], 0, v[22:23]
	v_lshl_add_u64 v[24:25], v[2:3], 0, v[24:25]
	v_lshl_add_u64 v[26:27], v[2:3], 0, v[26:27]
	v_lshl_add_u64 v[28:29], v[2:3], 0, v[28:29]
	v_lshl_add_u64 v[30:31], v[2:3], 0, v[30:31]
	v_lshl_add_u64 v[32:33], v[2:3], 0, v[32:33]
	v_lshl_add_u64 v[34:35], v[2:3], 0, v[34:35]
	global_store_short v[4:5], v183, off
	global_store_short_d16_hi v[6:7], v183, off
	global_store_short v[8:9], v182, off
	global_store_short_d16_hi v[10:11], v182, off
	global_store_short v[12:13], v181, off
	global_store_short_d16_hi v[14:15], v181, off
	global_store_short v[16:17], v180, off
	global_store_short_d16_hi v[18:19], v180, off
	global_store_short v[20:21], v179, off
	global_store_short_d16_hi v[22:23], v179, off
	global_store_short v[24:25], v177, off
	global_store_short_d16_hi v[26:27], v177, off
	global_store_short v[28:29], v178, off
	global_store_short_d16_hi v[30:31], v178, off
	global_store_short v[32:33], v173, off
	global_store_short_d16_hi v[34:35], v173, off
	global_store_short v[4:5], v176, off offset:64
	global_store_short_d16_hi v[6:7], v176, off offset:64
	global_store_short v[8:9], v170, off offset:64
	global_store_short_d16_hi v[10:11], v170, off offset:64
	global_store_short v[12:13], v175, off offset:64
	global_store_short_d16_hi v[14:15], v175, off offset:64
	global_store_short v[16:17], v174, off offset:64
	global_store_short_d16_hi v[18:19], v174, off offset:64
	global_store_short v[20:21], v172, off offset:64
	global_store_short_d16_hi v[22:23], v172, off offset:64
	global_store_short v[24:25], v171, off offset:64
	global_store_short_d16_hi v[26:27], v171, off offset:64
	global_store_short v[28:29], v169, off offset:64
	global_store_short_d16_hi v[30:31], v169, off offset:64
	global_store_short v[32:33], v168, off offset:64
	global_store_short_d16_hi v[34:35], v168, off offset:64
; DI int crow(int i, int h) { return (i & 3) + 8 * (i >> 2) + 4 * h; }
; DI void phase_merge(CP p, const Ptrs& w, int l, bf16_t* sA, bf16_t* sB, unsigned* sU) {
;     ...
;   for (int kk = 0; kk < nrounds; ++kk) {
;     ...
;     bf16_t* dst = w.R2;
; #pragma unroll
;     for (int mi = 0; mi < 2; ++mi)
; #pragma unroll
;       for (int ni = 0; ni < 2; ++ni)
; #pragma unroll
;         for (int i = 0; i < 16; ++i) {
;           int row = m0 + wm * 64 + mi * 32 + crow(i, h), col = n0 + wn * 64 + ni * 32 + r;
;           const unsigned tv = totp[mi][ni][i >> 1];
;           dst[(size_t)row * 2048 + col] = (bf16_t)((i & 1) ? (tv >> 16) : (tv & 0xffffu));
;         }
	v_or_b32_e32 v4, 32, v0
	v_or_b32_e32 v6, 33, v0
	v_or_b32_e32 v8, 34, v0
	v_or_b32_e32 v10, 35, v0
	v_or_b32_e32 v12, 40, v0
	v_or_b32_e32 v14, 41, v0
	v_or_b32_e32 v16, 42, v0
	v_or_b32_e32 v18, 43, v0
	v_or_b32_e32 v20, 48, v0
	v_or_b32_e32 v22, 49, v0
	v_or_b32_e32 v24, 50, v0
	v_or_b32_e32 v26, 51, v0
	v_or_b32_e32 v28, 56, v0
	v_or_b32_e32 v30, 57, v0
	v_or_b32_e32 v32, 58, v0
	v_or_b32_e32 v0, 59, v0
	v_ashrrev_i32_e32 v5, 31, v4
	v_ashrrev_i32_e32 v7, 31, v6
	v_ashrrev_i32_e32 v9, 31, v8
	v_ashrrev_i32_e32 v11, 31, v10
	v_ashrrev_i32_e32 v13, 31, v12
	v_ashrrev_i32_e32 v15, 31, v14
	v_ashrrev_i32_e32 v17, 31, v16
	v_ashrrev_i32_e32 v19, 31, v18
	v_ashrrev_i32_e32 v21, 31, v20
	v_ashrrev_i32_e32 v23, 31, v22
	v_ashrrev_i32_e32 v25, 31, v24
	v_ashrrev_i32_e32 v27, 31, v26
	v_ashrrev_i32_e32 v29, 31, v28
	v_ashrrev_i32_e32 v31, 31, v30
	v_ashrrev_i32_e32 v33, 31, v32
	v_ashrrev_i32_e32 v1, 31, v0
	v_lshlrev_b64 v[4:5], 12, v[4:5]
	v_lshlrev_b64 v[6:7], 12, v[6:7]
	v_lshlrev_b64 v[8:9], 12, v[8:9]
	v_lshlrev_b64 v[10:11], 12, v[10:11]
	v_lshlrev_b64 v[12:13], 12, v[12:13]
	v_lshlrev_b64 v[14:15], 12, v[14:15]
	v_lshlrev_b64 v[16:17], 12, v[16:17]
	v_lshlrev_b64 v[18:19], 12, v[18:19]
	v_lshlrev_b64 v[20:21], 12, v[20:21]
	v_lshlrev_b64 v[22:23], 12, v[22:23]
	v_lshlrev_b64 v[24:25], 12, v[24:25]
	v_lshlrev_b64 v[26:27], 12, v[26:27]
	v_lshlrev_b64 v[28:29], 12, v[28:29]
	v_lshlrev_b64 v[30:31], 12, v[30:31]
	v_lshlrev_b64 v[32:33], 12, v[32:33]
	v_lshlrev_b64 v[0:1], 12, v[0:1]
	v_lshl_add_u64 v[4:5], v[2:3], 0, v[4:5]
	v_lshl_add_u64 v[6:7], v[2:3], 0, v[6:7]
	v_lshl_add_u64 v[8:9], v[2:3], 0, v[8:9]
	v_lshl_add_u64 v[10:11], v[2:3], 0, v[10:11]
	v_lshl_add_u64 v[12:13], v[2:3], 0, v[12:13]
	v_lshl_add_u64 v[14:15], v[2:3], 0, v[14:15]
	v_lshl_add_u64 v[16:17], v[2:3], 0, v[16:17]
	v_lshl_add_u64 v[18:19], v[2:3], 0, v[18:19]
	v_lshl_add_u64 v[20:21], v[2:3], 0, v[20:21]
	v_lshl_add_u64 v[22:23], v[2:3], 0, v[22:23]
	v_lshl_add_u64 v[24:25], v[2:3], 0, v[24:25]
	v_lshl_add_u64 v[26:27], v[2:3], 0, v[26:27]
	v_lshl_add_u64 v[28:29], v[2:3], 0, v[28:29]
	v_lshl_add_u64 v[30:31], v[2:3], 0, v[30:31]
	v_lshl_add_u64 v[32:33], v[2:3], 0, v[32:33]
	v_lshl_add_u64 v[0:1], v[2:3], 0, v[0:1]
	global_store_short v[4:5], v167, off
	global_store_short_d16_hi v[6:7], v167, off
	global_store_short v[8:9], v164, off
	global_store_short_d16_hi v[10:11], v164, off
	global_store_short v[12:13], v163, off
	global_store_short_d16_hi v[14:15], v163, off
	global_store_short v[16:17], v161, off
	global_store_short_d16_hi v[18:19], v161, off
	global_store_short v[20:21], v155, off
	global_store_short_d16_hi v[22:23], v155, off
	global_store_short v[24:25], v154, off
	global_store_short_d16_hi v[26:27], v154, off
	global_store_short v[28:29], v153, off
	global_store_short_d16_hi v[30:31], v153, off
	global_store_short v[32:33], v152, off
	global_store_short_d16_hi v[0:1], v152, off
	global_store_short v[4:5], v151, off offset:64
	global_store_short_d16_hi v[6:7], v151, off offset:64
	global_store_short v[8:9], v150, off offset:64
	global_store_short_d16_hi v[10:11], v150, off offset:64
	global_store_short v[12:13], v149, off offset:64
	global_store_short_d16_hi v[14:15], v149, off offset:64
	global_store_short v[16:17], v148, off offset:64
	global_store_short_d16_hi v[18:19], v148, off offset:64
	global_store_short v[20:21], v147, off offset:64
	global_store_short_d16_hi v[22:23], v147, off offset:64
	global_store_short v[24:25], v146, off offset:64
	global_store_short_d16_hi v[26:27], v146, off offset:64
	global_store_short v[28:29], v145, off offset:64
	global_store_short_d16_hi v[30:31], v145, off offset:64
	global_store_short v[32:33], v144, off offset:64
	global_store_short_d16_hi v[0:1], v144, off offset:64
	s_add_i32 s69, s69, 1
	s_cmp_lg_u32 s69, s60
	s_mov_b32 s42, s71
	s_cbranch_scc1 .LBB0_861
